# d1 + pre-barrier trimming in all GEMM K-loops: setprio 0 moved after post-MFMA barrier, segment waits merged into one s_waitcnt, redundant lgkmcnt waits removed
# speedup vs baseline: 1.0109x; 1.0109x over previous
; #define PG8_STAGE(bufoff, gbase, voff) do { _Pragma("unroll") for (int _i = 0; _i < 2; ++_i) \
;         __builtin_amdgcn_global_load_lds((const unsigned*)((const char*)(gbase) + (voff)[_i]), (LAS unsigned*)(lds + (bufoff) + ldsw + _i * 8192), 16, 0, 0); } while (0)
; #define PG8_LDA(dst, b, h) do { _Pragma("unroll") for (int m = 0; m < 4; ++m) _Pragma("unroll") for (int k = 0; k < 2; ++k) dst[m][k] = *(const LAS bf16x8*)(lds + PG8_SA(b, h) + aoff + m * 2048 + k * 1024); } while (0)
; #define PG8_LDB(dst, b, h) do { _Pragma("unroll") for (int n = 0; n < 2; ++n) _Pragma("unroll") for (int k = 0; k < 2; ++k) dst[n][k] = *(const LAS bf16x8*)(lds + PG8_SB(b, h) + boff + n * 2048 + k * 1024); } while (0)
; #define PG8_MMA(ai, bj, At, Bt) do { __builtin_amdgcn_s_setprio(1); _Pragma("unroll") for (int m = 0; m < 4; ++m) _Pragma("unroll") for (int n = 0; n < 2; ++n) _Pragma("unroll") for (int k = 0; k < 2; ++k) \
;         acc[ai][bj][m][n] = __builtin_amdgcn_mfma_f32_16x16x32_bf16(Bt[n][k], At[m][k], acc[ai][bj][m][n], 0, 0, 0); __builtin_amdgcn_s_setprio(0); } while (0)
; #define PG8_WAIT_V(n) asm volatile("s_waitcnt vmcnt(" #n ")" ::: "memory")
; #define PG8_WAIT_L(n) asm volatile("s_waitcnt lgkmcnt(" #n ")" ::: "memory")
; template <class Epi, class Sched, bool ALIGN_EPI, class Hook = NoHook>
; __device__ __forceinline__ void gemm_phase(LAS unsigned char* lds, const Gemm g, const Sched& S, const Epi& E, const Hook& H = Hook()) {
;     ...
;         for (int t = tb; t < te; t += 2) {
;             const bool last = (t == nt - 2);
;             const char* a1 = cA + (size_t)(t + 1) * kstep;
;             const char* a2 = last ? nA : cA + (size_t)(t + 2) * kstep; const char* b2 = last ? nB : cB + (size_t)(t + 2) * kstep;
;             const char* a3 = a2 + kstep; const char* b3 = b2 + kstep;
;             if (last && has_next) S.a_ready(nxt);
;             PG8_LDB(B0, 0, 0); PG8_LDB(B1, 0, 1); PG8_SCHED; PG8_LDA(At, 0, 0); PG8_STAGE(PG8_SA(1, 1), a1 + hA, voffA);
;             PG8_WAIT_V(8); PG8_WAIT_L(0); PG8_BAR; PG8_MMA(0, 0, At, B0); PG8_MMA(0, 1, At, B1); PG8_BAR; PG8_SCHED;
;             PG8_LDA(At, 0, 1); PG8_STAGE(PG8_SB(0, 0), b2, voffB); PG8_STAGE(PG8_SB(0, 1), b2 + hB, voffB); PG8_STAGE(PG8_SA(0, 0), a2, voffA);
;             PG8_WAIT_V(8); PG8_WAIT_L(0); PG8_BAR; PG8_MMA(1, 0, At, B0); PG8_MMA(1, 1, At, B1); PG8_BAR; PG8_SCHED;
.LBB0_199:
	ds_read_b128 v[130:133], v217
	ds_read_b128 v[134:137], v217 offset:1024
	s_add_u32 s34, s4, 0x100
	s_addc_u32 s35, s5, 0
	s_cmp_eq_u32 s64, 60
	s_cselect_b32 s39, s7, s35
	s_cselect_b32 s38, s8, s34
	s_cselect_b32 s37, s23, s63
	s_cselect_b32 s36, s25, s31
	s_add_i32 m0, s40, 0xc000
	s_nop 0
	global_load_lds_dwordx4 v172, s[4:5]
	ds_read_b128 v[138:141], v217 offset:2048
	ds_read_b128 v[142:145], v217 offset:3072
	ds_read_b128 v[146:149], v218
	ds_read_b128 v[150:153], v218 offset:1024
	ds_read_b128 v[154:157], v218 offset:2048
	ds_read_b128 v[158:161], v218 offset:3072
	ds_read_b128 v[180:183], v219
	s_add_i32 m0, s40, 0xe000
	s_nop 0
	global_load_lds_dwordx4 v174, s[4:5]
	ds_read_b128 v[184:187], v219 offset:1024
	ds_read_b128 v[188:191], v219 offset:2048
	ds_read_b128 v[192:195], v219 offset:3072
	ds_read_b128 v[196:199], v219 offset:4096
	ds_read_b128 v[200:203], v219 offset:5120
	ds_read_b128 v[204:207], v219 offset:6144
	ds_read_b128 v[208:211], v219 offset:7168
	s_barrier
	s_setprio 1
	s_waitcnt lgkmcnt(0)
	v_mfma_f32_16x16x32_bf16 v[126:129], v[130:133], v[180:183], v[126:129]
	v_mfma_f32_16x16x32_bf16 v[94:97], v[138:141], v[180:183], v[94:97]
	v_mfma_f32_16x16x32_bf16 v[122:125], v[130:133], v[188:191], v[122:125]
	v_mfma_f32_16x16x32_bf16 v[90:93], v[138:141], v[188:191], v[90:93]
	v_mfma_f32_16x16x32_bf16 v[118:121], v[130:133], v[196:199], v[118:121]
	v_mfma_f32_16x16x32_bf16 v[86:89], v[138:141], v[196:199], v[86:89]
	v_mfma_f32_16x16x32_bf16 v[114:117], v[130:133], v[204:207], v[114:117]
	v_mfma_f32_16x16x32_bf16 v[82:85], v[138:141], v[204:207], v[82:85]
	v_mfma_f32_16x16x32_bf16 v[126:129], v[134:137], v[184:187], v[126:129]
	v_mfma_f32_16x16x32_bf16 v[94:97], v[142:145], v[184:187], v[94:97]
	v_mfma_f32_16x16x32_bf16 v[122:125], v[134:137], v[192:195], v[122:125]
	v_mfma_f32_16x16x32_bf16 v[90:93], v[142:145], v[192:195], v[90:93]
	v_mfma_f32_16x16x32_bf16 v[118:121], v[134:137], v[200:203], v[118:121]
	v_mfma_f32_16x16x32_bf16 v[86:89], v[142:145], v[200:203], v[86:89]
	v_mfma_f32_16x16x32_bf16 v[114:117], v[134:137], v[208:211], v[114:117]
	v_mfma_f32_16x16x32_bf16 v[82:85], v[142:145], v[208:211], v[82:85]
	s_setprio 0
	s_setprio 1
	v_mfma_f32_16x16x32_bf16 v[62:65], v[146:149], v[180:183], v[62:65]
	v_mfma_f32_16x16x32_bf16 v[30:33], v[154:157], v[180:183], v[30:33]
	v_mfma_f32_16x16x32_bf16 v[58:61], v[146:149], v[188:191], v[58:61]
	v_mfma_f32_16x16x32_bf16 v[26:29], v[154:157], v[188:191], v[26:29]
	v_mfma_f32_16x16x32_bf16 v[54:57], v[146:149], v[196:199], v[54:57]
	v_mfma_f32_16x16x32_bf16 v[22:25], v[154:157], v[196:199], v[22:25]
	v_mfma_f32_16x16x32_bf16 v[50:53], v[146:149], v[204:207], v[50:53]
	v_mfma_f32_16x16x32_bf16 v[18:21], v[154:157], v[204:207], v[18:21]
	v_mfma_f32_16x16x32_bf16 v[62:65], v[150:153], v[184:187], v[62:65]
	v_mfma_f32_16x16x32_bf16 v[30:33], v[158:161], v[184:187], v[30:33]
	v_mfma_f32_16x16x32_bf16 v[58:61], v[150:153], v[192:195], v[58:61]
	v_mfma_f32_16x16x32_bf16 v[26:29], v[158:161], v[192:195], v[26:29]
	v_mfma_f32_16x16x32_bf16 v[54:57], v[150:153], v[200:203], v[54:57]
	v_mfma_f32_16x16x32_bf16 v[22:25], v[158:161], v[200:203], v[22:25]
	v_mfma_f32_16x16x32_bf16 v[50:53], v[150:153], v[208:211], v[50:53]
	v_mfma_f32_16x16x32_bf16 v[18:21], v[158:161], v[208:211], v[18:21]
	s_waitcnt vmcnt(8)
	s_barrier
	s_setprio 0
	s_add_i32 s4, s59, s21
	s_mov_b32 m0, s4
	ds_read_b128 v[180:183], v219 offset:16384
	ds_read_b128 v[184:187], v219 offset:17408
	global_load_lds_dwordx4 v164, s[36:37]
	ds_read_b128 v[188:191], v219 offset:18432
	s_add_i32 m0, s4, 0x2000
	s_add_u32 s4, s36, 0x100000
	s_addc_u32 s5, s37, 0
	s_add_i32 s65, s60, s21
	global_load_lds_dwordx4 v168, s[36:37]
	ds_read_b128 v[192:195], v219 offset:19456
	s_mov_b32 m0, s65
	s_nop 0
	global_load_lds_dwordx4 v164, s[4:5]
	ds_read_b128 v[196:199], v219 offset:20480
	s_add_i32 m0, s65, 0x2000
	s_nop 0
	global_load_lds_dwordx4 v168, s[4:5]
	ds_read_b128 v[200:203], v219 offset:21504
	s_mov_b32 m0, s40
	s_nop 0
	global_load_lds_dwordx4 v162, s[38:39]
	ds_read_b128 v[204:207], v219 offset:22528
	s_mov_b32 m0, s41
	s_nop 0
	global_load_lds_dwordx4 v166, s[38:39]
	ds_read_b128 v[208:211], v219 offset:23552
	s_barrier
	s_setprio 1
	s_waitcnt lgkmcnt(0)
	v_mfma_f32_16x16x32_bf16 v[110:113], v[130:133], v[180:183], v[110:113]
	v_mfma_f32_16x16x32_bf16 v[78:81], v[138:141], v[180:183], v[78:81]
	v_mfma_f32_16x16x32_bf16 v[106:109], v[130:133], v[188:191], v[106:109]
	v_mfma_f32_16x16x32_bf16 v[74:77], v[138:141], v[188:191], v[74:77]
	v_mfma_f32_16x16x32_bf16 v[102:105], v[130:133], v[196:199], v[102:105]
	v_mfma_f32_16x16x32_bf16 v[70:73], v[138:141], v[196:199], v[70:73]
	v_mfma_f32_16x16x32_bf16 v[98:101], v[130:133], v[204:207], v[98:101]
	v_mfma_f32_16x16x32_bf16 v[66:69], v[138:141], v[204:207], v[66:69]
	v_mfma_f32_16x16x32_bf16 v[110:113], v[134:137], v[184:187], v[110:113]
	v_mfma_f32_16x16x32_bf16 v[78:81], v[142:145], v[184:187], v[78:81]
	v_mfma_f32_16x16x32_bf16 v[106:109], v[134:137], v[192:195], v[106:109]
	v_mfma_f32_16x16x32_bf16 v[74:77], v[142:145], v[192:195], v[74:77]
	v_mfma_f32_16x16x32_bf16 v[102:105], v[134:137], v[200:203], v[102:105]
	v_mfma_f32_16x16x32_bf16 v[70:73], v[142:145], v[200:203], v[70:73]
	v_mfma_f32_16x16x32_bf16 v[98:101], v[134:137], v[208:211], v[98:101]
	v_mfma_f32_16x16x32_bf16 v[66:69], v[142:145], v[208:211], v[66:69]
	s_setprio 0
	s_setprio 1
	v_mfma_f32_16x16x32_bf16 v[46:49], v[146:149], v[180:183], v[46:49]
	v_mfma_f32_16x16x32_bf16 v[14:17], v[154:157], v[180:183], v[14:17]
	v_mfma_f32_16x16x32_bf16 v[42:45], v[146:149], v[188:191], v[42:45]
	v_mfma_f32_16x16x32_bf16 v[10:13], v[154:157], v[188:191], v[10:13]
	v_mfma_f32_16x16x32_bf16 v[38:41], v[146:149], v[196:199], v[38:41]
	v_mfma_f32_16x16x32_bf16 v[6:9], v[154:157], v[196:199], v[6:9]
	v_mfma_f32_16x16x32_bf16 v[34:37], v[146:149], v[204:207], v[34:37]
	v_mfma_f32_16x16x32_bf16 v[2:5], v[154:157], v[204:207], v[2:5]
	v_mfma_f32_16x16x32_bf16 v[46:49], v[150:153], v[184:187], v[46:49]
	v_mfma_f32_16x16x32_bf16 v[14:17], v[158:161], v[184:187], v[14:17]
	v_mfma_f32_16x16x32_bf16 v[42:45], v[150:153], v[192:195], v[42:45]
	v_mfma_f32_16x16x32_bf16 v[10:13], v[158:161], v[192:195], v[10:13]
	v_mfma_f32_16x16x32_bf16 v[38:41], v[150:153], v[200:203], v[38:41]
	v_mfma_f32_16x16x32_bf16 v[6:9], v[158:161], v[200:203], v[6:9]
	v_mfma_f32_16x16x32_bf16 v[34:37], v[150:153], v[208:211], v[34:37]
	v_mfma_f32_16x16x32_bf16 v[2:5], v[158:161], v[208:211], v[2:5]
	s_waitcnt vmcnt(8)
	s_barrier
; #define PG8_STAGE(bufoff, gbase, voff) do { _Pragma("unroll") for (int _i = 0; _i < 2; ++_i) \
;         __builtin_amdgcn_global_load_lds((const unsigned*)((const char*)(gbase) + (voff)[_i]), (LAS unsigned*)(lds + (bufoff) + ldsw + _i * 8192), 16, 0, 0); } while (0)
; #define PG8_LDA(dst, b, h) do { _Pragma("unroll") for (int m = 0; m < 4; ++m) _Pragma("unroll") for (int k = 0; k < 2; ++k) dst[m][k] = *(const LAS bf16x8*)(lds + PG8_SA(b, h) + aoff + m * 2048 + k * 1024); } while (0)
; #define PG8_LDB(dst, b, h) do { _Pragma("unroll") for (int n = 0; n < 2; ++n) _Pragma("unroll") for (int k = 0; k < 2; ++k) dst[n][k] = *(const LAS bf16x8*)(lds + PG8_SB(b, h) + boff + n * 2048 + k * 1024); } while (0)
; #define PG8_MMA(ai, bj, At, Bt) do { __builtin_amdgcn_s_setprio(1); _Pragma("unroll") for (int m = 0; m < 4; ++m) _Pragma("unroll") for (int n = 0; n < 2; ++n) _Pragma("unroll") for (int k = 0; k < 2; ++k) \
;         acc[ai][bj][m][n] = __builtin_amdgcn_mfma_f32_16x16x32_bf16(Bt[n][k], At[m][k], acc[ai][bj][m][n], 0, 0, 0); __builtin_amdgcn_s_setprio(0); } while (0)
; #define PG8_WAIT_V(n) asm volatile("s_waitcnt vmcnt(" #n ")" ::: "memory")
; #define PG8_WAIT_L(n) asm volatile("s_waitcnt lgkmcnt(" #n ")" ::: "memory")
; #define PG8_BAR __builtin_amdgcn_s_barrier()
; #define PG8_SCHED __builtin_amdgcn_sched_barrier(0)
; template <class Epi, class Sched, bool ALIGN_EPI, class Hook = NoHook>
; __device__ __forceinline__ void gemm_phase(LAS unsigned char* lds, const Gemm g, const Sched& S, const Epi& E, const Hook& H = Hook()) {
;     ...
;             PG8_LDB(B0, 1, 0); PG8_LDB(B1, 1, 1); PG8_SCHED; PG8_LDA(At, 1, 0); PG8_STAGE(PG8_SA(0, 1), a2 + hA, voffA);
;             PG8_WAIT_V(8); PG8_WAIT_L(0); PG8_BAR; PG8_MMA(0, 0, At, B0); PG8_MMA(0, 1, At, B1); PG8_BAR; PG8_SCHED;
;             PG8_LDA(At, 1, 1); PG8_STAGE(PG8_SB(1, 0), b3, voffB); PG8_STAGE(PG8_SB(1, 1), b3 + hB, voffB); PG8_STAGE(PG8_SA(1, 0), a3, voffA);
;             PG8_WAIT_V(8); PG8_WAIT_L(0); PG8_BAR; PG8_MMA(1, 0, At, B0); PG8_MMA(1, 1, At, B1); PG8_BAR; PG8_SCHED;
;         }
	s_setprio 0
	s_add_i32 s65, 0, 0x18000
	s_add_i32 s66, 0, 0x1c000
	v_add_u32_e32 v142, s65, v213
	v_add_u32_e32 v158, s66, v213
	ds_read_b128 v[130:133], v142
	ds_read_b128 v[134:137], v142 offset:1024
	s_add_u32 s4, s38, 0x8000
	s_addc_u32 s5, s39, 0
	s_mov_b32 m0, s42
	s_nop 0
	global_load_lds_dwordx4 v162, s[4:5]
	ds_read_b128 v[138:141], v142 offset:2048
	ds_read_b128 v[142:145], v142 offset:3072
	ds_read_b128 v[146:149], v158
	ds_read_b128 v[150:153], v158 offset:1024
	ds_read_b128 v[154:157], v158 offset:2048
	ds_read_b128 v[158:161], v158 offset:3072
	ds_read_b128 v[180:183], v219 offset:32768
	s_mov_b32 m0, s43
	s_nop 0
	global_load_lds_dwordx4 v166, s[4:5]
	ds_read_b128 v[184:187], v219 offset:33792
	ds_read_b128 v[188:191], v219 offset:34816
	ds_read_b128 v[192:195], v219 offset:35840
	ds_read_b128 v[196:199], v219 offset:36864
	ds_read_b128 v[200:203], v219 offset:37888
	ds_read_b128 v[204:207], v219 offset:38912
	ds_read_b128 v[208:211], v219 offset:39936
	s_barrier
	s_setprio 1
	s_waitcnt lgkmcnt(0)
	v_mfma_f32_16x16x32_bf16 v[126:129], v[130:133], v[180:183], v[126:129]
	v_mfma_f32_16x16x32_bf16 v[94:97], v[138:141], v[180:183], v[94:97]
	v_mfma_f32_16x16x32_bf16 v[122:125], v[130:133], v[188:191], v[122:125]
	v_mfma_f32_16x16x32_bf16 v[90:93], v[138:141], v[188:191], v[90:93]
	v_mfma_f32_16x16x32_bf16 v[118:121], v[130:133], v[196:199], v[118:121]
	v_mfma_f32_16x16x32_bf16 v[86:89], v[138:141], v[196:199], v[86:89]
	v_mfma_f32_16x16x32_bf16 v[114:117], v[130:133], v[204:207], v[114:117]
	v_mfma_f32_16x16x32_bf16 v[82:85], v[138:141], v[204:207], v[82:85]
	v_mfma_f32_16x16x32_bf16 v[126:129], v[134:137], v[184:187], v[126:129]
	v_mfma_f32_16x16x32_bf16 v[94:97], v[142:145], v[184:187], v[94:97]
	v_mfma_f32_16x16x32_bf16 v[122:125], v[134:137], v[192:195], v[122:125]
	v_mfma_f32_16x16x32_bf16 v[90:93], v[142:145], v[192:195], v[90:93]
	v_mfma_f32_16x16x32_bf16 v[118:121], v[134:137], v[200:203], v[118:121]
	v_mfma_f32_16x16x32_bf16 v[86:89], v[142:145], v[200:203], v[86:89]
	v_mfma_f32_16x16x32_bf16 v[114:117], v[134:137], v[208:211], v[114:117]
	v_mfma_f32_16x16x32_bf16 v[82:85], v[142:145], v[208:211], v[82:85]
	s_setprio 0
	s_setprio 1
	v_mfma_f32_16x16x32_bf16 v[62:65], v[146:149], v[180:183], v[62:65]
	v_mfma_f32_16x16x32_bf16 v[30:33], v[154:157], v[180:183], v[30:33]
	v_mfma_f32_16x16x32_bf16 v[58:61], v[146:149], v[188:191], v[58:61]
	v_mfma_f32_16x16x32_bf16 v[26:29], v[154:157], v[188:191], v[26:29]
	v_mfma_f32_16x16x32_bf16 v[54:57], v[146:149], v[196:199], v[54:57]
	v_mfma_f32_16x16x32_bf16 v[22:25], v[154:157], v[196:199], v[22:25]
	v_mfma_f32_16x16x32_bf16 v[50:53], v[146:149], v[204:207], v[50:53]
	v_mfma_f32_16x16x32_bf16 v[18:21], v[154:157], v[204:207], v[18:21]
	v_mfma_f32_16x16x32_bf16 v[62:65], v[150:153], v[184:187], v[62:65]
	v_mfma_f32_16x16x32_bf16 v[30:33], v[158:161], v[184:187], v[30:33]
	v_mfma_f32_16x16x32_bf16 v[58:61], v[150:153], v[192:195], v[58:61]
	v_mfma_f32_16x16x32_bf16 v[26:29], v[158:161], v[192:195], v[26:29]
	v_mfma_f32_16x16x32_bf16 v[54:57], v[150:153], v[200:203], v[54:57]
	v_mfma_f32_16x16x32_bf16 v[22:25], v[158:161], v[200:203], v[22:25]
	v_mfma_f32_16x16x32_bf16 v[50:53], v[150:153], v[208:211], v[50:53]
	v_mfma_f32_16x16x32_bf16 v[18:21], v[158:161], v[208:211], v[18:21]
	s_waitcnt vmcnt(8)
	s_barrier
	s_setprio 0
	s_add_i32 s4, s65, s21
	s_add_u32 s68, s36, s14
	s_addc_u32 s69, s37, s15
	s_mov_b32 m0, s4
	ds_read_b128 v[180:183], v219 offset:49152
	ds_read_b128 v[184:187], v219 offset:50176
	global_load_lds_dwordx4 v164, s[68:69]
	ds_read_b128 v[188:191], v219 offset:51200
	s_add_i32 m0, s4, 0x2000
	s_add_u32 s4, s36, 0x100080
	s_addc_u32 s5, s37, 0
	s_add_i32 s36, s66, s21
	global_load_lds_dwordx4 v168, s[68:69]
	ds_read_b128 v[192:195], v219 offset:52224
	s_mov_b32 m0, s36
	s_nop 0
	global_load_lds_dwordx4 v164, s[4:5]
	ds_read_b128 v[196:199], v219 offset:53248
	s_add_i32 m0, s36, 0x2000
	s_nop 0
	global_load_lds_dwordx4 v168, s[4:5]
	ds_read_b128 v[200:203], v219 offset:54272
	s_add_u32 s70, s38, s14
	s_addc_u32 s71, s39, s15
	s_mov_b32 m0, s51
	s_nop 0
	global_load_lds_dwordx4 v162, s[70:71]
	ds_read_b128 v[204:207], v219 offset:55296
	s_mov_b32 m0, s52
	s_nop 0
	global_load_lds_dwordx4 v166, s[70:71]
	ds_read_b128 v[208:211], v219 offset:56320
	s_barrier
	s_setprio 1
	s_waitcnt lgkmcnt(0)
	v_mfma_f32_16x16x32_bf16 v[110:113], v[130:133], v[180:183], v[110:113]
	v_mfma_f32_16x16x32_bf16 v[78:81], v[138:141], v[180:183], v[78:81]
	v_mfma_f32_16x16x32_bf16 v[106:109], v[130:133], v[188:191], v[106:109]
	v_mfma_f32_16x16x32_bf16 v[74:77], v[138:141], v[188:191], v[74:77]
	v_mfma_f32_16x16x32_bf16 v[102:105], v[130:133], v[196:199], v[102:105]
	v_mfma_f32_16x16x32_bf16 v[70:73], v[138:141], v[196:199], v[70:73]
	v_mfma_f32_16x16x32_bf16 v[98:101], v[130:133], v[204:207], v[98:101]
	v_mfma_f32_16x16x32_bf16 v[66:69], v[138:141], v[204:207], v[66:69]
	v_mfma_f32_16x16x32_bf16 v[110:113], v[134:137], v[184:187], v[110:113]
	v_mfma_f32_16x16x32_bf16 v[78:81], v[142:145], v[184:187], v[78:81]
	v_mfma_f32_16x16x32_bf16 v[106:109], v[134:137], v[192:195], v[106:109]
	v_mfma_f32_16x16x32_bf16 v[74:77], v[142:145], v[192:195], v[74:77]
	v_mfma_f32_16x16x32_bf16 v[102:105], v[134:137], v[200:203], v[102:105]
	v_mfma_f32_16x16x32_bf16 v[70:73], v[142:145], v[200:203], v[70:73]
	v_mfma_f32_16x16x32_bf16 v[98:101], v[134:137], v[208:211], v[98:101]
	v_mfma_f32_16x16x32_bf16 v[66:69], v[142:145], v[208:211], v[66:69]
	s_setprio 0
	s_setprio 1
	v_mfma_f32_16x16x32_bf16 v[46:49], v[146:149], v[180:183], v[46:49]
	v_mfma_f32_16x16x32_bf16 v[14:17], v[154:157], v[180:183], v[14:17]
	v_mfma_f32_16x16x32_bf16 v[42:45], v[146:149], v[188:191], v[42:45]
	v_mfma_f32_16x16x32_bf16 v[10:13], v[154:157], v[188:191], v[10:13]
	v_mfma_f32_16x16x32_bf16 v[38:41], v[146:149], v[196:199], v[38:41]
	v_mfma_f32_16x16x32_bf16 v[6:9], v[154:157], v[196:199], v[6:9]
	v_mfma_f32_16x16x32_bf16 v[34:37], v[146:149], v[204:207], v[34:37]
	v_mfma_f32_16x16x32_bf16 v[2:5], v[154:157], v[204:207], v[2:5]
	v_mfma_f32_16x16x32_bf16 v[46:49], v[150:153], v[184:187], v[46:49]
	v_mfma_f32_16x16x32_bf16 v[14:17], v[158:161], v[184:187], v[14:17]
	v_mfma_f32_16x16x32_bf16 v[42:45], v[150:153], v[192:195], v[42:45]
	v_mfma_f32_16x16x32_bf16 v[10:13], v[158:161], v[192:195], v[10:13]
	v_mfma_f32_16x16x32_bf16 v[38:41], v[150:153], v[200:203], v[38:41]
	v_mfma_f32_16x16x32_bf16 v[6:9], v[158:161], v[200:203], v[6:9]
	v_mfma_f32_16x16x32_bf16 v[34:37], v[150:153], v[208:211], v[34:37]
	v_mfma_f32_16x16x32_bf16 v[2:5], v[158:161], v[208:211], v[2:5]
	s_waitcnt vmcnt(8)
	s_barrier
	s_setprio 0
	s_add_i32 s64, s64, 2
	s_add_u32 s31, s31, 0x100
	s_addc_u32 s63, s63, 0
	s_cmp_gt_u32 s64, 61
	s_mov_b64 s[4:5], s[34:35]
	s_cbranch_scc0 .LBB0_199
	s_branch .Lmy_d199X
; #define PG8_STAGE(bufoff, gbase, voff) do { _Pragma("unroll") for (int _i = 0; _i < 2; ++_i) \
;         __builtin_amdgcn_global_load_lds((const unsigned*)((const char*)(gbase) + (voff)[_i]), (LAS unsigned*)(lds + (bufoff) + ldsw + _i * 8192), 16, 0, 0); } while (0)
; #define PG8_LDA(dst, b, h) do { _Pragma("unroll") for (int m = 0; m < 4; ++m) _Pragma("unroll") for (int k = 0; k < 2; ++k) dst[m][k] = *(const LAS bf16x8*)(lds + PG8_SA(b, h) + aoff + m * 2048 + k * 1024); } while (0)
; #define PG8_LDB(dst, b, h) do { _Pragma("unroll") for (int n = 0; n < 2; ++n) _Pragma("unroll") for (int k = 0; k < 2; ++k) dst[n][k] = *(const LAS bf16x8*)(lds + PG8_SB(b, h) + boff + n * 2048 + k * 1024); } while (0)
; #define PG8_MMA(ai, bj, At, Bt) do { __builtin_amdgcn_s_setprio(1); _Pragma("unroll") for (int m = 0; m < 4; ++m) _Pragma("unroll") for (int n = 0; n < 2; ++n) _Pragma("unroll") for (int k = 0; k < 2; ++k) \
;         acc[ai][bj][m][n] = __builtin_amdgcn_mfma_f32_16x16x32_bf16(Bt[n][k], At[m][k], acc[ai][bj][m][n], 0, 0, 0); __builtin_amdgcn_s_setprio(0); } while (0)
; #define PG8_WAIT_V(n) asm volatile("s_waitcnt vmcnt(" #n ")" ::: "memory")
; #define PG8_WAIT_L(n) asm volatile("s_waitcnt lgkmcnt(" #n ")" ::: "memory")
; template <class Epi, class Sched, bool ALIGN_EPI, class Hook = NoHook>
; __device__ __forceinline__ void gemm_phase(LAS unsigned char* lds, const Gemm g, const Sched& S, const Epi& E, const Hook& H = Hook()) {
;     ...
;         for (int t = tb; t < te; t += 2) {
;             const bool last = (t == nt - 2);
;             const char* a1 = cA + (size_t)(t + 1) * kstep;
;             const char* a2 = last ? nA : cA + (size_t)(t + 2) * kstep; const char* b2 = last ? nB : cB + (size_t)(t + 2) * kstep;
;             const char* a3 = a2 + kstep; const char* b3 = b2 + kstep;
;             if (last && has_next) S.a_ready(nxt);
;             PG8_LDB(B0, 0, 0); PG8_LDB(B1, 0, 1); PG8_SCHED; PG8_LDA(At, 0, 0); PG8_STAGE(PG8_SA(1, 1), a1 + hA, voffA);
;             PG8_WAIT_V(8); PG8_WAIT_L(0); PG8_BAR; PG8_MMA(0, 0, At, B0); PG8_MMA(0, 1, At, B1); PG8_BAR; PG8_SCHED;
;             PG8_LDA(At, 0, 1); PG8_STAGE(PG8_SB(0, 0), b2, voffB); PG8_STAGE(PG8_SB(0, 1), b2 + hB, voffB); PG8_STAGE(PG8_SA(0, 0), a2, voffA);
;             PG8_WAIT_V(8); PG8_WAIT_L(0); PG8_BAR; PG8_MMA(1, 0, At, B0); PG8_MMA(1, 1, At, B1); PG8_BAR; PG8_SCHED;
.Lmy_d199B:
	ds_read_b128 v[130:133], v217
	ds_read_b128 v[134:137], v217 offset:1024
	s_add_u32 s34, s4, 0x100
	s_addc_u32 s35, s5, 0
	s_cmp_eq_u32 s64, 60
	s_cselect_b32 s39, s7, s35
	s_cselect_b32 s38, s8, s34
	s_cselect_b32 s37, s23, s63
	s_cselect_b32 s36, s25, s31
	s_add_i32 m0, s40, 0xc000
	s_nop 0
	global_load_lds_dwordx4 v172, s[4:5]
	ds_read_b128 v[138:141], v217 offset:2048
	ds_read_b128 v[142:145], v217 offset:3072
	ds_read_b128 v[146:149], v218
	ds_read_b128 v[150:153], v218 offset:1024
	ds_read_b128 v[154:157], v218 offset:2048
	ds_read_b128 v[158:161], v218 offset:3072
	ds_read_b128 v[180:183], v219
	s_add_i32 m0, s40, 0xe000
	s_nop 0
	global_load_lds_dwordx4 v174, s[4:5]
	ds_read_b128 v[184:187], v219 offset:1024
	ds_read_b128 v[188:191], v219 offset:2048
	ds_read_b128 v[192:195], v219 offset:3072
	ds_read_b128 v[196:199], v219 offset:4096
	ds_read_b128 v[200:203], v219 offset:5120
	ds_read_b128 v[204:207], v219 offset:6144
	ds_read_b128 v[208:211], v219 offset:7168
	s_waitcnt vmcnt(8) lgkmcnt(0)
	s_barrier
	s_setprio 1
	v_mfma_f32_16x16x32_bf16 v[126:129], v[130:133], v[180:183], v[126:129]
	v_mfma_f32_16x16x32_bf16 v[94:97], v[138:141], v[180:183], v[94:97]
	v_mfma_f32_16x16x32_bf16 v[122:125], v[130:133], v[188:191], v[122:125]
	v_mfma_f32_16x16x32_bf16 v[90:93], v[138:141], v[188:191], v[90:93]
	v_mfma_f32_16x16x32_bf16 v[118:121], v[130:133], v[196:199], v[118:121]
	v_mfma_f32_16x16x32_bf16 v[86:89], v[138:141], v[196:199], v[86:89]
	v_mfma_f32_16x16x32_bf16 v[114:117], v[130:133], v[204:207], v[114:117]
	v_mfma_f32_16x16x32_bf16 v[82:85], v[138:141], v[204:207], v[82:85]
	v_mfma_f32_16x16x32_bf16 v[126:129], v[134:137], v[184:187], v[126:129]
	v_mfma_f32_16x16x32_bf16 v[94:97], v[142:145], v[184:187], v[94:97]
	v_mfma_f32_16x16x32_bf16 v[122:125], v[134:137], v[192:195], v[122:125]
	v_mfma_f32_16x16x32_bf16 v[90:93], v[142:145], v[192:195], v[90:93]
	v_mfma_f32_16x16x32_bf16 v[118:121], v[134:137], v[200:203], v[118:121]
	v_mfma_f32_16x16x32_bf16 v[86:89], v[142:145], v[200:203], v[86:89]
	v_mfma_f32_16x16x32_bf16 v[114:117], v[134:137], v[208:211], v[114:117]
	v_mfma_f32_16x16x32_bf16 v[82:85], v[142:145], v[208:211], v[82:85]
	s_setprio 0
	s_setprio 1
	v_mfma_f32_16x16x32_bf16 v[62:65], v[146:149], v[180:183], v[62:65]
	v_mfma_f32_16x16x32_bf16 v[30:33], v[154:157], v[180:183], v[30:33]
	v_mfma_f32_16x16x32_bf16 v[58:61], v[146:149], v[188:191], v[58:61]
	v_mfma_f32_16x16x32_bf16 v[26:29], v[154:157], v[188:191], v[26:29]
	v_mfma_f32_16x16x32_bf16 v[54:57], v[146:149], v[196:199], v[54:57]
	v_mfma_f32_16x16x32_bf16 v[22:25], v[154:157], v[196:199], v[22:25]
	v_mfma_f32_16x16x32_bf16 v[50:53], v[146:149], v[204:207], v[50:53]
	v_mfma_f32_16x16x32_bf16 v[18:21], v[154:157], v[204:207], v[18:21]
	v_mfma_f32_16x16x32_bf16 v[62:65], v[150:153], v[184:187], v[62:65]
	v_mfma_f32_16x16x32_bf16 v[30:33], v[158:161], v[184:187], v[30:33]
	v_mfma_f32_16x16x32_bf16 v[58:61], v[150:153], v[192:195], v[58:61]
	v_mfma_f32_16x16x32_bf16 v[26:29], v[158:161], v[192:195], v[26:29]
	v_mfma_f32_16x16x32_bf16 v[54:57], v[150:153], v[200:203], v[54:57]
	v_mfma_f32_16x16x32_bf16 v[22:25], v[158:161], v[200:203], v[22:25]
	v_mfma_f32_16x16x32_bf16 v[50:53], v[150:153], v[208:211], v[50:53]
	v_mfma_f32_16x16x32_bf16 v[18:21], v[158:161], v[208:211], v[18:21]
	s_barrier
	s_setprio 0
	s_add_i32 s4, s59, s21
	s_mov_b32 m0, s4
	ds_read_b128 v[180:183], v219 offset:16384
	ds_read_b128 v[184:187], v219 offset:17408
	global_load_lds_dwordx4 v164, s[36:37]
	ds_read_b128 v[188:191], v219 offset:18432
	s_add_i32 m0, s4, 0x2000
	s_add_u32 s4, s36, 0x100000
	s_addc_u32 s5, s37, 0
	s_add_i32 s65, s60, s21
	global_load_lds_dwordx4 v168, s[36:37]
	ds_read_b128 v[192:195], v219 offset:19456
	s_mov_b32 m0, s65
	s_nop 0
	global_load_lds_dwordx4 v164, s[4:5]
	ds_read_b128 v[196:199], v219 offset:20480
	s_add_i32 m0, s65, 0x2000
	s_nop 0
	global_load_lds_dwordx4 v168, s[4:5]
	ds_read_b128 v[200:203], v219 offset:21504
	s_mov_b32 m0, s40
	s_nop 0
	global_load_lds_dwordx4 v162, s[38:39]
	ds_read_b128 v[204:207], v219 offset:22528
	s_mov_b32 m0, s41
	s_nop 0
	global_load_lds_dwordx4 v166, s[38:39]
	ds_read_b128 v[208:211], v219 offset:23552
	s_waitcnt vmcnt(8) lgkmcnt(0)
	s_barrier
	s_setprio 1
	v_mfma_f32_16x16x32_bf16 v[110:113], v[130:133], v[180:183], v[110:113]
	v_mfma_f32_16x16x32_bf16 v[78:81], v[138:141], v[180:183], v[78:81]
	v_mfma_f32_16x16x32_bf16 v[106:109], v[130:133], v[188:191], v[106:109]
	v_mfma_f32_16x16x32_bf16 v[74:77], v[138:141], v[188:191], v[74:77]
	v_mfma_f32_16x16x32_bf16 v[102:105], v[130:133], v[196:199], v[102:105]
	v_mfma_f32_16x16x32_bf16 v[70:73], v[138:141], v[196:199], v[70:73]
	v_mfma_f32_16x16x32_bf16 v[98:101], v[130:133], v[204:207], v[98:101]
	v_mfma_f32_16x16x32_bf16 v[66:69], v[138:141], v[204:207], v[66:69]
	v_mfma_f32_16x16x32_bf16 v[110:113], v[134:137], v[184:187], v[110:113]
	v_mfma_f32_16x16x32_bf16 v[78:81], v[142:145], v[184:187], v[78:81]
	v_mfma_f32_16x16x32_bf16 v[106:109], v[134:137], v[192:195], v[106:109]
	v_mfma_f32_16x16x32_bf16 v[74:77], v[142:145], v[192:195], v[74:77]
	v_mfma_f32_16x16x32_bf16 v[102:105], v[134:137], v[200:203], v[102:105]
	v_mfma_f32_16x16x32_bf16 v[70:73], v[142:145], v[200:203], v[70:73]
	v_mfma_f32_16x16x32_bf16 v[98:101], v[134:137], v[208:211], v[98:101]
	v_mfma_f32_16x16x32_bf16 v[66:69], v[142:145], v[208:211], v[66:69]
	s_setprio 0
	s_setprio 1
	v_mfma_f32_16x16x32_bf16 v[46:49], v[146:149], v[180:183], v[46:49]
	v_mfma_f32_16x16x32_bf16 v[14:17], v[154:157], v[180:183], v[14:17]
	v_mfma_f32_16x16x32_bf16 v[42:45], v[146:149], v[188:191], v[42:45]
	v_mfma_f32_16x16x32_bf16 v[10:13], v[154:157], v[188:191], v[10:13]
	v_mfma_f32_16x16x32_bf16 v[38:41], v[146:149], v[196:199], v[38:41]
	v_mfma_f32_16x16x32_bf16 v[6:9], v[154:157], v[196:199], v[6:9]
	v_mfma_f32_16x16x32_bf16 v[34:37], v[146:149], v[204:207], v[34:37]
	v_mfma_f32_16x16x32_bf16 v[2:5], v[154:157], v[204:207], v[2:5]
	v_mfma_f32_16x16x32_bf16 v[46:49], v[150:153], v[184:187], v[46:49]
	v_mfma_f32_16x16x32_bf16 v[14:17], v[158:161], v[184:187], v[14:17]
	v_mfma_f32_16x16x32_bf16 v[42:45], v[150:153], v[192:195], v[42:45]
	v_mfma_f32_16x16x32_bf16 v[10:13], v[158:161], v[192:195], v[10:13]
	v_mfma_f32_16x16x32_bf16 v[38:41], v[150:153], v[200:203], v[38:41]
	v_mfma_f32_16x16x32_bf16 v[6:9], v[158:161], v[200:203], v[6:9]
	v_mfma_f32_16x16x32_bf16 v[34:37], v[150:153], v[208:211], v[34:37]
	v_mfma_f32_16x16x32_bf16 v[2:5], v[158:161], v[208:211], v[2:5]
	s_barrier
; #define PG8_STAGE(bufoff, gbase, voff) do { _Pragma("unroll") for (int _i = 0; _i < 2; ++_i) \
;         __builtin_amdgcn_global_load_lds((const unsigned*)((const char*)(gbase) + (voff)[_i]), (LAS unsigned*)(lds + (bufoff) + ldsw + _i * 8192), 16, 0, 0); } while (0)
; #define PG8_LDA(dst, b, h) do { _Pragma("unroll") for (int m = 0; m < 4; ++m) _Pragma("unroll") for (int k = 0; k < 2; ++k) dst[m][k] = *(const LAS bf16x8*)(lds + PG8_SA(b, h) + aoff + m * 2048 + k * 1024); } while (0)
; #define PG8_LDB(dst, b, h) do { _Pragma("unroll") for (int n = 0; n < 2; ++n) _Pragma("unroll") for (int k = 0; k < 2; ++k) dst[n][k] = *(const LAS bf16x8*)(lds + PG8_SB(b, h) + boff + n * 2048 + k * 1024); } while (0)
; #define PG8_MMA(ai, bj, At, Bt) do { __builtin_amdgcn_s_setprio(1); _Pragma("unroll") for (int m = 0; m < 4; ++m) _Pragma("unroll") for (int n = 0; n < 2; ++n) _Pragma("unroll") for (int k = 0; k < 2; ++k) \
;         acc[ai][bj][m][n] = __builtin_amdgcn_mfma_f32_16x16x32_bf16(Bt[n][k], At[m][k], acc[ai][bj][m][n], 0, 0, 0); __builtin_amdgcn_s_setprio(0); } while (0)
; #define PG8_WAIT_V(n) asm volatile("s_waitcnt vmcnt(" #n ")" ::: "memory")
; #define PG8_WAIT_L(n) asm volatile("s_waitcnt lgkmcnt(" #n ")" ::: "memory")
; #define PG8_BAR __builtin_amdgcn_s_barrier()
; #define PG8_SCHED __builtin_amdgcn_sched_barrier(0)
; template <class Epi, class Sched, bool ALIGN_EPI, class Hook = NoHook>
; __device__ __forceinline__ void gemm_phase(LAS unsigned char* lds, const Gemm g, const Sched& S, const Epi& E, const Hook& H = Hook()) {
;     ...
;             PG8_LDB(B0, 1, 0); PG8_LDB(B1, 1, 1); PG8_SCHED; PG8_LDA(At, 1, 0); PG8_STAGE(PG8_SA(0, 1), a2 + hA, voffA);
;             PG8_WAIT_V(8); PG8_WAIT_L(0); PG8_BAR; PG8_MMA(0, 0, At, B0); PG8_MMA(0, 1, At, B1); PG8_BAR; PG8_SCHED;
;             PG8_LDA(At, 1, 1); PG8_STAGE(PG8_SB(1, 0), b3, voffB); PG8_STAGE(PG8_SB(1, 1), b3 + hB, voffB); PG8_STAGE(PG8_SA(1, 0), a3, voffA);
;             PG8_WAIT_V(8); PG8_WAIT_L(0); PG8_BAR; PG8_MMA(1, 0, At, B0); PG8_MMA(1, 1, At, B1); PG8_BAR; PG8_SCHED;
;         }
	s_setprio 0
	s_add_i32 s65, 0, 0x18000
	s_add_i32 s66, 0, 0x1c000
	v_add_u32_e32 v142, s65, v213
	v_add_u32_e32 v158, s66, v213
	ds_read_b128 v[130:133], v142
	ds_read_b128 v[134:137], v142 offset:1024
	s_add_u32 s4, s38, 0x8000
	s_addc_u32 s5, s39, 0
	s_mov_b32 m0, s42
	s_nop 0
	global_load_lds_dwordx4 v162, s[4:5]
	ds_read_b128 v[138:141], v142 offset:2048
	ds_read_b128 v[142:145], v142 offset:3072
	ds_read_b128 v[146:149], v158
	ds_read_b128 v[150:153], v158 offset:1024
	ds_read_b128 v[154:157], v158 offset:2048
	ds_read_b128 v[158:161], v158 offset:3072
	ds_read_b128 v[180:183], v219 offset:32768
	s_mov_b32 m0, s43
	s_nop 0
	global_load_lds_dwordx4 v166, s[4:5]
	ds_read_b128 v[184:187], v219 offset:33792
	ds_read_b128 v[188:191], v219 offset:34816
	ds_read_b128 v[192:195], v219 offset:35840
	ds_read_b128 v[196:199], v219 offset:36864
	ds_read_b128 v[200:203], v219 offset:37888
	ds_read_b128 v[204:207], v219 offset:38912
	ds_read_b128 v[208:211], v219 offset:39936
	s_waitcnt vmcnt(8) lgkmcnt(0)
	s_barrier
	s_setprio 1
	v_mfma_f32_16x16x32_bf16 v[126:129], v[130:133], v[180:183], v[126:129]
	v_mfma_f32_16x16x32_bf16 v[94:97], v[138:141], v[180:183], v[94:97]
	v_mfma_f32_16x16x32_bf16 v[122:125], v[130:133], v[188:191], v[122:125]
	v_mfma_f32_16x16x32_bf16 v[90:93], v[138:141], v[188:191], v[90:93]
	v_mfma_f32_16x16x32_bf16 v[118:121], v[130:133], v[196:199], v[118:121]
	v_mfma_f32_16x16x32_bf16 v[86:89], v[138:141], v[196:199], v[86:89]
	v_mfma_f32_16x16x32_bf16 v[114:117], v[130:133], v[204:207], v[114:117]
	v_mfma_f32_16x16x32_bf16 v[82:85], v[138:141], v[204:207], v[82:85]
	v_mfma_f32_16x16x32_bf16 v[126:129], v[134:137], v[184:187], v[126:129]
	v_mfma_f32_16x16x32_bf16 v[94:97], v[142:145], v[184:187], v[94:97]
	v_mfma_f32_16x16x32_bf16 v[122:125], v[134:137], v[192:195], v[122:125]
	v_mfma_f32_16x16x32_bf16 v[90:93], v[142:145], v[192:195], v[90:93]
	v_mfma_f32_16x16x32_bf16 v[118:121], v[134:137], v[200:203], v[118:121]
	v_mfma_f32_16x16x32_bf16 v[86:89], v[142:145], v[200:203], v[86:89]
	v_mfma_f32_16x16x32_bf16 v[114:117], v[134:137], v[208:211], v[114:117]
	v_mfma_f32_16x16x32_bf16 v[82:85], v[142:145], v[208:211], v[82:85]
	s_setprio 0
	s_setprio 1
	v_mfma_f32_16x16x32_bf16 v[62:65], v[146:149], v[180:183], v[62:65]
	v_mfma_f32_16x16x32_bf16 v[30:33], v[154:157], v[180:183], v[30:33]
	v_mfma_f32_16x16x32_bf16 v[58:61], v[146:149], v[188:191], v[58:61]
	v_mfma_f32_16x16x32_bf16 v[26:29], v[154:157], v[188:191], v[26:29]
	v_mfma_f32_16x16x32_bf16 v[54:57], v[146:149], v[196:199], v[54:57]
	v_mfma_f32_16x16x32_bf16 v[22:25], v[154:157], v[196:199], v[22:25]
	v_mfma_f32_16x16x32_bf16 v[50:53], v[146:149], v[204:207], v[50:53]
	v_mfma_f32_16x16x32_bf16 v[18:21], v[154:157], v[204:207], v[18:21]
	v_mfma_f32_16x16x32_bf16 v[62:65], v[150:153], v[184:187], v[62:65]
	v_mfma_f32_16x16x32_bf16 v[30:33], v[158:161], v[184:187], v[30:33]
	v_mfma_f32_16x16x32_bf16 v[58:61], v[150:153], v[192:195], v[58:61]
	v_mfma_f32_16x16x32_bf16 v[26:29], v[158:161], v[192:195], v[26:29]
	v_mfma_f32_16x16x32_bf16 v[54:57], v[150:153], v[200:203], v[54:57]
	v_mfma_f32_16x16x32_bf16 v[22:25], v[158:161], v[200:203], v[22:25]
	v_mfma_f32_16x16x32_bf16 v[50:53], v[150:153], v[208:211], v[50:53]
	v_mfma_f32_16x16x32_bf16 v[18:21], v[158:161], v[208:211], v[18:21]
	s_barrier
	s_setprio 0
	s_add_i32 s4, s65, s21
	s_add_u32 s68, s36, s14
	s_addc_u32 s69, s37, s15
	s_mov_b32 m0, s4
	ds_read_b128 v[180:183], v219 offset:49152
	ds_read_b128 v[184:187], v219 offset:50176
	global_load_lds_dwordx4 v164, s[68:69]
	ds_read_b128 v[188:191], v219 offset:51200
	s_add_i32 m0, s4, 0x2000
	s_add_u32 s4, s36, 0x100080
	s_addc_u32 s5, s37, 0
	s_add_i32 s36, s66, s21
	global_load_lds_dwordx4 v168, s[68:69]
	ds_read_b128 v[192:195], v219 offset:52224
	s_mov_b32 m0, s36
	s_nop 0
	global_load_lds_dwordx4 v164, s[4:5]
	ds_read_b128 v[196:199], v219 offset:53248
	s_add_i32 m0, s36, 0x2000
	s_nop 0
	global_load_lds_dwordx4 v168, s[4:5]
	ds_read_b128 v[200:203], v219 offset:54272
	s_add_u32 s70, s38, s14
	s_addc_u32 s71, s39, s15
	s_mov_b32 m0, s51
	s_nop 0
	global_load_lds_dwordx4 v162, s[70:71]
	ds_read_b128 v[204:207], v219 offset:55296
	s_mov_b32 m0, s52
	s_nop 0
	global_load_lds_dwordx4 v166, s[70:71]
	ds_read_b128 v[208:211], v219 offset:56320
	s_waitcnt vmcnt(8) lgkmcnt(0)
	s_barrier
	s_setprio 1
	v_mfma_f32_16x16x32_bf16 v[110:113], v[130:133], v[180:183], v[110:113]
	v_mfma_f32_16x16x32_bf16 v[78:81], v[138:141], v[180:183], v[78:81]
	v_mfma_f32_16x16x32_bf16 v[106:109], v[130:133], v[188:191], v[106:109]
	v_mfma_f32_16x16x32_bf16 v[74:77], v[138:141], v[188:191], v[74:77]
	v_mfma_f32_16x16x32_bf16 v[102:105], v[130:133], v[196:199], v[102:105]
	v_mfma_f32_16x16x32_bf16 v[70:73], v[138:141], v[196:199], v[70:73]
	v_mfma_f32_16x16x32_bf16 v[98:101], v[130:133], v[204:207], v[98:101]
	v_mfma_f32_16x16x32_bf16 v[66:69], v[138:141], v[204:207], v[66:69]
	v_mfma_f32_16x16x32_bf16 v[110:113], v[134:137], v[184:187], v[110:113]
	v_mfma_f32_16x16x32_bf16 v[78:81], v[142:145], v[184:187], v[78:81]
	v_mfma_f32_16x16x32_bf16 v[106:109], v[134:137], v[192:195], v[106:109]
	v_mfma_f32_16x16x32_bf16 v[74:77], v[142:145], v[192:195], v[74:77]
	v_mfma_f32_16x16x32_bf16 v[102:105], v[134:137], v[200:203], v[102:105]
	v_mfma_f32_16x16x32_bf16 v[70:73], v[142:145], v[200:203], v[70:73]
	v_mfma_f32_16x16x32_bf16 v[98:101], v[134:137], v[208:211], v[98:101]
	v_mfma_f32_16x16x32_bf16 v[66:69], v[142:145], v[208:211], v[66:69]
	s_setprio 0
	s_setprio 1
	v_mfma_f32_16x16x32_bf16 v[46:49], v[146:149], v[180:183], v[46:49]
	v_mfma_f32_16x16x32_bf16 v[14:17], v[154:157], v[180:183], v[14:17]
	v_mfma_f32_16x16x32_bf16 v[42:45], v[146:149], v[188:191], v[42:45]
	v_mfma_f32_16x16x32_bf16 v[10:13], v[154:157], v[188:191], v[10:13]
	v_mfma_f32_16x16x32_bf16 v[38:41], v[146:149], v[196:199], v[38:41]
	v_mfma_f32_16x16x32_bf16 v[6:9], v[154:157], v[196:199], v[6:9]
	v_mfma_f32_16x16x32_bf16 v[34:37], v[146:149], v[204:207], v[34:37]
	v_mfma_f32_16x16x32_bf16 v[2:5], v[154:157], v[204:207], v[2:5]
	v_mfma_f32_16x16x32_bf16 v[46:49], v[150:153], v[184:187], v[46:49]
	v_mfma_f32_16x16x32_bf16 v[14:17], v[158:161], v[184:187], v[14:17]
	v_mfma_f32_16x16x32_bf16 v[42:45], v[150:153], v[192:195], v[42:45]
	v_mfma_f32_16x16x32_bf16 v[10:13], v[158:161], v[192:195], v[10:13]
	v_mfma_f32_16x16x32_bf16 v[38:41], v[150:153], v[200:203], v[38:41]
	v_mfma_f32_16x16x32_bf16 v[6:9], v[158:161], v[200:203], v[6:9]
	v_mfma_f32_16x16x32_bf16 v[34:37], v[150:153], v[208:211], v[34:37]
	v_mfma_f32_16x16x32_bf16 v[2:5], v[158:161], v[208:211], v[2:5]
	s_barrier
	s_setprio 0
	s_add_i32 s64, s64, 2
	s_add_u32 s31, s31, 0x100
	s_addc_u32 s63, s63, 0
	s_cmp_gt_u32 s64, 61
	s_mov_b64 s[4:5], s[34:35]
	s_cbranch_scc0 .Lmy_d199B

; #define PG8_STAGE(bufoff, gbase, voff) do { _Pragma("unroll") for (int _i = 0; _i < 2; ++_i) \
;         __builtin_amdgcn_global_load_lds((const unsigned*)((const char*)(gbase) + (voff)[_i]), (LAS unsigned*)(lds + (bufoff) + ldsw + _i * 8192), 16, 0, 0); } while (0)
; #define PG8_LDA(dst, b, h) do { _Pragma("unroll") for (int m = 0; m < 4; ++m) _Pragma("unroll") for (int k = 0; k < 2; ++k) dst[m][k] = *(const LAS bf16x8*)(lds + PG8_SA(b, h) + aoff + m * 2048 + k * 1024); } while (0)
; #define PG8_LDB(dst, b, h) do { _Pragma("unroll") for (int n = 0; n < 2; ++n) _Pragma("unroll") for (int k = 0; k < 2; ++k) dst[n][k] = *(const LAS bf16x8*)(lds + PG8_SB(b, h) + boff + n * 2048 + k * 1024); } while (0)
; #define PG8_MMA(ai, bj, At, Bt) do { __builtin_amdgcn_s_setprio(1); _Pragma("unroll") for (int m = 0; m < 4; ++m) _Pragma("unroll") for (int n = 0; n < 2; ++n) _Pragma("unroll") for (int k = 0; k < 2; ++k) \
;         acc[ai][bj][m][n] = __builtin_amdgcn_mfma_f32_16x16x32_bf16(Bt[n][k], At[m][k], acc[ai][bj][m][n], 0, 0, 0); __builtin_amdgcn_s_setprio(0); } while (0)
; #define PG8_WAIT_V(n) asm volatile("s_waitcnt vmcnt(" #n ")" ::: "memory")
; #define PG8_WAIT_L(n) asm volatile("s_waitcnt lgkmcnt(" #n ")" ::: "memory")
; template <class Epi, class Sched, bool ALIGN_EPI, class Hook = NoHook>
; __device__ __forceinline__ void gemm_phase(LAS unsigned char* lds, const Gemm g, const Sched& S, const Epi& E, const Hook& H = Hook()) {
;     ...
;         for (int t = tb; t < te; t += 2) {
;             const bool last = (t == nt - 2);
;             const char* a1 = cA + (size_t)(t + 1) * kstep;
;             const char* a2 = last ? nA : cA + (size_t)(t + 2) * kstep; const char* b2 = last ? nB : cB + (size_t)(t + 2) * kstep;
;             const char* a3 = a2 + kstep; const char* b3 = b2 + kstep;
;             if (last && has_next) S.a_ready(nxt);
;             PG8_LDB(B0, 0, 0); PG8_LDB(B1, 0, 1); PG8_SCHED; PG8_LDA(At, 0, 0); PG8_STAGE(PG8_SA(1, 1), a1 + hA, voffA);
;             PG8_WAIT_V(8); PG8_WAIT_L(0); PG8_BAR; PG8_MMA(0, 0, At, B0); PG8_MMA(0, 1, At, B1); PG8_BAR; PG8_SCHED;
;             PG8_LDA(At, 0, 1); PG8_STAGE(PG8_SB(0, 0), b2, voffB); PG8_STAGE(PG8_SB(0, 1), b2 + hB, voffB); PG8_STAGE(PG8_SA(0, 0), a2, voffA);
;             PG8_WAIT_V(8); PG8_WAIT_L(0); PG8_BAR; PG8_MMA(1, 0, At, B0); PG8_MMA(1, 1, At, B1); PG8_BAR; PG8_SCHED;
.LBB0_262:
	ds_read_b128 v[148:151], v145
	ds_read_b128 v[152:155], v145 offset:1024
	s_add_u32 s22, s20, 0xfff00080
	s_addc_u32 s23, s21, -1
	s_cmp_eq_u32 s50, 4
	s_cselect_b32 s25, s11, s23
	s_cselect_b32 s24, s13, s22
	s_cselect_b32 s23, s40, s43
	s_cselect_b32 s22, s41, s42
	s_add_i32 m0, s5, 0xc000
	s_nop 0
	global_load_lds_dwordx4 v136, s[20:21]
	ds_read_b128 v[156:159], v145 offset:2048
	ds_read_b128 v[160:163], v145 offset:3072
	ds_read_b128 v[164:167], v146
	ds_read_b128 v[168:171], v146 offset:1024
	ds_read_b128 v[172:175], v146 offset:2048
	ds_read_b128 v[176:179], v146 offset:3072
	ds_read_b128 v[180:183], v147
	s_add_i32 m0, s5, 0xe000
	s_nop 0
	global_load_lds_dwordx4 v138, s[20:21]
	ds_read_b128 v[184:187], v147 offset:1024
	ds_read_b128 v[188:191], v147 offset:2048
	ds_read_b128 v[192:195], v147 offset:3072
	ds_read_b128 v[196:199], v147 offset:4096
	ds_read_b128 v[200:203], v147 offset:5120
	ds_read_b128 v[204:207], v147 offset:6144
	ds_read_b128 v[208:211], v147 offset:7168
	s_waitcnt vmcnt(8) lgkmcnt(0)
	s_barrier
	s_setprio 1
	v_mfma_f32_16x16x32_bf16 v[126:129], v[148:151], v[180:183], v[126:129]
	v_mfma_f32_16x16x32_bf16 v[122:125], v[156:159], v[180:183], v[122:125]
	v_mfma_f32_16x16x32_bf16 v[118:121], v[148:151], v[188:191], v[118:121]
	v_mfma_f32_16x16x32_bf16 v[114:117], v[156:159], v[188:191], v[114:117]
	v_mfma_f32_16x16x32_bf16 v[106:109], v[148:151], v[196:199], v[106:109]
	v_mfma_f32_16x16x32_bf16 v[98:101], v[156:159], v[196:199], v[98:101]
	v_mfma_f32_16x16x32_bf16 v[90:93], v[148:151], v[204:207], v[90:93]
	v_mfma_f32_16x16x32_bf16 v[82:85], v[156:159], v[204:207], v[82:85]
	v_mfma_f32_16x16x32_bf16 v[126:129], v[152:155], v[184:187], v[126:129]
	v_mfma_f32_16x16x32_bf16 v[122:125], v[160:163], v[184:187], v[122:125]
	v_mfma_f32_16x16x32_bf16 v[118:121], v[152:155], v[192:195], v[118:121]
	v_mfma_f32_16x16x32_bf16 v[114:117], v[160:163], v[192:195], v[114:117]
	v_mfma_f32_16x16x32_bf16 v[106:109], v[152:155], v[200:203], v[106:109]
	v_mfma_f32_16x16x32_bf16 v[98:101], v[160:163], v[200:203], v[98:101]
	v_mfma_f32_16x16x32_bf16 v[90:93], v[152:155], v[208:211], v[90:93]
	v_mfma_f32_16x16x32_bf16 v[82:85], v[160:163], v[208:211], v[82:85]
	s_setprio 0
	s_setprio 1
	v_mfma_f32_16x16x32_bf16 v[110:113], v[164:167], v[180:183], v[110:113]
	v_mfma_f32_16x16x32_bf16 v[102:105], v[172:175], v[180:183], v[102:105]
	v_mfma_f32_16x16x32_bf16 v[94:97], v[164:167], v[188:191], v[94:97]
	v_mfma_f32_16x16x32_bf16 v[86:89], v[172:175], v[188:191], v[86:89]
	v_mfma_f32_16x16x32_bf16 v[78:81], v[164:167], v[196:199], v[78:81]
	v_mfma_f32_16x16x32_bf16 v[74:77], v[172:175], v[196:199], v[74:77]
	v_mfma_f32_16x16x32_bf16 v[70:73], v[164:167], v[204:207], v[70:73]
	v_mfma_f32_16x16x32_bf16 v[66:69], v[172:175], v[204:207], v[66:69]
	v_mfma_f32_16x16x32_bf16 v[110:113], v[168:171], v[184:187], v[110:113]
	v_mfma_f32_16x16x32_bf16 v[102:105], v[176:179], v[184:187], v[102:105]
	v_mfma_f32_16x16x32_bf16 v[94:97], v[168:171], v[192:195], v[94:97]
	v_mfma_f32_16x16x32_bf16 v[86:89], v[176:179], v[192:195], v[86:89]
	v_mfma_f32_16x16x32_bf16 v[78:81], v[168:171], v[200:203], v[78:81]
	v_mfma_f32_16x16x32_bf16 v[74:77], v[176:179], v[200:203], v[74:77]
	v_mfma_f32_16x16x32_bf16 v[70:73], v[168:171], v[208:211], v[70:73]
	v_mfma_f32_16x16x32_bf16 v[66:69], v[176:179], v[208:211], v[66:69]
	s_barrier
	s_setprio 0
	s_add_i32 s51, s38, s29
	s_mov_b32 m0, s51
	ds_read_b128 v[180:183], v147 offset:16384
	ds_read_b128 v[184:187], v147 offset:17408
	global_load_lds_dwordx4 v132, s[22:23]
	ds_read_b128 v[188:191], v147 offset:18432
	s_add_i32 m0, s51, 0x2000
	s_add_u32 s52, s22, 0x100000
	s_addc_u32 s53, s23, 0
	s_add_i32 s51, s39, s29
	global_load_lds_dwordx4 v130, s[22:23]
	ds_read_b128 v[192:195], v147 offset:19456
	s_mov_b32 m0, s51
	s_nop 0
	global_load_lds_dwordx4 v132, s[52:53]
	ds_read_b128 v[196:199], v147 offset:20480
	s_add_i32 m0, s51, 0x2000
	s_nop 0
	global_load_lds_dwordx4 v130, s[52:53]
	ds_read_b128 v[200:203], v147 offset:21504
	s_add_u32 s56, s24, s8
	s_addc_u32 s57, s25, s9
	s_mov_b32 m0, s5
	s_nop 0
	global_load_lds_dwordx4 v132, s[24:25]
	ds_read_b128 v[204:207], v147 offset:22528
	s_mov_b32 m0, s7
	s_nop 0
	global_load_lds_dwordx4 v130, s[24:25]
	ds_read_b128 v[208:211], v147 offset:23552
	s_waitcnt vmcnt(8) lgkmcnt(0)
	s_barrier
	s_setprio 1
	v_mfma_f32_16x16x32_bf16 v[62:65], v[148:151], v[180:183], v[62:65]
	v_mfma_f32_16x16x32_bf16 v[58:61], v[156:159], v[180:183], v[58:61]
	v_mfma_f32_16x16x32_bf16 v[54:57], v[148:151], v[188:191], v[54:57]
	v_mfma_f32_16x16x32_bf16 v[50:53], v[156:159], v[188:191], v[50:53]
	v_mfma_f32_16x16x32_bf16 v[38:41], v[148:151], v[196:199], v[38:41]
	v_mfma_f32_16x16x32_bf16 v[34:37], v[156:159], v[196:199], v[34:37]
	v_mfma_f32_16x16x32_bf16 v[22:25], v[148:151], v[204:207], v[22:25]
	v_mfma_f32_16x16x32_bf16 v[18:21], v[156:159], v[204:207], v[18:21]
	v_mfma_f32_16x16x32_bf16 v[62:65], v[152:155], v[184:187], v[62:65]
	v_mfma_f32_16x16x32_bf16 v[58:61], v[160:163], v[184:187], v[58:61]
	v_mfma_f32_16x16x32_bf16 v[54:57], v[152:155], v[192:195], v[54:57]
	v_mfma_f32_16x16x32_bf16 v[50:53], v[160:163], v[192:195], v[50:53]
	v_mfma_f32_16x16x32_bf16 v[38:41], v[152:155], v[200:203], v[38:41]
	v_mfma_f32_16x16x32_bf16 v[34:37], v[160:163], v[200:203], v[34:37]
	v_mfma_f32_16x16x32_bf16 v[22:25], v[152:155], v[208:211], v[22:25]
	v_mfma_f32_16x16x32_bf16 v[18:21], v[160:163], v[208:211], v[18:21]
	s_setprio 0
	s_setprio 1
	v_mfma_f32_16x16x32_bf16 v[46:49], v[164:167], v[180:183], v[46:49]
	v_mfma_f32_16x16x32_bf16 v[42:45], v[172:175], v[180:183], v[42:45]
	v_mfma_f32_16x16x32_bf16 v[30:33], v[164:167], v[188:191], v[30:33]
	v_mfma_f32_16x16x32_bf16 v[26:29], v[172:175], v[188:191], v[26:29]
	v_mfma_f32_16x16x32_bf16 v[14:17], v[164:167], v[196:199], v[14:17]
	v_mfma_f32_16x16x32_bf16 v[10:13], v[172:175], v[196:199], v[10:13]
	v_mfma_f32_16x16x32_bf16 v[6:9], v[164:167], v[204:207], v[6:9]
	v_mfma_f32_16x16x32_bf16 v[2:5], v[172:175], v[204:207], v[2:5]
	v_mfma_f32_16x16x32_bf16 v[46:49], v[168:171], v[184:187], v[46:49]
	v_mfma_f32_16x16x32_bf16 v[42:45], v[176:179], v[184:187], v[42:45]
	v_mfma_f32_16x16x32_bf16 v[30:33], v[168:171], v[192:195], v[30:33]
	v_mfma_f32_16x16x32_bf16 v[26:29], v[176:179], v[192:195], v[26:29]
	v_mfma_f32_16x16x32_bf16 v[14:17], v[168:171], v[200:203], v[14:17]
	v_mfma_f32_16x16x32_bf16 v[10:13], v[176:179], v[200:203], v[10:13]
	v_mfma_f32_16x16x32_bf16 v[6:9], v[168:171], v[208:211], v[6:9]
	v_mfma_f32_16x16x32_bf16 v[2:5], v[176:179], v[208:211], v[2:5]
	s_barrier
; #define PG8_STAGE(bufoff, gbase, voff) do { _Pragma("unroll") for (int _i = 0; _i < 2; ++_i) \
;         __builtin_amdgcn_global_load_lds((const unsigned*)((const char*)(gbase) + (voff)[_i]), (LAS unsigned*)(lds + (bufoff) + ldsw + _i * 8192), 16, 0, 0); } while (0)
; #define PG8_LDA(dst, b, h) do { _Pragma("unroll") for (int m = 0; m < 4; ++m) _Pragma("unroll") for (int k = 0; k < 2; ++k) dst[m][k] = *(const LAS bf16x8*)(lds + PG8_SA(b, h) + aoff + m * 2048 + k * 1024); } while (0)
; #define PG8_LDB(dst, b, h) do { _Pragma("unroll") for (int n = 0; n < 2; ++n) _Pragma("unroll") for (int k = 0; k < 2; ++k) dst[n][k] = *(const LAS bf16x8*)(lds + PG8_SB(b, h) + boff + n * 2048 + k * 1024); } while (0)
; #define PG8_MMA(ai, bj, At, Bt) do { __builtin_amdgcn_s_setprio(1); _Pragma("unroll") for (int m = 0; m < 4; ++m) _Pragma("unroll") for (int n = 0; n < 2; ++n) _Pragma("unroll") for (int k = 0; k < 2; ++k) \
;         acc[ai][bj][m][n] = __builtin_amdgcn_mfma_f32_16x16x32_bf16(Bt[n][k], At[m][k], acc[ai][bj][m][n], 0, 0, 0); __builtin_amdgcn_s_setprio(0); } while (0)
; #define PG8_WAIT_V(n) asm volatile("s_waitcnt vmcnt(" #n ")" ::: "memory")
; #define PG8_WAIT_L(n) asm volatile("s_waitcnt lgkmcnt(" #n ")" ::: "memory")
; #define PG8_BAR __builtin_amdgcn_s_barrier()
; #define PG8_SCHED __builtin_amdgcn_sched_barrier(0)
; template <class Epi, class Sched, bool ALIGN_EPI, class Hook = NoHook>
; __device__ __forceinline__ void gemm_phase(LAS unsigned char* lds, const Gemm g, const Sched& S, const Epi& E, const Hook& H = Hook()) {
;     ...
;             PG8_WAIT_V(8); PG8_WAIT_L(0); PG8_BAR; PG8_MMA(1, 0, At, B0); PG8_MMA(1, 1, At, B1); PG8_BAR; PG8_SCHED;
;             PG8_LDB(B0, 1, 0); PG8_LDB(B1, 1, 1); PG8_SCHED; PG8_LDA(At, 1, 0); PG8_STAGE(PG8_SA(0, 1), a2 + hA, voffA);
;             PG8_WAIT_V(8); PG8_WAIT_L(0); PG8_BAR; PG8_MMA(0, 0, At, B0); PG8_MMA(0, 1, At, B1); PG8_BAR; PG8_SCHED;
;             PG8_LDA(At, 1, 1); PG8_STAGE(PG8_SB(1, 0), b3, voffB); PG8_STAGE(PG8_SB(1, 1), b3 + hB, voffB); PG8_STAGE(PG8_SA(1, 0), a3, voffA);
	s_setprio 0
	s_add_i32 s51, 0, 0x18000
	s_add_i32 s52, 0, 0x1c000
	v_add_u32_e32 v160, s51, v144
	v_add_u32_e32 v176, s52, v144
	ds_read_b128 v[148:151], v160
	ds_read_b128 v[152:155], v160 offset:1024
	s_add_u32 s24, s24, 0x100000
	s_addc_u32 s25, s25, 0
	s_mov_b32 m0, s30
	s_nop 0
	global_load_lds_dwordx4 v132, s[24:25]
	ds_read_b128 v[156:159], v160 offset:2048
	ds_read_b128 v[160:163], v160 offset:3072
	ds_read_b128 v[164:167], v176
	ds_read_b128 v[168:171], v176 offset:1024
	ds_read_b128 v[172:175], v176 offset:2048
	ds_read_b128 v[176:179], v176 offset:3072
	ds_read_b128 v[180:183], v147 offset:32768
	s_mov_b32 m0, s31
	s_nop 0
	global_load_lds_dwordx4 v130, s[24:25]
	ds_read_b128 v[184:187], v147 offset:33792
	ds_read_b128 v[188:191], v147 offset:34816
	ds_read_b128 v[192:195], v147 offset:35840
	ds_read_b128 v[196:199], v147 offset:36864
	ds_read_b128 v[200:203], v147 offset:37888
	ds_read_b128 v[204:207], v147 offset:38912
	ds_read_b128 v[208:211], v147 offset:39936
	s_waitcnt vmcnt(8) lgkmcnt(0)
	s_barrier
	s_setprio 1
	v_mfma_f32_16x16x32_bf16 v[126:129], v[148:151], v[180:183], v[126:129]
	v_mfma_f32_16x16x32_bf16 v[122:125], v[156:159], v[180:183], v[122:125]
	v_mfma_f32_16x16x32_bf16 v[118:121], v[148:151], v[188:191], v[118:121]
	v_mfma_f32_16x16x32_bf16 v[114:117], v[156:159], v[188:191], v[114:117]
	v_mfma_f32_16x16x32_bf16 v[106:109], v[148:151], v[196:199], v[106:109]
	v_mfma_f32_16x16x32_bf16 v[98:101], v[156:159], v[196:199], v[98:101]
	v_mfma_f32_16x16x32_bf16 v[90:93], v[148:151], v[204:207], v[90:93]
	v_mfma_f32_16x16x32_bf16 v[82:85], v[156:159], v[204:207], v[82:85]
	v_mfma_f32_16x16x32_bf16 v[126:129], v[152:155], v[184:187], v[126:129]
	v_mfma_f32_16x16x32_bf16 v[122:125], v[160:163], v[184:187], v[122:125]
	v_mfma_f32_16x16x32_bf16 v[118:121], v[152:155], v[192:195], v[118:121]
	v_mfma_f32_16x16x32_bf16 v[114:117], v[160:163], v[192:195], v[114:117]
	v_mfma_f32_16x16x32_bf16 v[106:109], v[152:155], v[200:203], v[106:109]
	v_mfma_f32_16x16x32_bf16 v[98:101], v[160:163], v[200:203], v[98:101]
	v_mfma_f32_16x16x32_bf16 v[90:93], v[152:155], v[208:211], v[90:93]
	v_mfma_f32_16x16x32_bf16 v[82:85], v[160:163], v[208:211], v[82:85]
	s_setprio 0
	s_setprio 1
	v_mfma_f32_16x16x32_bf16 v[110:113], v[164:167], v[180:183], v[110:113]
	v_mfma_f32_16x16x32_bf16 v[102:105], v[172:175], v[180:183], v[102:105]
	v_mfma_f32_16x16x32_bf16 v[94:97], v[164:167], v[188:191], v[94:97]
	v_mfma_f32_16x16x32_bf16 v[86:89], v[172:175], v[188:191], v[86:89]
	v_mfma_f32_16x16x32_bf16 v[78:81], v[164:167], v[196:199], v[78:81]
	v_mfma_f32_16x16x32_bf16 v[74:77], v[172:175], v[196:199], v[74:77]
	v_mfma_f32_16x16x32_bf16 v[70:73], v[164:167], v[204:207], v[70:73]
	v_mfma_f32_16x16x32_bf16 v[66:69], v[172:175], v[204:207], v[66:69]
	v_mfma_f32_16x16x32_bf16 v[110:113], v[168:171], v[184:187], v[110:113]
	v_mfma_f32_16x16x32_bf16 v[102:105], v[176:179], v[184:187], v[102:105]
	v_mfma_f32_16x16x32_bf16 v[94:97], v[168:171], v[192:195], v[94:97]
	v_mfma_f32_16x16x32_bf16 v[86:89], v[176:179], v[192:195], v[86:89]
	v_mfma_f32_16x16x32_bf16 v[78:81], v[168:171], v[200:203], v[78:81]
	v_mfma_f32_16x16x32_bf16 v[74:77], v[176:179], v[200:203], v[74:77]
	v_mfma_f32_16x16x32_bf16 v[70:73], v[168:171], v[208:211], v[70:73]
	v_mfma_f32_16x16x32_bf16 v[66:69], v[176:179], v[208:211], v[66:69]
	s_barrier
	s_setprio 0
	s_add_i32 s24, s51, s29
	s_add_u32 s54, s22, s8
	s_addc_u32 s55, s23, s9
	s_mov_b32 m0, s24
	ds_read_b128 v[180:183], v147 offset:49152
	ds_read_b128 v[184:187], v147 offset:50176
	global_load_lds_dwordx4 v132, s[54:55]
	ds_read_b128 v[188:191], v147 offset:51200
	s_add_i32 m0, s24, 0x2000
	s_add_u32 s22, s22, 0x100080
	s_addc_u32 s23, s23, 0
	s_add_i32 s24, s52, s29
	global_load_lds_dwordx4 v130, s[54:55]
	ds_read_b128 v[192:195], v147 offset:52224
	s_mov_b32 m0, s24
	s_nop 0
	global_load_lds_dwordx4 v132, s[22:23]
	ds_read_b128 v[196:199], v147 offset:53248
	s_add_i32 m0, s24, 0x2000
	s_nop 0
	global_load_lds_dwordx4 v130, s[22:23]
	ds_read_b128 v[200:203], v147 offset:54272
	s_mov_b32 m0, s35
	s_nop 0
	global_load_lds_dwordx4 v132, s[56:57]
	ds_read_b128 v[204:207], v147 offset:55296
	s_mov_b32 m0, s36
	s_nop 0
	global_load_lds_dwordx4 v130, s[56:57]
	ds_read_b128 v[208:211], v147 offset:56320
	s_waitcnt vmcnt(8) lgkmcnt(0)
	s_barrier
; #define PG8_MMA(ai, bj, At, Bt) do { __builtin_amdgcn_s_setprio(1); _Pragma("unroll") for (int m = 0; m < 4; ++m) _Pragma("unroll") for (int n = 0; n < 2; ++n) _Pragma("unroll") for (int k = 0; k < 2; ++k) \
;         acc[ai][bj][m][n] = __builtin_amdgcn_mfma_f32_16x16x32_bf16(Bt[n][k], At[m][k], acc[ai][bj][m][n], 0, 0, 0); __builtin_amdgcn_s_setprio(0); } while (0)
; #define PG8_WAIT_V(n) asm volatile("s_waitcnt vmcnt(" #n ")" ::: "memory")
; #define PG8_WAIT_L(n) asm volatile("s_waitcnt lgkmcnt(" #n ")" ::: "memory")
; #define PG8_BAR __builtin_amdgcn_s_barrier()
; #define PG8_SCHED __builtin_amdgcn_sched_barrier(0)
;     __device__ __forceinline__ void operator()(const f32x4 (&acc)[2][2][4][2], const Unit& u, int wr, int wc, int fr, int fq) const {
;         float* base = C + (size_t)(u.ka / kslab) * slab_stride;
;         const int row0 = u.pm * BM + wr * 64 + fr, col0 = wc * 32 + 4 * fq;
; #pragma unroll
;         for (int ai = 0; ai < 2; ++ai)
; #pragma unroll
;             for (int m = 0; m < 4; ++m) { float* rowp = base + (size_t)(row0 + ai * HALF + m * 16) * 256 + col0;
; #pragma unroll
;                 for (int bj = 0; bj < 2; ++bj)
; #pragma unroll
;                     for (int n = 0; n < 2; ++n) *(f32x4*)(rowp + bj * HALF + n * 16) = acc[ai][bj][m][n]; }
;     }
; template <class Epi, class Sched, bool ALIGN_EPI, class Hook = NoHook>
; __device__ __forceinline__ void gemm_phase(LAS unsigned char* lds, const Gemm g, const Sched& S, const Epi& E, const Hook& H = Hook()) {
;     ...
;             PG8_WAIT_V(8); PG8_WAIT_L(0); PG8_BAR; PG8_MMA(1, 0, At, B0); PG8_MMA(1, 1, At, B1); PG8_BAR; PG8_SCHED;
;         }
;         if constexpr (Hook::ON) H.after(te, acc, cur, wr, wc, fr, fq);
;         }
;         if constexpr (ALIGN_EPI) { if (wr == 0) PG8_BAR; }
;         if constexpr (!Epi::AFTER_DRAIN) { E(acc, cur, wr, wc, fr, fq); S.done(cur); }
;         if (!has_next) break;
	s_setprio 1
	v_mfma_f32_16x16x32_bf16 v[62:65], v[148:151], v[180:183], v[62:65]
	v_mfma_f32_16x16x32_bf16 v[58:61], v[156:159], v[180:183], v[58:61]
	v_mfma_f32_16x16x32_bf16 v[54:57], v[148:151], v[188:191], v[54:57]
	v_mfma_f32_16x16x32_bf16 v[50:53], v[156:159], v[188:191], v[50:53]
	v_mfma_f32_16x16x32_bf16 v[38:41], v[148:151], v[196:199], v[38:41]
	v_mfma_f32_16x16x32_bf16 v[34:37], v[156:159], v[196:199], v[34:37]
	v_mfma_f32_16x16x32_bf16 v[22:25], v[148:151], v[204:207], v[22:25]
	v_mfma_f32_16x16x32_bf16 v[18:21], v[156:159], v[204:207], v[18:21]
	v_mfma_f32_16x16x32_bf16 v[62:65], v[152:155], v[184:187], v[62:65]
	v_mfma_f32_16x16x32_bf16 v[58:61], v[160:163], v[184:187], v[58:61]
	v_mfma_f32_16x16x32_bf16 v[54:57], v[152:155], v[192:195], v[54:57]
	v_mfma_f32_16x16x32_bf16 v[50:53], v[160:163], v[192:195], v[50:53]
	v_mfma_f32_16x16x32_bf16 v[38:41], v[152:155], v[200:203], v[38:41]
	v_mfma_f32_16x16x32_bf16 v[34:37], v[160:163], v[200:203], v[34:37]
	v_mfma_f32_16x16x32_bf16 v[22:25], v[152:155], v[208:211], v[22:25]
	v_mfma_f32_16x16x32_bf16 v[18:21], v[160:163], v[208:211], v[18:21]
	s_setprio 0
	s_setprio 1
	v_mfma_f32_16x16x32_bf16 v[46:49], v[164:167], v[180:183], v[46:49]
	v_mfma_f32_16x16x32_bf16 v[42:45], v[172:175], v[180:183], v[42:45]
	v_mfma_f32_16x16x32_bf16 v[30:33], v[164:167], v[188:191], v[30:33]
	v_mfma_f32_16x16x32_bf16 v[26:29], v[172:175], v[188:191], v[26:29]
	v_mfma_f32_16x16x32_bf16 v[14:17], v[164:167], v[196:199], v[14:17]
	v_mfma_f32_16x16x32_bf16 v[10:13], v[172:175], v[196:199], v[10:13]
	v_mfma_f32_16x16x32_bf16 v[6:9], v[164:167], v[204:207], v[6:9]
	v_mfma_f32_16x16x32_bf16 v[2:5], v[172:175], v[204:207], v[2:5]
	v_mfma_f32_16x16x32_bf16 v[46:49], v[168:171], v[184:187], v[46:49]
	v_mfma_f32_16x16x32_bf16 v[42:45], v[176:179], v[184:187], v[42:45]
	v_mfma_f32_16x16x32_bf16 v[30:33], v[168:171], v[192:195], v[30:33]
	v_mfma_f32_16x16x32_bf16 v[26:29], v[176:179], v[192:195], v[26:29]
	v_mfma_f32_16x16x32_bf16 v[14:17], v[168:171], v[200:203], v[14:17]
	v_mfma_f32_16x16x32_bf16 v[10:13], v[176:179], v[200:203], v[10:13]
	v_mfma_f32_16x16x32_bf16 v[6:9], v[168:171], v[208:211], v[6:9]
	v_mfma_f32_16x16x32_bf16 v[2:5], v[176:179], v[208:211], v[2:5]
	s_barrier
	s_setprio 0
	s_add_i32 s50, s50, 2
	s_add_u32 s20, s20, 0x100
	s_addc_u32 s21, s21, 0
	s_add_u32 s42, s42, 0x100
	s_addc_u32 s43, s43, 0
	s_cmp_gt_u32 s50, 5
	s_cbranch_scc0 .LBB0_262
	s_ashr_i32 s11, s6, 31
	s_lshr_b32 s11, s11, 23
	s_add_i32 s6, s6, s11
	s_ashr_i32 s20, s6, 9
	s_ashr_i32 s21, s20, 31
	v_lshl_add_u32 v148, s4, 8, v1
	s_lshl_b64 s[20:21], s[20:21], 23
	v_ashrrev_i32_e32 v149, 31, v148
	v_lshl_add_u64 v[150:151], v[134:135], 0, s[20:21]
	v_lshlrev_b64 v[152:153], 10, v[148:149]
	v_lshl_add_u64 v[152:153], v[150:151], 0, v[152:153]
	global_store_dwordx4 v[152:153], v[126:129], off
	global_store_dwordx4 v[152:153], v[122:125], off offset:64
	global_store_dwordx4 v[152:153], v[110:113], off offset:512
	global_store_dwordx4 v[152:153], v[102:105], off offset:576
	s_mov_b32 s4, 0x20000
	s_mov_b64 s[20:21], 0x20000
	v_or_b32_e32 v102, 16, v148
	v_ashrrev_i32_e32 v103, 31, v102
	v_lshlrev_b64 v[102:103], 10, v[102:103]
	v_lshl_add_u64 v[102:103], v[150:151], 0, v[102:103]
	global_store_dwordx4 v[102:103], v[118:121], off
	global_store_dwordx4 v[102:103], v[114:117], off offset:64
	global_store_dwordx4 v[102:103], v[94:97], off offset:512
	global_store_dwordx4 v[102:103], v[86:89], off offset:576
	s_mov_b32 s6, s12
	s_mov_b64 s[22:23], s[18:19]
	v_or_b32_e32 v86, 32, v148
	v_ashrrev_i32_e32 v87, 31, v86
	v_lshlrev_b64 v[86:87], 10, v[86:87]
	v_lshl_add_u64 v[86:87], v[150:151], 0, v[86:87]
	global_store_dwordx4 v[86:87], v[106:109], off
	global_store_dwordx4 v[86:87], v[98:101], off offset:64
	global_store_dwordx4 v[86:87], v[78:81], off offset:512
	global_store_dwordx4 v[86:87], v[74:77], off offset:576
	s_nop 1
	v_or_b32_e32 v74, 48, v148
	v_ashrrev_i32_e32 v75, 31, v74
	v_lshlrev_b64 v[74:75], 10, v[74:75]
	v_lshl_add_u64 v[74:75], v[150:151], 0, v[74:75]
	global_store_dwordx4 v[74:75], v[90:93], off
	global_store_dwordx4 v[74:75], v[82:85], off offset:64
	global_store_dwordx4 v[74:75], v[70:73], off offset:512
	global_store_dwordx4 v[74:75], v[66:69], off offset:576
	s_nop 1
	v_add_co_u32_e32 v68, vcc, s4, v152
	s_mov_b32 s4, 0x24000
	s_nop 0
	v_addc_co_u32_e32 v69, vcc, 0, v153, vcc
	v_lshl_add_u64 v[66:67], v[152:153], 0, s[20:21]
	global_store_dwordx4 v[68:69], v[62:65], off
	global_store_dwordx4 v[66:67], v[58:61], off offset:64
	global_store_dwordx4 v[66:67], v[46:49], off offset:512
	global_store_dwordx4 v[66:67], v[42:45], off offset:576
	s_mov_b64 s[20:21], 0x24000
	s_nop 0
	v_add_co_u32_e32 v44, vcc, s4, v152
	s_mov_b32 s4, 0x28000
	s_nop 0
	v_addc_co_u32_e32 v45, vcc, 0, v153, vcc
	v_lshl_add_u64 v[42:43], v[152:153], 0, s[20:21]
	global_store_dwordx4 v[44:45], v[54:57], off
	global_store_dwordx4 v[42:43], v[50:53], off offset:64
	global_store_dwordx4 v[42:43], v[30:33], off offset:512
	global_store_dwordx4 v[42:43], v[26:29], off offset:576
	s_mov_b64 s[20:21], 0x28000
	s_nop 0
	v_add_co_u32_e32 v28, vcc, s4, v152
	v_lshl_add_u64 v[26:27], v[152:153], 0, s[20:21]
	s_nop 0
	v_addc_co_u32_e32 v29, vcc, 0, v153, vcc
	global_store_dwordx4 v[28:29], v[38:41], off
	global_store_dwordx4 v[26:27], v[34:37], off offset:64
	global_store_dwordx4 v[26:27], v[14:17], off offset:512
	global_store_dwordx4 v[26:27], v[10:13], off offset:576
	s_mov_b64 s[20:21], 0x2c000
	s_mov_b32 s4, s10
	v_add_co_u32_e32 v12, vcc, 0x2c000, v152
	v_lshl_add_u64 v[10:11], v[152:153], 0, s[20:21]
	s_nop 0
	v_addc_co_u32_e32 v13, vcc, 0, v153, vcc
	s_and_b64 vcc, exec, s[2:3]
	s_mov_b64 s[20:21], s[14:15]
	global_store_dwordx4 v[12:13], v[22:25], off
	global_store_dwordx4 v[10:11], v[18:21], off offset:64
	global_store_dwordx4 v[10:11], v[6:9], off offset:512
	global_store_dwordx4 v[10:11], v[2:5], off offset:576
	s_cbranch_vccz .LBB0_259
	s_waitcnt vmcnt(0)
	s_cmpk_gt_u32 s26, 0xff
	s_cbranch_scc1 .LBB0_266
	s_barrier

; #define PG8_STAGE(bufoff, gbase, voff) do { _Pragma("unroll") for (int _i = 0; _i < 2; ++_i) \
;         __builtin_amdgcn_global_load_lds((const unsigned*)((const char*)(gbase) + (voff)[_i]), (LAS unsigned*)(lds + (bufoff) + ldsw + _i * 8192), 16, 0, 0); } while (0)
; #define PG8_LDA(dst, b, h) do { _Pragma("unroll") for (int m = 0; m < 4; ++m) _Pragma("unroll") for (int k = 0; k < 2; ++k) dst[m][k] = *(const LAS bf16x8*)(lds + PG8_SA(b, h) + aoff + m * 2048 + k * 1024); } while (0)
; #define PG8_LDB(dst, b, h) do { _Pragma("unroll") for (int n = 0; n < 2; ++n) _Pragma("unroll") for (int k = 0; k < 2; ++k) dst[n][k] = *(const LAS bf16x8*)(lds + PG8_SB(b, h) + boff + n * 2048 + k * 1024); } while (0)
; #define PG8_MMA(ai, bj, At, Bt) do { __builtin_amdgcn_s_setprio(1); _Pragma("unroll") for (int m = 0; m < 4; ++m) _Pragma("unroll") for (int n = 0; n < 2; ++n) _Pragma("unroll") for (int k = 0; k < 2; ++k) \
;         acc[ai][bj][m][n] = __builtin_amdgcn_mfma_f32_16x16x32_bf16(Bt[n][k], At[m][k], acc[ai][bj][m][n], 0, 0, 0); __builtin_amdgcn_s_setprio(0); } while (0)
; #define PG8_WAIT_V(n) asm volatile("s_waitcnt vmcnt(" #n ")" ::: "memory")
; #define PG8_WAIT_L(n) asm volatile("s_waitcnt lgkmcnt(" #n ")" ::: "memory")
; template <class Epi, class Sched, bool ALIGN_EPI, class Hook = NoHook>
; __device__ __forceinline__ void gemm_phase(LAS unsigned char* lds, const Gemm g, const Sched& S, const Epi& E, const Hook& H = Hook()) {
;     ...
;         for (int t = tb; t < te; t += 2) {
;             const bool last = (t == nt - 2);
;             const char* a1 = cA + (size_t)(t + 1) * kstep;
;             const char* a2 = last ? nA : cA + (size_t)(t + 2) * kstep; const char* b2 = last ? nB : cB + (size_t)(t + 2) * kstep;
;             const char* a3 = a2 + kstep; const char* b3 = b2 + kstep;
;             if (last && has_next) S.a_ready(nxt);
;             PG8_LDB(B0, 0, 0); PG8_LDB(B1, 0, 1); PG8_SCHED; PG8_LDA(At, 0, 0); PG8_STAGE(PG8_SA(1, 1), a1 + hA, voffA);
;             PG8_WAIT_V(8); PG8_WAIT_L(0); PG8_BAR; PG8_MMA(0, 0, At, B0); PG8_MMA(0, 1, At, B1); PG8_BAR; PG8_SCHED;
;             PG8_LDA(At, 0, 1); PG8_STAGE(PG8_SB(0, 0), b2, voffB); PG8_STAGE(PG8_SB(0, 1), b2 + hB, voffB); PG8_STAGE(PG8_SA(0, 0), a2, voffA);
;             PG8_WAIT_V(8); PG8_WAIT_L(0); PG8_BAR; PG8_MMA(1, 0, At, B0); PG8_MMA(1, 1, At, B1); PG8_BAR; PG8_SCHED;
.LBB0_783:
	v_add_u32_e32 v3, s56, v222
	s_add_i32 s67, s67, 2
	ds_read_b128 v[126:129], v3
	ds_read_b128 v[130:133], v3 offset:1024
	ds_read_b128 v[142:145], v3 offset:2048
	ds_read_b128 v[146:149], v3 offset:3072
	v_add_u32_e32 v3, s57, v222
	s_add_u32 s28, s22, s26
	s_addc_u32 s29, s23, s27
	s_add_u32 s28, s28, 0x100
	s_addc_u32 s29, s29, 0
	s_add_u32 s68, s63, s26
	s_addc_u32 s69, s64, s27
	s_cmpk_eq_i32 s26, 0x5f00
	s_cselect_b32 s31, s5, s29
	s_cselect_b32 s30, s4, s28
	s_cselect_b32 s29, s21, s69
	s_cselect_b32 s28, s20, s68
	ds_read_b128 v[150:153], v3
	ds_read_b128 v[154:157], v3 offset:1024
	ds_read_b128 v[158:161], v3 offset:2048
	ds_read_b128 v[162:165], v3 offset:3072
	v_lshl_add_u64 v[4:5], v[182:183], 0, s[26:27]
	s_add_i32 m0, s37, 0xc000
	s_nop 0
	global_load_lds_dwordx4 v[4:5], off
	ds_read_b128 v[186:189], v224
	ds_read_b128 v[190:193], v224 offset:1024
	ds_read_b128 v[194:197], v224 offset:2048
	ds_read_b128 v[198:201], v224 offset:3072
	ds_read_b128 v[202:205], v224 offset:4096
	ds_read_b128 v[206:209], v224 offset:5120
	ds_read_b128 v[210:213], v224 offset:6144
	ds_read_b128 v[214:217], v224 offset:7168
	v_lshl_add_u64 v[4:5], v[184:185], 0, s[26:27]
	s_add_i32 m0, s37, 0xe000
	s_nop 0
	global_load_lds_dwordx4 v[4:5], off
	s_waitcnt vmcnt(8) lgkmcnt(0)
	s_barrier
	s_setprio 1
	v_mfma_f32_16x16x32_bf16 v[138:141], v[126:129], v[186:189], v[138:141]
	v_mfma_f32_16x16x32_bf16 v[134:137], v[142:145], v[186:189], v[134:137]
	v_mfma_f32_16x16x32_bf16 v[122:125], v[126:129], v[194:197], v[122:125]
	v_mfma_f32_16x16x32_bf16 v[118:121], v[142:145], v[194:197], v[118:121]
	v_mfma_f32_16x16x32_bf16 v[114:117], v[126:129], v[202:205], v[114:117]
	v_mfma_f32_16x16x32_bf16 v[110:113], v[142:145], v[202:205], v[110:113]
	v_mfma_f32_16x16x32_bf16 v[106:109], v[126:129], v[210:213], v[106:109]
	v_mfma_f32_16x16x32_bf16 v[102:105], v[142:145], v[210:213], v[102:105]
	v_mfma_f32_16x16x32_bf16 v[138:141], v[130:133], v[190:193], v[138:141]
	v_mfma_f32_16x16x32_bf16 v[134:137], v[146:149], v[190:193], v[134:137]
	v_mfma_f32_16x16x32_bf16 v[122:125], v[130:133], v[198:201], v[122:125]
	v_mfma_f32_16x16x32_bf16 v[118:121], v[146:149], v[198:201], v[118:121]
	v_mfma_f32_16x16x32_bf16 v[114:117], v[130:133], v[206:209], v[114:117]
	v_mfma_f32_16x16x32_bf16 v[110:113], v[146:149], v[206:209], v[110:113]
	v_mfma_f32_16x16x32_bf16 v[106:109], v[130:133], v[214:217], v[106:109]
	v_mfma_f32_16x16x32_bf16 v[102:105], v[146:149], v[214:217], v[102:105]
	s_setprio 0
	s_setprio 1
	v_mfma_f32_16x16x32_bf16 v[66:69], v[150:153], v[186:189], v[66:69]
	v_mfma_f32_16x16x32_bf16 v[62:65], v[158:161], v[186:189], v[62:65]
	v_mfma_f32_16x16x32_bf16 v[58:61], v[150:153], v[194:197], v[58:61]
	v_mfma_f32_16x16x32_bf16 v[54:57], v[158:161], v[194:197], v[54:57]
	v_mfma_f32_16x16x32_bf16 v[50:53], v[150:153], v[202:205], v[50:53]
	v_mfma_f32_16x16x32_bf16 v[46:49], v[158:161], v[202:205], v[46:49]
	v_mfma_f32_16x16x32_bf16 v[42:45], v[150:153], v[210:213], v[42:45]
	v_mfma_f32_16x16x32_bf16 v[38:41], v[158:161], v[210:213], v[38:41]
	v_mfma_f32_16x16x32_bf16 v[66:69], v[154:157], v[190:193], v[66:69]
	v_mfma_f32_16x16x32_bf16 v[62:65], v[162:165], v[190:193], v[62:65]
	v_mfma_f32_16x16x32_bf16 v[58:61], v[154:157], v[198:201], v[58:61]
	v_mfma_f32_16x16x32_bf16 v[54:57], v[162:165], v[198:201], v[54:57]
	v_mfma_f32_16x16x32_bf16 v[50:53], v[154:157], v[206:209], v[50:53]
	v_mfma_f32_16x16x32_bf16 v[46:49], v[162:165], v[206:209], v[46:49]
	v_mfma_f32_16x16x32_bf16 v[42:45], v[154:157], v[214:217], v[42:45]
	v_mfma_f32_16x16x32_bf16 v[38:41], v[162:165], v[214:217], v[38:41]
	s_barrier
	s_setprio 0
	s_add_i32 s68, s56, s35
	s_mov_b32 m0, s68
	ds_read_b128 v[186:189], v224 offset:16384
	ds_read_b128 v[190:193], v224 offset:17408
	global_load_lds_dwordx4 v168, s[28:29]
	ds_read_b128 v[194:197], v224 offset:18432
	s_add_i32 m0, s68, 0x2000
	s_add_u32 s68, s28, 0x300000
	s_addc_u32 s69, s29, 0
	s_add_i32 s70, s57, s35
	global_load_lds_dwordx4 v172, s[28:29]
	ds_read_b128 v[198:201], v224 offset:19456
	s_mov_b32 m0, s70
	s_add_u32 s74, s30, s14
	s_addc_u32 s75, s31, s15
	global_load_lds_dwordx4 v168, s[68:69]
	ds_read_b128 v[202:205], v224 offset:20480
	s_add_i32 m0, s70, 0x2000
	s_nop 0
	global_load_lds_dwordx4 v172, s[68:69]
	ds_read_b128 v[206:209], v224 offset:21504
	s_mov_b32 m0, s37
	s_nop 0
	global_load_lds_dwordx4 v166, s[30:31]
	ds_read_b128 v[210:213], v224 offset:22528
	s_mov_b32 m0, s38
	s_nop 0
	global_load_lds_dwordx4 v170, s[30:31]
	ds_read_b128 v[214:217], v224 offset:23552
	s_waitcnt vmcnt(8) lgkmcnt(0)
	s_barrier
; #define PG8_STAGE(bufoff, gbase, voff) do { _Pragma("unroll") for (int _i = 0; _i < 2; ++_i) \
;         __builtin_amdgcn_global_load_lds((const unsigned*)((const char*)(gbase) + (voff)[_i]), (LAS unsigned*)(lds + (bufoff) + ldsw + _i * 8192), 16, 0, 0); } while (0)
; #define PG8_LDA(dst, b, h) do { _Pragma("unroll") for (int m = 0; m < 4; ++m) _Pragma("unroll") for (int k = 0; k < 2; ++k) dst[m][k] = *(const LAS bf16x8*)(lds + PG8_SA(b, h) + aoff + m * 2048 + k * 1024); } while (0)
; #define PG8_LDB(dst, b, h) do { _Pragma("unroll") for (int n = 0; n < 2; ++n) _Pragma("unroll") for (int k = 0; k < 2; ++k) dst[n][k] = *(const LAS bf16x8*)(lds + PG8_SB(b, h) + boff + n * 2048 + k * 1024); } while (0)
; #define PG8_MMA(ai, bj, At, Bt) do { __builtin_amdgcn_s_setprio(1); _Pragma("unroll") for (int m = 0; m < 4; ++m) _Pragma("unroll") for (int n = 0; n < 2; ++n) _Pragma("unroll") for (int k = 0; k < 2; ++k) \
;         acc[ai][bj][m][n] = __builtin_amdgcn_mfma_f32_16x16x32_bf16(Bt[n][k], At[m][k], acc[ai][bj][m][n], 0, 0, 0); __builtin_amdgcn_s_setprio(0); } while (0)
; #define PG8_WAIT_V(n) asm volatile("s_waitcnt vmcnt(" #n ")" ::: "memory")
; #define PG8_WAIT_L(n) asm volatile("s_waitcnt lgkmcnt(" #n ")" ::: "memory")
; #define PG8_BAR __builtin_amdgcn_s_barrier()
; #define PG8_SCHED __builtin_amdgcn_sched_barrier(0)
; template <class Epi, class Sched, bool ALIGN_EPI, class Hook = NoHook>
; __device__ __forceinline__ void gemm_phase(LAS unsigned char* lds, const Gemm g, const Sched& S, const Epi& E, const Hook& H = Hook()) {
;     ...
;             PG8_WAIT_V(8); PG8_WAIT_L(0); PG8_BAR; PG8_MMA(1, 0, At, B0); PG8_MMA(1, 1, At, B1); PG8_BAR; PG8_SCHED;
;             PG8_LDB(B0, 1, 0); PG8_LDB(B1, 1, 1); PG8_SCHED; PG8_LDA(At, 1, 0); PG8_STAGE(PG8_SA(0, 1), a2 + hA, voffA);
;             PG8_WAIT_V(8); PG8_WAIT_L(0); PG8_BAR; PG8_MMA(0, 0, At, B0); PG8_MMA(0, 1, At, B1); PG8_BAR; PG8_SCHED;
;             PG8_LDA(At, 1, 1); PG8_STAGE(PG8_SB(1, 0), b3, voffB); PG8_STAGE(PG8_SB(1, 1), b3 + hB, voffB); PG8_STAGE(PG8_SA(1, 0), a3, voffA);
	s_setprio 1
	v_mfma_f32_16x16x32_bf16 v[98:101], v[126:129], v[186:189], v[98:101]
	v_mfma_f32_16x16x32_bf16 v[94:97], v[142:145], v[186:189], v[94:97]
	v_mfma_f32_16x16x32_bf16 v[90:93], v[126:129], v[194:197], v[90:93]
	v_mfma_f32_16x16x32_bf16 v[86:89], v[142:145], v[194:197], v[86:89]
	v_mfma_f32_16x16x32_bf16 v[82:85], v[126:129], v[202:205], v[82:85]
	v_mfma_f32_16x16x32_bf16 v[78:81], v[142:145], v[202:205], v[78:81]
	v_mfma_f32_16x16x32_bf16 v[74:77], v[126:129], v[210:213], v[74:77]
	v_mfma_f32_16x16x32_bf16 v[70:73], v[142:145], v[210:213], v[70:73]
	v_mfma_f32_16x16x32_bf16 v[98:101], v[130:133], v[190:193], v[98:101]
	v_mfma_f32_16x16x32_bf16 v[94:97], v[146:149], v[190:193], v[94:97]
	v_mfma_f32_16x16x32_bf16 v[90:93], v[130:133], v[198:201], v[90:93]
	v_mfma_f32_16x16x32_bf16 v[86:89], v[146:149], v[198:201], v[86:89]
	v_mfma_f32_16x16x32_bf16 v[82:85], v[130:133], v[206:209], v[82:85]
	v_mfma_f32_16x16x32_bf16 v[78:81], v[146:149], v[206:209], v[78:81]
	v_mfma_f32_16x16x32_bf16 v[74:77], v[130:133], v[214:217], v[74:77]
	v_mfma_f32_16x16x32_bf16 v[70:73], v[146:149], v[214:217], v[70:73]
	s_setprio 0
	s_setprio 1
	v_mfma_f32_16x16x32_bf16 v[34:37], v[150:153], v[186:189], v[34:37]
	v_mfma_f32_16x16x32_bf16 v[30:33], v[158:161], v[186:189], v[30:33]
	v_mfma_f32_16x16x32_bf16 v[26:29], v[150:153], v[194:197], v[26:29]
	v_mfma_f32_16x16x32_bf16 v[22:25], v[158:161], v[194:197], v[22:25]
	v_mfma_f32_16x16x32_bf16 v[18:21], v[150:153], v[202:205], v[18:21]
	v_mfma_f32_16x16x32_bf16 v[14:17], v[158:161], v[202:205], v[14:17]
	v_mfma_f32_16x16x32_bf16 v[10:13], v[150:153], v[210:213], v[10:13]
	v_mfma_f32_16x16x32_bf16 v[4:7], v[158:161], v[210:213], v[6:9]
	v_mfma_f32_16x16x32_bf16 v[34:37], v[154:157], v[190:193], v[34:37]
	v_mfma_f32_16x16x32_bf16 v[30:33], v[162:165], v[190:193], v[30:33]
	v_mfma_f32_16x16x32_bf16 v[26:29], v[154:157], v[198:201], v[26:29]
	v_mfma_f32_16x16x32_bf16 v[22:25], v[162:165], v[198:201], v[22:25]
	v_mfma_f32_16x16x32_bf16 v[18:21], v[154:157], v[206:209], v[18:21]
	v_mfma_f32_16x16x32_bf16 v[14:17], v[162:165], v[206:209], v[14:17]
	v_mfma_f32_16x16x32_bf16 v[10:13], v[154:157], v[214:217], v[10:13]
	v_mfma_f32_16x16x32_bf16 v[4:7], v[162:165], v[214:217], v[4:7]
	s_barrier
	s_setprio 0
	s_add_i32 s68, 0, 0x18000
	v_add_u32_e32 v3, s68, v222
	s_add_i32 s69, 0, 0x1c000
	ds_read_b128 v[126:129], v3
	ds_read_b128 v[130:133], v3 offset:1024
	ds_read_b128 v[142:145], v3 offset:2048
	ds_read_b128 v[146:149], v3 offset:3072
	v_add_u32_e32 v3, s69, v222
	s_add_u32 s30, s30, 0x300000
	s_addc_u32 s31, s31, 0
	s_mov_b32 m0, s39
	s_nop 0
	global_load_lds_dwordx4 v166, s[30:31]
	ds_read_b128 v[150:153], v3
	ds_read_b128 v[154:157], v3 offset:1024
	ds_read_b128 v[158:161], v3 offset:2048
	ds_read_b128 v[162:165], v3 offset:3072
	ds_read_b128 v[186:189], v224 offset:32768
	ds_read_b128 v[190:193], v224 offset:33792
	ds_read_b128 v[194:197], v224 offset:34816
	s_mov_b32 m0, s40
	s_nop 0
	global_load_lds_dwordx4 v170, s[30:31]
	ds_read_b128 v[198:201], v224 offset:35840
	ds_read_b128 v[202:205], v224 offset:36864
	ds_read_b128 v[206:209], v224 offset:37888
	ds_read_b128 v[210:213], v224 offset:38912
	ds_read_b128 v[214:217], v224 offset:39936
	s_waitcnt vmcnt(8) lgkmcnt(0)
	s_barrier
	s_setprio 1
	v_mfma_f32_16x16x32_bf16 v[138:141], v[126:129], v[186:189], v[138:141]
	v_mfma_f32_16x16x32_bf16 v[134:137], v[142:145], v[186:189], v[134:137]
	v_mfma_f32_16x16x32_bf16 v[122:125], v[126:129], v[194:197], v[122:125]
	v_mfma_f32_16x16x32_bf16 v[118:121], v[142:145], v[194:197], v[118:121]
	v_mfma_f32_16x16x32_bf16 v[114:117], v[126:129], v[202:205], v[114:117]
	v_mfma_f32_16x16x32_bf16 v[110:113], v[142:145], v[202:205], v[110:113]
	v_mfma_f32_16x16x32_bf16 v[106:109], v[126:129], v[210:213], v[106:109]
	v_mfma_f32_16x16x32_bf16 v[102:105], v[142:145], v[210:213], v[102:105]
	v_mfma_f32_16x16x32_bf16 v[138:141], v[130:133], v[190:193], v[138:141]
	v_mfma_f32_16x16x32_bf16 v[134:137], v[146:149], v[190:193], v[134:137]
	v_mfma_f32_16x16x32_bf16 v[122:125], v[130:133], v[198:201], v[122:125]
	v_mfma_f32_16x16x32_bf16 v[118:121], v[146:149], v[198:201], v[118:121]
	v_mfma_f32_16x16x32_bf16 v[114:117], v[130:133], v[206:209], v[114:117]
	v_mfma_f32_16x16x32_bf16 v[110:113], v[146:149], v[206:209], v[110:113]
	v_mfma_f32_16x16x32_bf16 v[106:109], v[130:133], v[214:217], v[106:109]
	v_mfma_f32_16x16x32_bf16 v[102:105], v[146:149], v[214:217], v[102:105]
	s_setprio 0
	s_setprio 1
	v_mfma_f32_16x16x32_bf16 v[66:69], v[150:153], v[186:189], v[66:69]
	v_mfma_f32_16x16x32_bf16 v[62:65], v[158:161], v[186:189], v[62:65]
	v_mfma_f32_16x16x32_bf16 v[58:61], v[150:153], v[194:197], v[58:61]
	v_mfma_f32_16x16x32_bf16 v[54:57], v[158:161], v[194:197], v[54:57]
	v_mfma_f32_16x16x32_bf16 v[50:53], v[150:153], v[202:205], v[50:53]
	v_mfma_f32_16x16x32_bf16 v[46:49], v[158:161], v[202:205], v[46:49]
	v_mfma_f32_16x16x32_bf16 v[42:45], v[150:153], v[210:213], v[42:45]
	v_mfma_f32_16x16x32_bf16 v[38:41], v[158:161], v[210:213], v[38:41]
	v_mfma_f32_16x16x32_bf16 v[66:69], v[154:157], v[190:193], v[66:69]
	v_mfma_f32_16x16x32_bf16 v[62:65], v[162:165], v[190:193], v[62:65]
	v_mfma_f32_16x16x32_bf16 v[58:61], v[154:157], v[198:201], v[58:61]
	v_mfma_f32_16x16x32_bf16 v[54:57], v[162:165], v[198:201], v[54:57]
	v_mfma_f32_16x16x32_bf16 v[50:53], v[154:157], v[206:209], v[50:53]
	v_mfma_f32_16x16x32_bf16 v[46:49], v[162:165], v[206:209], v[46:49]
	v_mfma_f32_16x16x32_bf16 v[42:45], v[154:157], v[214:217], v[42:45]
	v_mfma_f32_16x16x32_bf16 v[38:41], v[162:165], v[214:217], v[38:41]
	s_barrier
; #define PG8_MMA(ai, bj, At, Bt) do { __builtin_amdgcn_s_setprio(1); _Pragma("unroll") for (int m = 0; m < 4; ++m) _Pragma("unroll") for (int n = 0; n < 2; ++n) _Pragma("unroll") for (int k = 0; k < 2; ++k) \
;         acc[ai][bj][m][n] = __builtin_amdgcn_mfma_f32_16x16x32_bf16(Bt[n][k], At[m][k], acc[ai][bj][m][n], 0, 0, 0); __builtin_amdgcn_s_setprio(0); } while (0)
; #define PG8_WAIT_V(n) asm volatile("s_waitcnt vmcnt(" #n ")" ::: "memory")
; #define PG8_WAIT_L(n) asm volatile("s_waitcnt lgkmcnt(" #n ")" ::: "memory")
; #define PG8_BAR __builtin_amdgcn_s_barrier()
; #define PG8_SCHED __builtin_amdgcn_sched_barrier(0)
;     __device__ __forceinline__ void after(int te, f32x4 (&acc)[2][2][4][2], const Unit& u, int wr, int wc, int fr, int fq) const {
;         if (te > D_INNER / BK) return;
;         const int g = (te >> 4) - 1;
;         asm volatile("" : "+v"(fr), "+v"(fq));
; #pragma unroll
;         for (int ai = 0; ai < 2; ++ai)
; #pragma unroll
;             for (int m = 0; m < 4; ++m) { const float f = tab[(ai * HALF + wr * 64 + m * 16 + fr) * 8 + g];
; #pragma unroll
;                 for (int bj = 0; bj < 2; ++bj)
; #pragma unroll
;                     for (int n = 0; n < 2; ++n) acc[ai][bj][m][n] *= f; }
; template <class Epi, class Sched, bool ALIGN_EPI, class Hook = NoHook>
; __device__ __forceinline__ void gemm_phase(LAS unsigned char* lds, const Gemm g, const Sched& S, const Epi& E, const Hook& H = Hook()) {
;     ...
;             PG8_WAIT_V(8); PG8_WAIT_L(0); PG8_BAR; PG8_MMA(1, 0, At, B0); PG8_MMA(1, 1, At, B1); PG8_BAR; PG8_SCHED;
;         }
;         if constexpr (Hook::ON) H.after(te, acc, cur, wr, wc, fr, fq);
	s_setprio 0
	s_add_i32 s30, s68, s35
	s_add_u32 s72, s28, s14
	s_addc_u32 s73, s29, s15
	s_mov_b32 m0, s30
	ds_read_b128 v[186:189], v224 offset:49152
	ds_read_b128 v[190:193], v224 offset:50176
	global_load_lds_dwordx4 v168, s[72:73]
	ds_read_b128 v[194:197], v224 offset:51200
	s_add_i32 m0, s30, 0x2000
	s_add_u32 s28, s28, 0x300080
	s_addc_u32 s29, s29, 0
	s_add_i32 s30, s69, s35
	global_load_lds_dwordx4 v172, s[72:73]
	ds_read_b128 v[198:201], v224 offset:52224
	s_mov_b32 m0, s30
	s_nop 0
	global_load_lds_dwordx4 v168, s[28:29]
	ds_read_b128 v[202:205], v224 offset:53248
	s_add_i32 m0, s30, 0x2000
	s_nop 0
	global_load_lds_dwordx4 v172, s[28:29]
	ds_read_b128 v[206:209], v224 offset:54272
	s_mov_b32 m0, s45
	s_nop 0
	global_load_lds_dwordx4 v166, s[74:75]
	ds_read_b128 v[210:213], v224 offset:55296
	s_mov_b32 m0, s46
	s_nop 0
	global_load_lds_dwordx4 v170, s[74:75]
	ds_read_b128 v[214:217], v224 offset:56320
	s_waitcnt vmcnt(8) lgkmcnt(0)
	s_barrier
	s_setprio 1
	v_mfma_f32_16x16x32_bf16 v[98:101], v[126:129], v[186:189], v[98:101]
	v_mfma_f32_16x16x32_bf16 v[94:97], v[142:145], v[186:189], v[94:97]
	v_mfma_f32_16x16x32_bf16 v[90:93], v[126:129], v[194:197], v[90:93]
	v_mfma_f32_16x16x32_bf16 v[86:89], v[142:145], v[194:197], v[86:89]
	v_mfma_f32_16x16x32_bf16 v[82:85], v[126:129], v[202:205], v[82:85]
	v_mfma_f32_16x16x32_bf16 v[78:81], v[142:145], v[202:205], v[78:81]
	v_mfma_f32_16x16x32_bf16 v[74:77], v[126:129], v[210:213], v[74:77]
	v_mfma_f32_16x16x32_bf16 v[70:73], v[142:145], v[210:213], v[70:73]
	v_mfma_f32_16x16x32_bf16 v[98:101], v[130:133], v[190:193], v[98:101]
	v_mfma_f32_16x16x32_bf16 v[94:97], v[146:149], v[190:193], v[94:97]
	v_mfma_f32_16x16x32_bf16 v[90:93], v[130:133], v[198:201], v[90:93]
	v_mfma_f32_16x16x32_bf16 v[86:89], v[146:149], v[198:201], v[86:89]
	v_mfma_f32_16x16x32_bf16 v[82:85], v[130:133], v[206:209], v[82:85]
	v_mfma_f32_16x16x32_bf16 v[78:81], v[146:149], v[206:209], v[78:81]
	v_mfma_f32_16x16x32_bf16 v[74:77], v[130:133], v[214:217], v[74:77]
	v_mfma_f32_16x16x32_bf16 v[70:73], v[146:149], v[214:217], v[70:73]
	s_setprio 0
	s_setprio 1
	v_mfma_f32_16x16x32_bf16 v[34:37], v[150:153], v[186:189], v[34:37]
	v_mfma_f32_16x16x32_bf16 v[30:33], v[158:161], v[186:189], v[30:33]
	v_mfma_f32_16x16x32_bf16 v[26:29], v[150:153], v[194:197], v[26:29]
	v_mfma_f32_16x16x32_bf16 v[22:25], v[158:161], v[194:197], v[22:25]
	v_mfma_f32_16x16x32_bf16 v[18:21], v[150:153], v[202:205], v[18:21]
	v_mfma_f32_16x16x32_bf16 v[14:17], v[158:161], v[202:205], v[14:17]
	v_mfma_f32_16x16x32_bf16 v[8:11], v[150:153], v[210:213], v[10:13]
	v_mfma_f32_16x16x32_bf16 v[4:7], v[158:161], v[210:213], v[4:7]
	v_mfma_f32_16x16x32_bf16 v[34:37], v[154:157], v[190:193], v[34:37]
	v_mfma_f32_16x16x32_bf16 v[30:33], v[162:165], v[190:193], v[30:33]
	v_mfma_f32_16x16x32_bf16 v[26:29], v[154:157], v[198:201], v[26:29]
	v_mfma_f32_16x16x32_bf16 v[22:25], v[162:165], v[198:201], v[22:25]
	v_mfma_f32_16x16x32_bf16 v[18:21], v[154:157], v[206:209], v[18:21]
	v_mfma_f32_16x16x32_bf16 v[14:17], v[162:165], v[206:209], v[14:17]
	v_mfma_f32_16x16x32_bf16 v[10:13], v[154:157], v[214:217], v[8:11]
	v_mfma_f32_16x16x32_bf16 v[6:9], v[162:165], v[214:217], v[4:7]
	s_barrier
	s_setprio 0
	s_add_u32 s26, s26, 0x100
	s_addc_u32 s27, s27, 0
	s_cmp_ge_u32 s67, s66
	s_cbranch_scc0 .LBB0_783
	s_cmpk_gt_u32 s65, 0x7f
	s_cbranch_scc1 .LBB0_787
	s_lshr_b32 s26, s66, 4
	s_add_i32 s26, s26, -1
	v_mov_b32_e32 v3, v1
	v_mov_b32_e32 v4, v220
	s_lshl_b32 s27, s26, 2
	s_add_i32 s28, s27, s48
	v_lshlrev_b32_e32 v5, 5, v3
	v_add_u32_e32 v126, s28, v5
	ds_read_b32 v126, v126
	s_add_i32 s28, s27, s49
	s_waitcnt lgkmcnt(0)
	v_pk_mul_f32 v[140:141], v[140:141], v[126:127] op_sel_hi:[1,0]
	v_pk_mul_f32 v[138:139], v[138:139], v[126:127] op_sel_hi:[1,0]
	v_pk_mul_f32 v[136:137], v[136:137], v[126:127] op_sel_hi:[1,0]
	v_pk_mul_f32 v[134:135], v[134:135], v[126:127] op_sel_hi:[1,0]
	v_pk_mul_f32 v[68:69], v[68:69], v[126:127] op_sel_hi:[1,0]
	v_pk_mul_f32 v[66:67], v[66:67], v[126:127] op_sel_hi:[1,0]
	v_pk_mul_f32 v[64:65], v[64:65], v[126:127] op_sel_hi:[1,0]
	v_pk_mul_f32 v[62:63], v[62:63], v[126:127] op_sel_hi:[1,0]
	v_add_u32_e32 v126, s28, v5
	ds_read_b32 v126, v126
	s_add_i32 s28, s27, s50
	s_waitcnt lgkmcnt(0)
	v_pk_mul_f32 v[124:125], v[124:125], v[126:127] op_sel_hi:[1,0]
	v_pk_mul_f32 v[122:123], v[122:123], v[126:127] op_sel_hi:[1,0]
	v_pk_mul_f32 v[120:121], v[120:121], v[126:127] op_sel_hi:[1,0]
	v_pk_mul_f32 v[118:119], v[118:119], v[126:127] op_sel_hi:[1,0]
	v_pk_mul_f32 v[60:61], v[60:61], v[126:127] op_sel_hi:[1,0]
	v_pk_mul_f32 v[58:59], v[58:59], v[126:127] op_sel_hi:[1,0]
	v_pk_mul_f32 v[56:57], v[56:57], v[126:127] op_sel_hi:[1,0]
	v_pk_mul_f32 v[54:55], v[54:55], v[126:127] op_sel_hi:[1,0]
	v_add_u32_e32 v126, s28, v5
	ds_read_b32 v126, v126
	s_add_i32 s28, s27, s51
	s_waitcnt lgkmcnt(0)
	v_pk_mul_f32 v[116:117], v[116:117], v[126:127] op_sel_hi:[1,0]
	v_pk_mul_f32 v[114:115], v[114:115], v[126:127] op_sel_hi:[1,0]
	v_pk_mul_f32 v[112:113], v[112:113], v[126:127] op_sel_hi:[1,0]
	v_pk_mul_f32 v[110:111], v[110:111], v[126:127] op_sel_hi:[1,0]
	v_pk_mul_f32 v[52:53], v[52:53], v[126:127] op_sel_hi:[1,0]
	v_pk_mul_f32 v[50:51], v[50:51], v[126:127] op_sel_hi:[1,0]
	v_pk_mul_f32 v[48:49], v[48:49], v[126:127] op_sel_hi:[1,0]
	v_pk_mul_f32 v[46:47], v[46:47], v[126:127] op_sel_hi:[1,0]
	v_add_u32_e32 v126, s28, v5
	ds_read_b32 v126, v126
	s_add_i32 s28, s27, s52
	s_waitcnt lgkmcnt(0)
;     __device__ __forceinline__ void after(int te, f32x4 (&acc)[2][2][4][2], const Unit& u, int wr, int wc, int fr, int fq) const {
;     ...
; #pragma unroll
;         for (int ai = 0; ai < 2; ++ai)
; #pragma unroll
;             for (int m = 0; m < 4; ++m) { const float f = tab[(ai * HALF + wr * 64 + m * 16 + fr) * 8 + g];
; #pragma unroll
;                 for (int bj = 0; bj < 2; ++bj)
; #pragma unroll
;                     for (int n = 0; n < 2; ++n) acc[ai][bj][m][n] *= f; }
;         if (g == 7) {
;             const int row0 = u.pm * BM + wr * 64 + fr, col0 = u.pn * BM + wc * 32 + 8 * fq;
; #pragma unroll
;             for (int bj = 0; bj < 2; ++bj) { const int c = col0 + bj * HALF;
;                 const f32x4 s0 = *(const f32x4*)(gb + c), s1 = *(const f32x4*)(gb + c + 4), a0 = *(const f32x4*)(gb + D_MODEL + c), a1 = *(const f32x4*)(gb + D_MODEL + c + 4);
; #pragma unroll
;                 for (int ai = 0; ai < 2; ++ai) {
;                     u32x4 gs[4], ga[4];
; #pragma unroll
;                     for (int m = 0; m < 4; ++m) { const size_t r = (size_t)(row0 + ai * HALF + m * 16); gs[m] = *(const u32x4*)(proj + r * LDP + PGS + c); ga[m] = *(const u32x4*)(proj + r * LDP + PGA + c); }
	v_pk_mul_f32 v[108:109], v[108:109], v[126:127] op_sel_hi:[1,0]
	v_pk_mul_f32 v[106:107], v[106:107], v[126:127] op_sel_hi:[1,0]
	v_pk_mul_f32 v[104:105], v[104:105], v[126:127] op_sel_hi:[1,0]
	v_pk_mul_f32 v[102:103], v[102:103], v[126:127] op_sel_hi:[1,0]
	v_pk_mul_f32 v[44:45], v[44:45], v[126:127] op_sel_hi:[1,0]
	v_pk_mul_f32 v[42:43], v[42:43], v[126:127] op_sel_hi:[1,0]
	v_pk_mul_f32 v[40:41], v[40:41], v[126:127] op_sel_hi:[1,0]
	v_pk_mul_f32 v[38:39], v[38:39], v[126:127] op_sel_hi:[1,0]
	v_add_u32_e32 v126, s28, v5
	ds_read_b32 v126, v126
	s_add_i32 s28, s27, s53
	s_waitcnt lgkmcnt(0)
	v_pk_mul_f32 v[100:101], v[100:101], v[126:127] op_sel_hi:[1,0]
	v_pk_mul_f32 v[98:99], v[98:99], v[126:127] op_sel_hi:[1,0]
	v_pk_mul_f32 v[96:97], v[96:97], v[126:127] op_sel_hi:[1,0]
	v_pk_mul_f32 v[94:95], v[94:95], v[126:127] op_sel_hi:[1,0]
	v_pk_mul_f32 v[36:37], v[36:37], v[126:127] op_sel_hi:[1,0]
	v_pk_mul_f32 v[34:35], v[34:35], v[126:127] op_sel_hi:[1,0]
	v_pk_mul_f32 v[32:33], v[32:33], v[126:127] op_sel_hi:[1,0]
	v_pk_mul_f32 v[30:31], v[30:31], v[126:127] op_sel_hi:[1,0]
	v_add_u32_e32 v126, s28, v5
	ds_read_b32 v126, v126
	s_add_i32 s28, s27, s54
	s_add_i32 s27, s27, s55
	s_cmp_lg_u32 s26, 7
	s_waitcnt lgkmcnt(0)
	v_pk_mul_f32 v[92:93], v[92:93], v[126:127] op_sel_hi:[1,0]
	v_pk_mul_f32 v[90:91], v[90:91], v[126:127] op_sel_hi:[1,0]
	v_pk_mul_f32 v[88:89], v[88:89], v[126:127] op_sel_hi:[1,0]
	v_pk_mul_f32 v[86:87], v[86:87], v[126:127] op_sel_hi:[1,0]
	v_pk_mul_f32 v[28:29], v[28:29], v[126:127] op_sel_hi:[1,0]
	v_pk_mul_f32 v[26:27], v[26:27], v[126:127] op_sel_hi:[1,0]
	v_pk_mul_f32 v[24:25], v[24:25], v[126:127] op_sel_hi:[1,0]
	v_pk_mul_f32 v[22:23], v[22:23], v[126:127] op_sel_hi:[1,0]
	v_add_u32_e32 v126, s28, v5
	ds_read_b32 v126, v126
	v_add_u32_e32 v5, s27, v5
	s_waitcnt lgkmcnt(0)
	v_pk_mul_f32 v[84:85], v[84:85], v[126:127] op_sel_hi:[1,0]
	v_pk_mul_f32 v[82:83], v[82:83], v[126:127] op_sel_hi:[1,0]
	v_pk_mul_f32 v[80:81], v[80:81], v[126:127] op_sel_hi:[1,0]
	v_pk_mul_f32 v[78:79], v[78:79], v[126:127] op_sel_hi:[1,0]
	v_pk_mul_f32 v[20:21], v[20:21], v[126:127] op_sel_hi:[1,0]
	v_pk_mul_f32 v[18:19], v[18:19], v[126:127] op_sel_hi:[1,0]
	v_pk_mul_f32 v[16:17], v[16:17], v[126:127] op_sel_hi:[1,0]
	v_pk_mul_f32 v[14:15], v[14:15], v[126:127] op_sel_hi:[1,0]
	ds_read_b32 v126, v5
	s_waitcnt lgkmcnt(0)
	v_pk_mul_f32 v[76:77], v[76:77], v[126:127] op_sel_hi:[1,0]
	v_pk_mul_f32 v[74:75], v[74:75], v[126:127] op_sel_hi:[1,0]
	v_pk_mul_f32 v[72:73], v[72:73], v[126:127] op_sel_hi:[1,0]
	v_pk_mul_f32 v[70:71], v[70:71], v[126:127] op_sel_hi:[1,0]
	v_pk_mul_f32 v[12:13], v[12:13], v[126:127] op_sel_hi:[1,0]
	v_pk_mul_f32 v[10:11], v[10:11], v[126:127] op_sel_hi:[1,0]
	v_pk_mul_f32 v[8:9], v[8:9], v[126:127] op_sel_hi:[1,0]
	v_pk_mul_f32 v[6:7], v[6:7], v[126:127] op_sel_hi:[1,0]
	s_cbranch_scc1 .LBB0_787
	v_add_u32_e32 v126, s62, v3
	v_ashrrev_i32_e32 v127, 31, v126
	v_lshl_add_u32 v4, v4, 3, s61
	v_lshlrev_b64 v[126:127], 14, v[126:127]
	v_ashrrev_i32_e32 v5, 31, v4
	v_lshl_add_u64 v[126:127], s[76:77], 0, v[126:127]
	v_lshl_add_u64 v[192:193], v[4:5], 1, v[126:127]
	v_readlane_b32 s68, v254, 20
	global_load_dwordx4 v[204:207], v[192:193], off
	v_add_co_u32_e32 v126, vcc, s41, v192
	v_lshlrev_b64 v[4:5], 2, v[4:5]
	v_readlane_b32 s70, v254, 22
	v_readlane_b32 s71, v254, 23
	v_addc_co_u32_e32 v127, vcc, 0, v193, vcc
	s_nop 0
	v_lshl_add_u64 v[196:197], s[70:71], 0, v[4:5]
	global_load_dwordx4 v[208:211], v[126:127], off
	global_load_dwordx4 v[142:145], v[196:197], off
	s_nop 0
	global_load_dwordx4 v[126:129], v[196:197], off offset:16
	v_lshl_add_u64 v[198:199], s[12:13], 0, v[4:5]
	global_load_dwordx4 v[146:149], v[198:199], off
	global_load_dwordx4 v[130:133], v[198:199], off offset:16
	s_mov_b64 s[26:27], 0x40000
	v_lshl_add_u64 v[4:5], v[192:193], 0, s[26:27]
	s_mov_b32 s26, 0x40000
	v_add_co_u32_e32 v150, vcc, s26, v192
	s_mov_b64 s[26:27], 0x42000
	s_nop 0
	v_addc_co_u32_e32 v151, vcc, 0, v193, vcc
	v_lshl_add_u64 v[186:187], v[192:193], 0, s[26:27]
	s_mov_b32 s26, 0x42000
	v_add_co_u32_e32 v152, vcc, s26, v192
	s_mov_b64 s[26:27], 0x80000
	s_nop 0
	v_addc_co_u32_e32 v153, vcc, 0, v193, vcc
	v_lshl_add_u64 v[188:189], v[192:193], 0, s[26:27]
	s_mov_b32 s26, 0x80000
	v_add_co_u32_e32 v154, vcc, s26, v192
	s_mov_b64 s[26:27], 0x82000
	s_nop 0
	v_addc_co_u32_e32 v155, vcc, 0, v193, vcc
	v_lshl_add_u64 v[190:191], v[192:193], 0, s[26:27]
	s_mov_b32 s26, 0x82000
	v_add_co_u32_e32 v156, vcc, s26, v192
	s_mov_b64 s[26:27], 0xc0000
	s_nop 0
	v_addc_co_u32_e32 v157, vcc, 0, v193, vcc
	v_lshl_add_u64 v[194:195], v[192:193], 0, s[26:27]
	s_mov_b32 s26, 0xc0000
	v_add_co_u32_e32 v228, vcc, s26, v192
	s_mov_b64 s[26:27], 0xc2000
	s_nop 0
	v_addc_co_u32_e32 v229, vcc, 0, v193, vcc
	v_lshl_add_u64 v[200:201], v[192:193], 0, s[26:27]
	s_mov_b32 s26, 0xc2000
	v_add_co_u32_e32 v230, vcc, s26, v192
	s_mov_b32 s26, 0x200000
	s_nop 0
	v_addc_co_u32_e32 v231, vcc, 0, v193, vcc
	global_load_dwordx4 v[212:215], v[150:151], off
	global_load_dwordx4 v[216:219], v[152:153], off
	global_load_dwordx4 v[162:165], v[154:155], off
	global_load_dwordx4 v[158:161], v[156:157], off
	s_nop 0
	global_load_dwordx4 v[154:157], v[228:229], off
	global_load_dwordx4 v[150:153], v[230:231], off
	v_lshl_add_u64 v[202:203], v[192:193], 0, s[18:19]
	v_readlane_b32 s76, v254, 28
	v_readlane_b32 s77, v254, 29
	v_readlane_b32 s76, v255, 8
	v_readlane_b32 s77, v255, 9
	v_readlane_b32 s69, v254, 21
	v_readlane_b32 s72, v254, 24
	v_readlane_b32 s73, v254, 25
	v_readlane_b32 s74, v254, 26
	v_readlane_b32 s75, v254, 27
	v_readlane_b32 s78, v254, 30
	v_readlane_b32 s79, v254, 31
	v_readlane_b32 s80, v254, 32
	v_readlane_b32 s81, v254, 33
	v_readlane_b32 s82, v254, 34
	v_readlane_b32 s83, v254, 35
	s_waitcnt vmcnt(0)
; __device__ __forceinline__ void unpack8(const u32x4 w, float (&v)[8]) { v[0] = bf_lo(w.x); v[1] = bf_hi(w.x); v[2] = bf_lo(w.y); v[3] = bf_hi(w.y); v[4] = bf_lo(w.z); v[5] = bf_hi(w.z); v[6] = bf_lo(w.w); v[7] = bf_hi(w.w); }
;     __device__ __forceinline__ void after(int te, f32x4 (&acc)[2][2][4][2], const Unit& u, int wr, int wc, int fr, int fq) const {
;     ...
;                     for (int m = 0; m < 4; ++m) { float vs[8], va[8]; unpack8(gs[m], vs); unpack8(ga[m], va);
; #pragma unroll
;                         for (int e = 0; e < 4; ++e) {
;                             acc[ai][bj][m][0][e] *= (1.f + __expf(-(va[e] + a0[e]))) * __builtin_amdgcn_rcpf(1.f + __expf(-(vs[e] + s0[e])));
;                             acc[ai][bj][m][1][e] *= (1.f + __expf(-(va[4 + e] + a1[e]))) * __builtin_amdgcn_rcpf(1.f + __expf(-(vs[4 + e] + s1[e]))); } }
	v_lshlrev_b32_e32 v3, 16, v204
	v_and_b32_e32 v204, 0xffff0000, v204
	v_lshlrev_b32_e32 v225, 16, v205
	v_and_b32_e32 v227, 0xffff0000, v205
	v_lshlrev_b32_e32 v205, 16, v206
	v_and_b32_e32 v228, 0xffff0000, v206
	v_lshlrev_b32_e32 v229, 16, v207
	v_and_b32_e32 v233, 0xffff0000, v207
	v_add_f32_e32 v3, v142, v3
	v_add_f32_e32 v204, v143, v204
	v_mul_f32_e32 v3, 0xbfb8aa3b, v3
	v_mul_f32_e32 v204, 0xbfb8aa3b, v204
	v_exp_f32_e32 v3, v3
	v_lshlrev_b32_e32 v230, 16, v209
	v_and_b32_e32 v231, 0xffff0000, v209
	v_exp_f32_e32 v209, v204
	v_lshlrev_b32_e32 v206, 16, v208
	v_and_b32_e32 v207, 0xffff0000, v208
	v_lshlrev_b32_e32 v208, 16, v210
	v_add_f32_e32 v206, v146, v206
	v_add_f32_e32 v208, v130, v208
	v_mul_f32_e32 v206, 0xbfb8aa3b, v206
	v_mul_f32_e32 v208, 0xbfb8aa3b, v208
	v_add_f32_e32 v3, 1.0, v3
	v_exp_f32_e32 v204, v206
	v_exp_f32_e32 v206, v208
	v_rcp_f32_e32 v208, v3
	v_add_f32_e32 v3, 1.0, v209
	v_rcp_f32_e32 v209, v3
	v_add_f32_e32 v3, v127, v228
	v_mul_f32_e32 v3, 0xbfb8aa3b, v3
	v_exp_f32_e32 v3, v3
	v_lshlrev_b32_e32 v234, 16, v211
	v_and_b32_e32 v235, 0xffff0000, v211
	v_add_f32_e32 v205, v126, v205
	v_add_f32_e32 v3, 1.0, v3
	v_rcp_f32_e32 v211, v3
	v_add_f32_e32 v3, v144, v225
	v_mul_f32_e32 v3, 0xbfb8aa3b, v3
	v_exp_f32_e32 v3, v3
	v_mul_f32_e32 v205, 0xbfb8aa3b, v205
	v_exp_f32_e32 v205, v205
	v_add_f32_e32 v225, v148, v230
	v_add_f32_e32 v3, 1.0, v3
	v_rcp_f32_e32 v230, v3
	v_add_f32_e32 v3, v128, v229
	v_mul_f32_e32 v3, 0xbfb8aa3b, v3
	v_add_f32_e32 v227, v145, v227
	v_mul_f32_e32 v225, 0xbfb8aa3b, v225
	v_exp_f32_e32 v3, v3
	v_mul_f32_e32 v227, 0xbfb8aa3b, v227
	v_add_f32_e32 v207, v147, v207
	v_exp_f32_e32 v228, v225
	v_add_f32_e32 v225, v132, v234
	v_exp_f32_e32 v227, v227
	v_and_b32_e32 v232, 0xffff0000, v210
	v_mul_f32_e32 v207, 0xbfb8aa3b, v207
	v_add_f32_e32 v205, 1.0, v205
	v_mul_f32_e32 v225, 0xbfb8aa3b, v225
	v_rcp_f32_e32 v210, v205
	v_exp_f32_e32 v205, v207
	v_add_f32_e32 v207, v131, v232
	v_exp_f32_e32 v232, v225
	v_add_f32_e32 v225, v149, v231
	v_add_f32_e32 v3, 1.0, v3
	v_mul_f32_e32 v225, 0xbfb8aa3b, v225
	v_exp_f32_e32 v229, v225
	v_rcp_f32_e32 v234, v3
	v_add_f32_e32 v3, 1.0, v227
	v_rcp_f32_e32 v231, v3
	v_pk_add_f32 v[228:229], v[228:229], 1.0 op_sel_hi:[1,0]
	v_pk_add_f32 v[204:205], v[204:205], 1.0 op_sel_hi:[1,0]
	v_add_f32_e32 v3, v133, v235
	v_pk_mul_f32 v[204:205], v[204:205], v[208:209]
	v_pk_mul_f32 v[208:209], v[228:229], v[230:231]
	v_mul_f32_e32 v3, 0xbfb8aa3b, v3
	v_pk_mul_f32 v[140:141], v[140:141], v[208:209]
	v_add_f32_e32 v208, v129, v233
	v_mul_f32_e32 v208, 0xbfb8aa3b, v208
	v_exp_f32_e32 v208, v208
	v_exp_f32_e32 v233, v3
	v_mul_f32_e32 v207, 0xbfb8aa3b, v207
	v_exp_f32_e32 v207, v207
	v_add_f32_e32 v3, 1.0, v208
	v_rcp_f32_e32 v235, v3
	v_lshlrev_b32_e32 v3, 16, v212
	v_add_f32_e32 v3, v142, v3
	v_mul_f32_e32 v3, 0xbfb8aa3b, v3
	v_exp_f32_e32 v3, v3
	v_pk_add_f32 v[206:207], v[206:207], 1.0 op_sel_hi:[1,0]
	v_pk_mul_f32 v[138:139], v[138:139], v[204:205]
	v_pk_mul_f32 v[206:207], v[206:207], v[210:211]
	v_add_f32_e32 v3, 1.0, v3
	v_pk_mul_f32 v[134:135], v[134:135], v[206:207]
	v_lshlrev_b32_e32 v207, 16, v214
	v_rcp_f32_e32 v206, v3
	v_add_f32_e32 v3, v126, v207
	v_mul_f32_e32 v3, 0xbfb8aa3b, v3
	v_exp_f32_e32 v3, v3
	v_pk_add_f32 v[204:205], v[232:233], 1.0 op_sel_hi:[1,0]
	v_lshlrev_b32_e32 v208, 16, v218
	v_pk_mul_f32 v[204:205], v[204:205], v[234:235]
	v_add_f32_e32 v3, 1.0, v3
	v_pk_mul_f32 v[136:137], v[136:137], v[204:205]
	v_and_b32_e32 v205, 0xffff0000, v212
	v_rcp_f32_e32 v210, v3
	v_add_f32_e32 v3, v143, v205
	v_mul_f32_e32 v3, 0xbfb8aa3b, v3
	v_exp_f32_e32 v3, v3
	v_add_f32_e32 v207, v130, v208
	v_and_b32_e32 v209, 0xffff0000, v214
	v_mul_f32_e32 v207, 0xbfb8aa3b, v207
	v_add_f32_e32 v3, 1.0, v3
	v_exp_f32_e32 v208, v207
	v_rcp_f32_e32 v207, v3
	v_add_f32_e32 v3, v127, v209
	v_mul_f32_e32 v3, 0xbfb8aa3b, v3
	v_exp_f32_e32 v3, v3
	v_lshlrev_b32_e32 v212, 16, v213
	v_and_b32_e32 v211, 0xffff0000, v216
	v_add_f32_e32 v205, v147, v211
	v_add_f32_e32 v3, 1.0, v3
	v_rcp_f32_e32 v211, v3
	v_add_f32_e32 v3, v144, v212
	v_mul_f32_e32 v3, 0xbfb8aa3b, v3
	v_exp_f32_e32 v3, v3
	v_lshlrev_b32_e32 v225, 16, v215
	v_lshlrev_b32_e32 v214, 16, v217
	v_and_b32_e32 v213, 0xffff0000, v213
	v_add_f32_e32 v3, 1.0, v3
	v_add_f32_e32 v212, v148, v214
	v_rcp_f32_e32 v214, v3
	v_add_f32_e32 v3, v128, v225
	v_mul_f32_e32 v3, 0xbfb8aa3b, v3
	v_add_f32_e32 v213, v145, v213
	v_and_b32_e32 v227, 0xffff0000, v215
	v_lshlrev_b32_e32 v204, 16, v216
	v_and_b32_e32 v215, 0xffff0000, v217
	v_and_b32_e32 v216, 0xffff0000, v218
	v_lshlrev_b32_e32 v217, 16, v219
	v_exp_f32_e32 v3, v3
	v_mul_f32_e32 v213, 0xbfb8aa3b, v213
	v_add_f32_e32 v209, v131, v216
	v_add_f32_e32 v216, v132, v217
	v_exp_f32_e32 v217, v213
	v_add_f32_e32 v204, v146, v204
	v_add_f32_e32 v215, v149, v215
	v_mul_f32_e32 v204, 0xbfb8aa3b, v204
	v_mul_f32_e32 v205, 0xbfb8aa3b, v205
	v_mul_f32_e32 v212, 0xbfb8aa3b, v212
	v_add_f32_e32 v3, 1.0, v3
	v_mul_f32_e32 v213, 0xbfb8aa3b, v215
	v_exp_f32_e32 v204, v204
	v_exp_f32_e32 v205, v205
	v_exp_f32_e32 v212, v212
	v_exp_f32_e32 v213, v213
	v_rcp_f32_e32 v218, v3
	v_add_f32_e32 v3, 1.0, v217
	v_rcp_f32_e32 v215, v3
	v_pk_add_f32 v[212:213], v[212:213], 1.0 op_sel_hi:[1,0]
	v_pk_add_f32 v[204:205], v[204:205], 1.0 op_sel_hi:[1,0]
	v_and_b32_e32 v219, 0xffff0000, v219
	v_pk_mul_f32 v[204:205], v[204:205], v[206:207]
	v_pk_mul_f32 v[206:207], v[212:213], v[214:215]
	v_add_f32_e32 v3, v133, v219
	v_pk_mul_f32 v[124:125], v[124:125], v[206:207]
	v_add_f32_e32 v206, v129, v227
	v_mul_f32_e32 v206, 0xbfb8aa3b, v206
	v_exp_f32_e32 v206, v206
	v_mul_f32_e32 v3, 0xbfb8aa3b, v3
	v_exp_f32_e32 v217, v3
; __device__ __forceinline__ void unpack8(const u32x4 w, float (&v)[8]) { v[0] = bf_lo(w.x); v[1] = bf_hi(w.x); v[2] = bf_lo(w.y); v[3] = bf_hi(w.y); v[4] = bf_lo(w.z); v[5] = bf_hi(w.z); v[6] = bf_lo(w.w); v[7] = bf_hi(w.w); }
;     __device__ __forceinline__ void after(int te, f32x4 (&acc)[2][2][4][2], const Unit& u, int wr, int wc, int fr, int fq) const {
;     ...
;                     for (int m = 0; m < 4; ++m) { const size_t r = (size_t)(row0 + ai * HALF + m * 16); gs[m] = *(const u32x4*)(proj + r * LDP + PGS + c); ga[m] = *(const u32x4*)(proj + r * LDP + PGA + c); }
;     ...
;                     for (int m = 0; m < 4; ++m) { float vs[8], va[8]; unpack8(gs[m], vs); unpack8(ga[m], va);
; #pragma unroll
;                         for (int e = 0; e < 4; ++e) {
;                             acc[ai][bj][m][0][e] *= (1.f + __expf(-(va[e] + a0[e]))) * __builtin_amdgcn_rcpf(1.f + __expf(-(vs[e] + s0[e])));
;                             acc[ai][bj][m][1][e] *= (1.f + __expf(-(va[4 + e] + a1[e]))) * __builtin_amdgcn_rcpf(1.f + __expf(-(vs[4 + e] + s1[e]))); } }
	v_mul_f32_e32 v216, 0xbfb8aa3b, v216
	v_add_f32_e32 v3, 1.0, v206
	v_rcp_f32_e32 v219, v3
	v_lshlrev_b32_e32 v3, 16, v162
	v_mul_f32_e32 v209, 0xbfb8aa3b, v209
	v_exp_f32_e32 v216, v216
	v_add_f32_e32 v3, v142, v3
	v_exp_f32_e32 v209, v209
	v_mul_f32_e32 v3, 0xbfb8aa3b, v3
	v_exp_f32_e32 v3, v3
	v_pk_mul_f32 v[122:123], v[122:123], v[204:205]
	v_pk_add_f32 v[204:205], v[216:217], 1.0 op_sel_hi:[1,0]
	v_pk_add_f32 v[206:207], v[208:209], 1.0 op_sel_hi:[1,0]
	v_pk_mul_f32 v[204:205], v[204:205], v[218:219]
	v_pk_mul_f32 v[206:207], v[206:207], v[210:211]
	v_pk_mul_f32 v[120:121], v[120:121], v[204:205]
	v_and_b32_e32 v204, 0xffff0000, v162
	v_lshlrev_b32_e32 v162, 16, v164
	v_add_f32_e32 v3, 1.0, v3
	v_pk_mul_f32 v[118:119], v[118:119], v[206:207]
	v_lshlrev_b32_e32 v206, 16, v159
	v_and_b32_e32 v210, 0xffff0000, v159
	v_lshlrev_b32_e32 v159, 16, v160
	v_and_b32_e32 v211, 0xffff0000, v160
	v_rcp_f32_e32 v160, v3
	v_add_f32_e32 v3, v126, v162
	v_mul_f32_e32 v3, 0xbfb8aa3b, v3
	v_exp_f32_e32 v3, v3
	v_lshlrev_b32_e32 v205, 16, v163
	v_and_b32_e32 v207, 0xffff0000, v163
	v_and_b32_e32 v163, 0xffff0000, v164
	v_lshlrev_b32_e32 v164, 16, v158
	v_add_f32_e32 v3, 1.0, v3
	v_lshlrev_b32_e32 v208, 16, v165
	v_and_b32_e32 v209, 0xffff0000, v165
	v_and_b32_e32 v165, 0xffff0000, v158
	v_add_f32_e32 v158, v146, v164
	v_rcp_f32_e32 v164, v3
	v_add_f32_e32 v3, v143, v204
	v_mul_f32_e32 v3, 0xbfb8aa3b, v3
	v_exp_f32_e32 v3, v3
	v_lshlrev_b32_e32 v212, 16, v161
	v_and_b32_e32 v213, 0xffff0000, v161
	v_add_f32_e32 v159, v130, v159
	v_add_f32_e32 v3, 1.0, v3
	v_rcp_f32_e32 v161, v3
	v_add_f32_e32 v3, v127, v163
	v_mul_f32_e32 v3, 0xbfb8aa3b, v3
	v_exp_f32_e32 v3, v3
	v_mul_f32_e32 v159, 0xbfb8aa3b, v159
	v_exp_f32_e32 v162, v159
	v_add_f32_e32 v159, v147, v165
	v_add_f32_e32 v3, 1.0, v3
	v_rcp_f32_e32 v165, v3
	v_add_f32_e32 v3, v144, v205
	v_mul_f32_e32 v3, 0xbfb8aa3b, v3
	v_exp_f32_e32 v3, v3
	v_add_f32_e32 v204, v148, v206
	v_add_f32_e32 v207, v145, v207
	v_mul_f32_e32 v207, 0xbfb8aa3b, v207
	v_add_f32_e32 v3, 1.0, v3
	v_rcp_f32_e32 v206, v3
	v_add_f32_e32 v3, v128, v208
	v_mul_f32_e32 v3, 0xbfb8aa3b, v3
	v_exp_f32_e32 v3, v3
	v_add_f32_e32 v205, v132, v212
	v_exp_f32_e32 v207, v207
	v_mul_f32_e32 v205, 0xbfb8aa3b, v205
	v_exp_f32_e32 v208, v205
	v_add_f32_e32 v205, v149, v210
	v_mul_f32_e32 v158, 0xbfb8aa3b, v158
	v_mul_f32_e32 v159, 0xbfb8aa3b, v159
	v_mul_f32_e32 v204, 0xbfb8aa3b, v204
	v_add_f32_e32 v3, 1.0, v3
	v_mul_f32_e32 v205, 0xbfb8aa3b, v205
	v_exp_f32_e32 v158, v158
	v_exp_f32_e32 v159, v159
	v_exp_f32_e32 v204, v204
	v_exp_f32_e32 v205, v205
	v_rcp_f32_e32 v210, v3
	v_add_f32_e32 v3, 1.0, v207
	v_rcp_f32_e32 v207, v3
	v_pk_add_f32 v[204:205], v[204:205], 1.0 op_sel_hi:[1,0]
	v_pk_add_f32 v[158:159], v[158:159], 1.0 op_sel_hi:[1,0]
	v_add_f32_e32 v3, v133, v213
	v_pk_mul_f32 v[158:159], v[158:159], v[160:161]
	v_pk_mul_f32 v[160:161], v[204:205], v[206:207]
	v_mul_f32_e32 v3, 0xbfb8aa3b, v3
	v_pk_mul_f32 v[116:117], v[116:117], v[160:161]
	v_add_f32_e32 v160, v129, v209
	v_mul_f32_e32 v160, 0xbfb8aa3b, v160
	v_exp_f32_e32 v160, v160
	v_exp_f32_e32 v209, v3
	v_add_f32_e32 v163, v131, v211
	v_mul_f32_e32 v163, 0xbfb8aa3b, v163
	v_add_f32_e32 v3, 1.0, v160
	v_rcp_f32_e32 v211, v3
	v_lshlrev_b32_e32 v3, 16, v154
	v_add_f32_e32 v3, v142, v3
	v_exp_f32_e32 v163, v163
	v_mul_f32_e32 v3, 0xbfb8aa3b, v3
	v_exp_f32_e32 v3, v3
	v_pk_mul_f32 v[114:115], v[114:115], v[158:159]
	v_pk_add_f32 v[158:159], v[208:209], 1.0 op_sel_hi:[1,0]
	v_pk_add_f32 v[160:161], v[162:163], 1.0 op_sel_hi:[1,0]
	v_pk_mul_f32 v[158:159], v[158:159], v[210:211]
	v_pk_mul_f32 v[160:161], v[160:161], v[164:165]
	v_pk_mul_f32 v[112:113], v[112:113], v[158:159]
	v_and_b32_e32 v158, 0xffff0000, v154
	v_lshlrev_b32_e32 v154, 16, v156
	v_add_f32_e32 v3, 1.0, v3
	v_pk_mul_f32 v[110:111], v[110:111], v[160:161]
	v_lshlrev_b32_e32 v160, 16, v151
	v_and_b32_e32 v204, 0xffff0000, v151
	v_lshlrev_b32_e32 v151, 16, v152
	v_and_b32_e32 v162, 0xffff0000, v152
	v_rcp_f32_e32 v152, v3
	v_add_f32_e32 v3, v126, v154
	v_mul_f32_e32 v3, 0xbfb8aa3b, v3
	v_exp_f32_e32 v3, v3
	v_lshlrev_b32_e32 v159, 16, v155
	v_and_b32_e32 v161, 0xffff0000, v155
	v_and_b32_e32 v155, 0xffff0000, v156
	v_lshlrev_b32_e32 v156, 16, v150
	v_add_f32_e32 v3, 1.0, v3
	v_lshlrev_b32_e32 v164, 16, v157
	v_and_b32_e32 v165, 0xffff0000, v157
	v_and_b32_e32 v157, 0xffff0000, v150
	v_add_f32_e32 v150, v146, v156
	v_rcp_f32_e32 v156, v3
	v_add_f32_e32 v3, v143, v158
	v_mul_f32_e32 v3, 0xbfb8aa3b, v3
	v_exp_f32_e32 v3, v3
	v_lshlrev_b32_e32 v205, 16, v153
	v_and_b32_e32 v206, 0xffff0000, v153
	v_add_f32_e32 v151, v130, v151
	v_add_f32_e32 v3, 1.0, v3
	v_rcp_f32_e32 v153, v3
	v_add_f32_e32 v3, v127, v155
	v_add_f32_e32 v155, v131, v162
	v_add_co_u32_e32 v162, vcc, s26, v192
	v_mul_f32_e32 v3, 0xbfb8aa3b, v3
	s_nop 0
	v_addc_co_u32_e32 v163, vcc, 0, v193, vcc
	global_load_dwordx4 v[228:231], v[162:163], off
	v_exp_f32_e32 v3, v3
	v_mul_f32_e32 v151, 0xbfb8aa3b, v151
	s_mov_b32 s26, 0x202000
	v_exp_f32_e32 v154, v151
	v_add_f32_e32 v3, 1.0, v3
	v_add_f32_e32 v151, v147, v157
	v_rcp_f32_e32 v157, v3
	v_add_f32_e32 v3, v144, v159
	v_add_co_u32_e32 v162, vcc, s26, v192
	v_mul_f32_e32 v3, 0xbfb8aa3b, v3
	s_nop 0
	v_addc_co_u32_e32 v163, vcc, 0, v193, vcc
	v_exp_f32_e32 v3, v3
	global_load_dwordx4 v[232:235], v[162:163], off
	v_add_f32_e32 v158, v148, v160
	v_add_f32_e32 v161, v145, v161
	v_add_f32_e32 v3, 1.0, v3
	v_rcp_f32_e32 v160, v3
	v_add_f32_e32 v3, v128, v164
	v_mul_f32_e32 v3, 0xbfb8aa3b, v3
	v_exp_f32_e32 v3, v3
	v_mul_f32_e32 v161, 0xbfb8aa3b, v161
	v_add_f32_e32 v159, v132, v205
	v_exp_f32_e32 v161, v161
	v_mul_f32_e32 v159, 0xbfb8aa3b, v159
; __device__ __forceinline__ void unpack8(const u32x4 w, float (&v)[8]) { v[0] = bf_lo(w.x); v[1] = bf_hi(w.x); v[2] = bf_lo(w.y); v[3] = bf_hi(w.y); v[4] = bf_lo(w.z); v[5] = bf_hi(w.z); v[6] = bf_lo(w.w); v[7] = bf_hi(w.w); }
;     __device__ __forceinline__ void after(int te, f32x4 (&acc)[2][2][4][2], const Unit& u, int wr, int wc, int fr, int fq) const {
;     ...
;                     for (int m = 0; m < 4; ++m) { const size_t r = (size_t)(row0 + ai * HALF + m * 16); gs[m] = *(const u32x4*)(proj + r * LDP + PGS + c); ga[m] = *(const u32x4*)(proj + r * LDP + PGA + c); }
;     ...
;                     for (int m = 0; m < 4; ++m) { float vs[8], va[8]; unpack8(gs[m], vs); unpack8(ga[m], va);
; #pragma unroll
;                         for (int e = 0; e < 4; ++e) {
;                             acc[ai][bj][m][0][e] *= (1.f + __expf(-(va[e] + a0[e]))) * __builtin_amdgcn_rcpf(1.f + __expf(-(vs[e] + s0[e])));
;                             acc[ai][bj][m][1][e] *= (1.f + __expf(-(va[4 + e] + a1[e]))) * __builtin_amdgcn_rcpf(1.f + __expf(-(vs[4 + e] + s1[e]))); } }
	v_exp_f32_e32 v162, v159
	v_add_f32_e32 v159, v149, v204
	v_mul_f32_e32 v150, 0xbfb8aa3b, v150
	v_mul_f32_e32 v151, 0xbfb8aa3b, v151
	v_mul_f32_e32 v158, 0xbfb8aa3b, v158
	v_add_f32_e32 v3, 1.0, v3
	v_mul_f32_e32 v159, 0xbfb8aa3b, v159
	v_exp_f32_e32 v150, v150
	v_exp_f32_e32 v151, v151
	v_exp_f32_e32 v158, v158
	v_exp_f32_e32 v159, v159
	v_rcp_f32_e32 v164, v3
	v_add_f32_e32 v3, 1.0, v161
	v_rcp_f32_e32 v161, v3
	v_pk_add_f32 v[158:159], v[158:159], 1.0 op_sel_hi:[1,0]
	v_pk_add_f32 v[150:151], v[150:151], 1.0 op_sel_hi:[1,0]
	v_add_f32_e32 v3, v133, v206
	v_pk_mul_f32 v[150:151], v[150:151], v[152:153]
	v_pk_mul_f32 v[152:153], v[158:159], v[160:161]
	v_mul_f32_e32 v3, 0xbfb8aa3b, v3
	v_pk_mul_f32 v[108:109], v[108:109], v[152:153]
	v_add_f32_e32 v152, v129, v165
	v_mul_f32_e32 v152, 0xbfb8aa3b, v152
	v_exp_f32_e32 v152, v152
	v_exp_f32_e32 v163, v3
	v_mul_f32_e32 v155, 0xbfb8aa3b, v155
	v_exp_f32_e32 v155, v155
	v_add_f32_e32 v3, 1.0, v152
	v_rcp_f32_e32 v165, v3
	s_mov_b64 s[26:27], 0x200000
	v_lshl_add_u64 v[218:219], v[192:193], 0, s[26:27]
	s_mov_b64 s[26:27], 0x202000
	v_pk_mul_f32 v[106:107], v[106:107], v[150:151]
	v_pk_add_f32 v[150:151], v[162:163], 1.0 op_sel_hi:[1,0]
	v_lshl_add_u64 v[216:217], v[192:193], 0, s[26:27]
	s_mov_b64 s[26:27], 0x240000
	v_pk_mul_f32 v[150:151], v[150:151], v[164:165]
	v_lshl_add_u64 v[204:205], v[192:193], 0, s[26:27]
	s_mov_b32 s26, 0x240000
	v_pk_add_f32 v[152:153], v[154:155], 1.0 op_sel_hi:[1,0]
	v_pk_mul_f32 v[104:105], v[104:105], v[150:151]
	v_add_co_u32_e32 v150, vcc, s26, v192
	s_mov_b64 s[26:27], 0x242000
	v_pk_mul_f32 v[152:153], v[152:153], v[156:157]
	v_addc_co_u32_e32 v151, vcc, 0, v193, vcc
	v_lshl_add_u64 v[206:207], v[192:193], 0, s[26:27]
	s_mov_b32 s26, 0x242000
	v_pk_mul_f32 v[102:103], v[102:103], v[152:153]
	v_add_co_u32_e32 v152, vcc, s26, v192
	s_mov_b64 s[26:27], 0x280000
	s_nop 0
	v_addc_co_u32_e32 v153, vcc, 0, v193, vcc
	global_load_dwordx4 v[236:239], v[150:151], off
	global_load_dwordx4 v[240:243], v[152:153], off
	s_waitcnt vmcnt(3)
	v_lshlrev_b32_e32 v3, 16, v228
	v_add_f32_e32 v3, v142, v3
	v_mul_f32_e32 v3, 0xbfb8aa3b, v3
	v_exp_f32_e32 v3, v3
	v_lshlrev_b32_e32 v227, 16, v229
	v_and_b32_e32 v245, 0xffff0000, v229
	v_lshlrev_b32_e32 v229, 16, v230
	v_add_f32_e32 v3, 1.0, v3
	v_and_b32_e32 v246, 0xffff0000, v230
	v_rcp_f32_e32 v230, v3
	v_add_f32_e32 v3, v126, v229
	v_mul_f32_e32 v3, 0xbfb8aa3b, v3
	v_exp_f32_e32 v3, v3
	v_lshl_add_u64 v[208:209], v[192:193], 0, s[26:27]
	s_mov_b32 s26, 0x280000
	v_add_co_u32_e32 v150, vcc, s26, v192
	s_mov_b64 s[26:27], 0x282000
	s_nop 0
	v_addc_co_u32_e32 v151, vcc, 0, v193, vcc
	v_lshl_add_u64 v[210:211], v[192:193], 0, s[26:27]
	s_mov_b32 s26, 0x282000
	v_add_co_u32_e32 v152, vcc, s26, v192
	v_and_b32_e32 v225, 0xffff0000, v228
	v_add_f32_e32 v3, 1.0, v3
	v_addc_co_u32_e32 v153, vcc, 0, v193, vcc
	global_load_dwordx4 v[162:165], v[150:151], off
	global_load_dwordx4 v[158:161], v[152:153], off
	v_lshlrev_b32_e32 v247, 16, v231
	v_and_b32_e32 v251, 0xffff0000, v231
	s_waitcnt vmcnt(4)
	v_lshlrev_b32_e32 v228, 16, v232
	v_and_b32_e32 v231, 0xffff0000, v232
	v_lshlrev_b32_e32 v248, 16, v233
	v_and_b32_e32 v249, 0xffff0000, v233
	v_lshlrev_b32_e32 v232, 16, v234
	v_and_b32_e32 v233, 0xffff0000, v234
	v_rcp_f32_e32 v234, v3
	v_add_f32_e32 v3, v143, v225
	v_mul_f32_e32 v3, 0xbfb8aa3b, v3
	v_exp_f32_e32 v3, v3
	v_add_f32_e32 v225, v147, v231
	v_lshlrev_b32_e32 v250, 16, v235
	v_and_b32_e32 v253, 0xffff0000, v235
	v_add_f32_e32 v3, 1.0, v3
	v_rcp_f32_e32 v231, v3
	v_add_f32_e32 v3, v127, v246
	v_mul_f32_e32 v3, 0xbfb8aa3b, v3
	v_exp_f32_e32 v3, v3
	v_add_f32_e32 v229, v130, v232
	v_mul_f32_e32 v229, 0xbfb8aa3b, v229
	v_mul_f32_e32 v225, 0xbfb8aa3b, v225
	v_add_f32_e32 v3, 1.0, v3
	v_rcp_f32_e32 v235, v3
	v_add_f32_e32 v3, v144, v227
	v_mul_f32_e32 v3, 0xbfb8aa3b, v3
	v_exp_f32_e32 v3, v3
	v_exp_f32_e32 v232, v229
	v_exp_f32_e32 v229, v225
	v_add_f32_e32 v225, v131, v233
	v_mul_f32_e32 v225, 0xbfb8aa3b, v225
	v_exp_f32_e32 v233, v225
	v_add_f32_e32 v225, v148, v248
	v_mul_f32_e32 v225, 0xbfb8aa3b, v225
	v_add_f32_e32 v3, 1.0, v3
	v_exp_f32_e32 v246, v225
	v_rcp_f32_e32 v248, v3
	v_add_f32_e32 v3, v128, v247
	v_add_f32_e32 v225, v132, v250
	v_mul_f32_e32 v3, 0xbfb8aa3b, v3
	v_mul_f32_e32 v225, 0xbfb8aa3b, v225
	v_add_f32_e32 v227, v145, v245
	v_exp_f32_e32 v3, v3
	v_exp_f32_e32 v250, v225
	v_add_f32_e32 v225, v149, v249
	v_mul_f32_e32 v227, 0xbfb8aa3b, v227
	v_exp_f32_e32 v227, v227
	v_mul_f32_e32 v225, 0xbfb8aa3b, v225
	v_exp_f32_e32 v247, v225
	v_add_f32_e32 v225, v129, v251
	v_mul_f32_e32 v225, 0xbfb8aa3b, v225
	v_add_f32_e32 v3, 1.0, v3
	v_exp_f32_e32 v225, v225
	v_rcp_f32_e32 v252, v3
	v_add_f32_e32 v3, 1.0, v227
	v_add_f32_e32 v228, v146, v228
	v_rcp_f32_e32 v249, v3
	v_add_f32_e32 v3, v133, v253
	v_mul_f32_e32 v228, 0xbfb8aa3b, v228
	v_mul_f32_e32 v3, 0xbfb8aa3b, v3
	v_exp_f32_e32 v228, v228
	v_exp_f32_e32 v251, v3
	v_add_f32_e32 v3, 1.0, v225
	v_rcp_f32_e32 v253, v3
	s_waitcnt vmcnt(3)
; __device__ __forceinline__ void unpack8(const u32x4 w, float (&v)[8]) { v[0] = bf_lo(w.x); v[1] = bf_hi(w.x); v[2] = bf_lo(w.y); v[3] = bf_hi(w.y); v[4] = bf_lo(w.z); v[5] = bf_hi(w.z); v[6] = bf_lo(w.w); v[7] = bf_hi(w.w); }
;     __device__ __forceinline__ void after(int te, f32x4 (&acc)[2][2][4][2], const Unit& u, int wr, int wc, int fr, int fq) const {
;     ...
;                     for (int m = 0; m < 4; ++m) { const size_t r = (size_t)(row0 + ai * HALF + m * 16); gs[m] = *(const u32x4*)(proj + r * LDP + PGS + c); ga[m] = *(const u32x4*)(proj + r * LDP + PGA + c); }
;     ...
;                     for (int m = 0; m < 4; ++m) { float vs[8], va[8]; unpack8(gs[m], vs); unpack8(ga[m], va);
; #pragma unroll
;                         for (int e = 0; e < 4; ++e) {
;                             acc[ai][bj][m][0][e] *= (1.f + __expf(-(va[e] + a0[e]))) * __builtin_amdgcn_rcpf(1.f + __expf(-(vs[e] + s0[e])));
;                             acc[ai][bj][m][1][e] *= (1.f + __expf(-(va[4 + e] + a1[e]))) * __builtin_amdgcn_rcpf(1.f + __expf(-(vs[4 + e] + s1[e]))); } }
	v_lshlrev_b32_e32 v3, 16, v236
	v_add_f32_e32 v3, v142, v3
	v_mul_f32_e32 v3, 0xbfb8aa3b, v3
	v_pk_add_f32 v[228:229], v[228:229], 1.0 op_sel_hi:[1,0]
	v_exp_f32_e32 v3, v3
	v_pk_add_f32 v[246:247], v[246:247], 1.0 op_sel_hi:[1,0]
	v_pk_mul_f32 v[228:229], v[228:229], v[230:231]
	v_pk_mul_f32 v[230:231], v[246:247], v[248:249]
	v_pk_mul_f32 v[98:99], v[98:99], v[228:229]
	v_pk_add_f32 v[228:229], v[250:251], 1.0 op_sel_hi:[1,0]
	v_pk_mul_f32 v[100:101], v[100:101], v[230:231]
	v_pk_add_f32 v[230:231], v[232:233], 1.0 op_sel_hi:[1,0]
	v_pk_mul_f32 v[228:229], v[228:229], v[252:253]
	v_pk_mul_f32 v[230:231], v[230:231], v[234:235]
	v_pk_mul_f32 v[96:97], v[96:97], v[228:229]
	v_lshlrev_b32_e32 v229, 16, v238
	v_add_f32_e32 v3, 1.0, v3
	v_pk_mul_f32 v[94:95], v[94:95], v[230:231]
	v_rcp_f32_e32 v230, v3
	v_add_f32_e32 v3, v126, v229
	v_mul_f32_e32 v3, 0xbfb8aa3b, v3
	v_exp_f32_e32 v3, v3
	v_and_b32_e32 v225, 0xffff0000, v236
	s_mov_b64 s[26:27], 0x2c0000
	v_lshl_add_u64 v[212:213], v[192:193], 0, s[26:27]
	v_add_f32_e32 v3, 1.0, v3
	v_rcp_f32_e32 v234, v3
	v_add_f32_e32 v3, v143, v225
	v_mul_f32_e32 v3, 0xbfb8aa3b, v3
	v_exp_f32_e32 v3, v3
	s_mov_b32 s26, 0x2c0000
	v_add_co_u32_e32 v150, vcc, s26, v192
	s_mov_b64 s[26:27], 0x2c2000
	s_nop 0
	v_addc_co_u32_e32 v151, vcc, 0, v193, vcc
	v_lshl_add_u64 v[214:215], v[192:193], 0, s[26:27]
	s_mov_b32 s26, 0x2c2000
	v_and_b32_e32 v233, 0xffff0000, v238
	s_waitcnt vmcnt(2)
	v_and_b32_e32 v231, 0xffff0000, v240
	v_add_f32_e32 v3, 1.0, v3
	v_add_co_u32_e32 v152, vcc, s26, v192
	v_add_f32_e32 v225, v147, v231
	v_rcp_f32_e32 v231, v3
	v_add_f32_e32 v3, v127, v233
	v_addc_co_u32_e32 v153, vcc, 0, v193, vcc
	v_mul_f32_e32 v3, 0xbfb8aa3b, v3
	global_load_dwordx4 v[154:157], v[150:151], off
	s_nop 0
	global_load_dwordx4 v[150:153], v[152:153], off
	v_exp_f32_e32 v3, v3
	v_lshlrev_b32_e32 v232, 16, v242
	v_add_f32_e32 v229, v130, v232
	v_lshlrev_b32_e32 v227, 16, v237
	v_and_b32_e32 v235, 0xffff0000, v242
	v_mul_f32_e32 v229, 0xbfb8aa3b, v229
	v_mul_f32_e32 v225, 0xbfb8aa3b, v225
	v_add_f32_e32 v3, 1.0, v3
	v_exp_f32_e32 v232, v229
	v_exp_f32_e32 v229, v225
	v_add_f32_e32 v225, v131, v235
	v_rcp_f32_e32 v235, v3
	v_add_f32_e32 v3, v144, v227
	v_mul_f32_e32 v3, 0xbfb8aa3b, v3
	v_exp_f32_e32 v3, v3
	v_lshlrev_b32_e32 v236, 16, v241
	v_mul_f32_e32 v225, 0xbfb8aa3b, v225
	v_exp_f32_e32 v233, v225
	v_add_f32_e32 v225, v148, v236
	v_lshlrev_b32_e32 v245, 16, v239
	v_lshlrev_b32_e32 v228, 16, v240
	v_lshlrev_b32_e32 v240, 16, v243
	v_mul_f32_e32 v225, 0xbfb8aa3b, v225
	v_add_f32_e32 v3, 1.0, v3
	v_and_b32_e32 v237, 0xffff0000, v237
	v_exp_f32_e32 v236, v225
	v_rcp_f32_e32 v238, v3
	v_add_f32_e32 v3, v128, v245
	v_add_f32_e32 v225, v132, v240
	v_and_b32_e32 v246, 0xffff0000, v239
	v_and_b32_e32 v239, 0xffff0000, v241
	v_mul_f32_e32 v3, 0xbfb8aa3b, v3
	v_mul_f32_e32 v225, 0xbfb8aa3b, v225
	v_add_f32_e32 v227, v145, v237
	v_exp_f32_e32 v3, v3
	v_exp_f32_e32 v240, v225
	v_add_f32_e32 v225, v149, v239
	v_mul_f32_e32 v227, 0xbfb8aa3b, v227
	v_exp_f32_e32 v227, v227
	v_mul_f32_e32 v225, 0xbfb8aa3b, v225
	v_exp_f32_e32 v237, v225
	v_add_f32_e32 v225, v129, v246
	v_mul_f32_e32 v225, 0xbfb8aa3b, v225
	v_add_f32_e32 v3, 1.0, v3
	v_exp_f32_e32 v225, v225
	v_and_b32_e32 v241, 0xffff0000, v243
	v_rcp_f32_e32 v242, v3
	v_add_f32_e32 v3, 1.0, v227
	v_rcp_f32_e32 v239, v3
	v_add_f32_e32 v3, v133, v241
	v_add_f32_e32 v228, v146, v228
	v_mul_f32_e32 v3, 0xbfb8aa3b, v3
	v_mul_f32_e32 v228, 0xbfb8aa3b, v228
	v_exp_f32_e32 v241, v3
	v_add_f32_e32 v3, 1.0, v225
	v_exp_f32_e32 v228, v228
	v_rcp_f32_e32 v243, v3
	s_waitcnt vmcnt(3)
	v_lshlrev_b32_e32 v3, 16, v162
	v_add_f32_e32 v3, v142, v3
	v_mul_f32_e32 v3, 0xbfb8aa3b, v3
	v_exp_f32_e32 v3, v3
	v_pk_add_f32 v[236:237], v[236:237], 1.0 op_sel_hi:[1,0]
	v_pk_add_f32 v[228:229], v[228:229], 1.0 op_sel_hi:[1,0]
	v_and_b32_e32 v225, 0xffff0000, v162
	v_pk_mul_f32 v[228:229], v[228:229], v[230:231]
	v_pk_mul_f32 v[230:231], v[236:237], v[238:239]
	v_pk_mul_f32 v[90:91], v[90:91], v[228:229]
	v_pk_mul_f32 v[92:93], v[92:93], v[230:231]
	v_pk_add_f32 v[228:229], v[240:241], 1.0 op_sel_hi:[1,0]
	v_pk_add_f32 v[230:231], v[232:233], 1.0 op_sel_hi:[1,0]
	v_pk_mul_f32 v[228:229], v[228:229], v[242:243]
	v_pk_mul_f32 v[230:231], v[230:231], v[234:235]
	v_lshlrev_b32_e32 v162, 16, v164
	v_add_f32_e32 v3, 1.0, v3
	v_pk_mul_f32 v[88:89], v[88:89], v[228:229]
	v_pk_mul_f32 v[86:87], v[86:87], v[230:231]
	s_waitcnt vmcnt(2)
; __device__ __forceinline__ void unpack8(const u32x4 w, float (&v)[8]) { v[0] = bf_lo(w.x); v[1] = bf_hi(w.x); v[2] = bf_lo(w.y); v[3] = bf_hi(w.y); v[4] = bf_lo(w.z); v[5] = bf_hi(w.z); v[6] = bf_lo(w.w); v[7] = bf_hi(w.w); }
;     __device__ __forceinline__ void after(int te, f32x4 (&acc)[2][2][4][2], const Unit& u, int wr, int wc, int fr, int fq) const {
;     ...
;                 const f32x4 s0 = *(const f32x4*)(gb + c), s1 = *(const f32x4*)(gb + c + 4), a0 = *(const f32x4*)(gb + D_MODEL + c), a1 = *(const f32x4*)(gb + D_MODEL + c + 4);
; #pragma unroll
;                 for (int ai = 0; ai < 2; ++ai) {
;                     u32x4 gs[4], ga[4];
; #pragma unroll
;                     for (int m = 0; m < 4; ++m) { const size_t r = (size_t)(row0 + ai * HALF + m * 16); gs[m] = *(const u32x4*)(proj + r * LDP + PGS + c); ga[m] = *(const u32x4*)(proj + r * LDP + PGA + c); }
;     ...
;                     for (int m = 0; m < 4; ++m) { float vs[8], va[8]; unpack8(gs[m], vs); unpack8(ga[m], va);
; #pragma unroll
;                         for (int e = 0; e < 4; ++e) {
;                             acc[ai][bj][m][0][e] *= (1.f + __expf(-(va[e] + a0[e]))) * __builtin_amdgcn_rcpf(1.f + __expf(-(vs[e] + s0[e])));
;                             acc[ai][bj][m][1][e] *= (1.f + __expf(-(va[4 + e] + a1[e]))) * __builtin_amdgcn_rcpf(1.f + __expf(-(vs[4 + e] + s1[e]))); } }
	v_lshlrev_b32_e32 v228, 16, v159
	v_and_b32_e32 v234, 0xffff0000, v159
	v_lshlrev_b32_e32 v159, 16, v160
	v_and_b32_e32 v230, 0xffff0000, v160
	v_rcp_f32_e32 v160, v3
	v_add_f32_e32 v3, v126, v162
	v_mul_f32_e32 v3, 0xbfb8aa3b, v3
	v_exp_f32_e32 v3, v3
	v_lshlrev_b32_e32 v227, 16, v163
	v_and_b32_e32 v229, 0xffff0000, v163
	v_and_b32_e32 v163, 0xffff0000, v164
	v_lshlrev_b32_e32 v164, 16, v158
	v_add_f32_e32 v3, 1.0, v3
	v_lshlrev_b32_e32 v231, 16, v165
	v_and_b32_e32 v233, 0xffff0000, v165
	v_and_b32_e32 v165, 0xffff0000, v158
	v_add_f32_e32 v158, v146, v164
	v_rcp_f32_e32 v164, v3
	v_add_f32_e32 v3, v143, v225
	v_mul_f32_e32 v3, 0xbfb8aa3b, v3
	v_exp_f32_e32 v3, v3
	v_lshlrev_b32_e32 v232, 16, v161
	v_and_b32_e32 v235, 0xffff0000, v161
	v_add_f32_e32 v159, v130, v159
	v_add_f32_e32 v3, 1.0, v3
	v_rcp_f32_e32 v161, v3
	v_add_f32_e32 v3, v127, v163
	v_mul_f32_e32 v3, 0xbfb8aa3b, v3
	v_exp_f32_e32 v3, v3
	v_mul_f32_e32 v159, 0xbfb8aa3b, v159
	v_exp_f32_e32 v162, v159
	v_add_f32_e32 v159, v147, v165
	v_add_f32_e32 v3, 1.0, v3
	v_rcp_f32_e32 v165, v3
	v_add_f32_e32 v3, v144, v227
	v_mul_f32_e32 v3, 0xbfb8aa3b, v3
	v_exp_f32_e32 v3, v3
	v_add_f32_e32 v163, v131, v230
	v_add_f32_e32 v225, v148, v228
	v_add_f32_e32 v227, v145, v229
	v_add_f32_e32 v3, 1.0, v3
	v_rcp_f32_e32 v230, v3
	v_add_f32_e32 v3, v128, v231
	v_mul_f32_e32 v3, 0xbfb8aa3b, v3
	v_mul_f32_e32 v225, 0xbfb8aa3b, v225
	v_exp_f32_e32 v3, v3
	v_mul_f32_e32 v227, 0xbfb8aa3b, v227
	v_exp_f32_e32 v228, v225
	v_add_f32_e32 v225, v132, v232
	v_exp_f32_e32 v227, v227
	v_mul_f32_e32 v225, 0xbfb8aa3b, v225
	v_exp_f32_e32 v232, v225
	v_add_f32_e32 v225, v149, v234
	v_mul_f32_e32 v158, 0xbfb8aa3b, v158
	v_mul_f32_e32 v159, 0xbfb8aa3b, v159
	v_add_f32_e32 v3, 1.0, v3
	v_mul_f32_e32 v225, 0xbfb8aa3b, v225
	v_exp_f32_e32 v158, v158
	v_exp_f32_e32 v159, v159
	v_exp_f32_e32 v229, v225
	v_rcp_f32_e32 v234, v3
	v_add_f32_e32 v3, 1.0, v227
	v_rcp_f32_e32 v231, v3
	v_pk_add_f32 v[228:229], v[228:229], 1.0 op_sel_hi:[1,0]
	v_pk_add_f32 v[158:159], v[158:159], 1.0 op_sel_hi:[1,0]
	v_add_f32_e32 v3, v133, v235
	v_pk_mul_f32 v[158:159], v[158:159], v[160:161]
	v_pk_mul_f32 v[160:161], v[228:229], v[230:231]
	v_mul_f32_e32 v3, 0xbfb8aa3b, v3
	v_pk_mul_f32 v[84:85], v[84:85], v[160:161]
	v_add_f32_e32 v160, v129, v233
	v_mul_f32_e32 v160, 0xbfb8aa3b, v160
	v_exp_f32_e32 v160, v160
	v_exp_f32_e32 v233, v3
	s_waitcnt vmcnt(1)
	v_lshlrev_b32_e32 v225, 16, v155
	v_and_b32_e32 v227, 0xffff0000, v155
	v_add_f32_e32 v3, 1.0, v160
	v_rcp_f32_e32 v235, v3
	v_lshlrev_b32_e32 v3, 16, v154
	v_add_f32_e32 v3, v142, v3
	v_mul_f32_e32 v3, 0xbfb8aa3b, v3
	v_exp_f32_e32 v3, v3
	v_lshlrev_b32_e32 v155, 16, v156
	v_and_b32_e32 v236, 0xffff0000, v156
	s_waitcnt vmcnt(0)
	v_lshlrev_b32_e32 v156, 16, v150
	v_add_f32_e32 v3, 1.0, v3
	v_mul_f32_e32 v163, 0xbfb8aa3b, v163
	v_add_f32_e32 v142, v146, v156
	v_rcp_f32_e32 v146, v3
	v_add_f32_e32 v3, v126, v155
	v_exp_f32_e32 v163, v163
	v_mul_f32_e32 v3, 0xbfb8aa3b, v3
	v_exp_f32_e32 v3, v3
	v_pk_mul_f32 v[82:83], v[82:83], v[158:159]
	v_pk_add_f32 v[158:159], v[232:233], 1.0 op_sel_hi:[1,0]
	v_pk_add_f32 v[160:161], v[162:163], 1.0 op_sel_hi:[1,0]
	v_pk_mul_f32 v[158:159], v[158:159], v[234:235]
	v_pk_mul_f32 v[160:161], v[160:161], v[164:165]
	v_and_b32_e32 v150, 0xffff0000, v150
	v_lshlrev_b32_e32 v239, 16, v151
	v_and_b32_e32 v240, 0xffff0000, v151
	v_lshlrev_b32_e32 v151, 16, v152
	global_load_dwordx4 v[228:231], v[192:193], off offset:256
	global_load_dwordx4 v[232:235], v[202:203], off offset:256
	v_add_f32_e32 v3, 1.0, v3
	v_pk_mul_f32 v[80:81], v[80:81], v[158:159]
	v_pk_mul_f32 v[78:79], v[78:79], v[160:161]
	v_and_b32_e32 v241, 0xffff0000, v152
	v_lshlrev_b32_e32 v242, 16, v153
	v_and_b32_e32 v243, 0xffff0000, v153
	v_add_f32_e32 v126, v130, v151
	v_rcp_f32_e32 v130, v3
	v_add_f32_e32 v3, v147, v150
	global_load_dwordx4 v[150:153], v[196:197], off offset:528
	global_load_dwordx4 v[158:161], v[196:197], off offset:512
	v_and_b32_e32 v154, 0xffff0000, v154
	v_lshlrev_b32_e32 v237, 16, v157
	v_and_b32_e32 v238, 0xffff0000, v157
	v_add_f32_e32 v143, v143, v154
	global_load_dwordx4 v[154:157], v[198:199], off offset:528
	global_load_dwordx4 v[162:165], v[198:199], off offset:512
	v_mul_f32_e32 v143, 0xbfb8aa3b, v143
	v_exp_f32_e32 v147, v143
	v_mul_f32_e32 v3, 0xbfb8aa3b, v3
	v_exp_f32_e32 v143, v3
	v_add_f32_e32 v145, v145, v227
	v_add_f32_e32 v3, 1.0, v147
	v_rcp_f32_e32 v147, v3
	v_add_f32_e32 v3, v127, v236
	v_mul_f32_e32 v3, 0xbfb8aa3b, v3
	v_exp_f32_e32 v3, v3
	v_add_f32_e32 v127, v131, v241
	v_mul_f32_e32 v145, 0xbfb8aa3b, v145
	v_add_f32_e32 v129, v129, v238
	v_add_f32_e32 v3, 1.0, v3
	v_rcp_f32_e32 v131, v3
	v_add_f32_e32 v3, v144, v225
	v_mul_f32_e32 v3, 0xbfb8aa3b, v3
	v_exp_f32_e32 v3, v3
	v_add_f32_e32 v144, v148, v239
	v_mul_f32_e32 v129, 0xbfb8aa3b, v129
	v_mul_f32_e32 v142, 0xbfb8aa3b, v142
	v_add_f32_e32 v3, 1.0, v3
	v_rcp_f32_e32 v148, v3
	v_add_f32_e32 v3, v128, v237
	v_mul_f32_e32 v3, 0xbfb8aa3b, v3
	v_exp_f32_e32 v3, v3
	v_add_f32_e32 v128, v132, v242
	v_add_f32_e32 v132, v149, v240
	v_exp_f32_e32 v149, v145
	v_add_f32_e32 v3, 1.0, v3
	v_mul_f32_e32 v132, 0xbfb8aa3b, v132
	v_exp_f32_e32 v145, v132
	v_rcp_f32_e32 v132, v3
	v_add_f32_e32 v3, 1.0, v149
	v_rcp_f32_e32 v149, v3
	v_add_f32_e32 v3, v133, v243
	v_exp_f32_e32 v133, v129
	v_mul_f32_e32 v126, 0xbfb8aa3b, v126
	v_mul_f32_e32 v127, 0xbfb8aa3b, v127
	v_mul_f32_e32 v144, 0xbfb8aa3b, v144
	v_mul_f32_e32 v128, 0xbfb8aa3b, v128
	v_mul_f32_e32 v3, 0xbfb8aa3b, v3
	v_exp_f32_e32 v142, v142
	v_exp_f32_e32 v126, v126
	v_exp_f32_e32 v127, v127
	v_exp_f32_e32 v144, v144
	v_exp_f32_e32 v128, v128
	v_exp_f32_e32 v129, v3
	v_add_f32_e32 v3, 1.0, v133
	v_rcp_f32_e32 v133, v3
	v_pk_add_f32 v[144:145], v[144:145], 1.0 op_sel_hi:[1,0]
	v_pk_add_f32 v[142:143], v[142:143], 1.0 op_sel_hi:[1,0]
	v_pk_add_f32 v[128:129], v[128:129], 1.0 op_sel_hi:[1,0]
	v_pk_add_f32 v[126:127], v[126:127], 1.0 op_sel_hi:[1,0]
	v_pk_mul_f32 v[142:143], v[142:143], v[146:147]
	v_pk_mul_f32 v[144:145], v[144:145], v[148:149]
	v_pk_mul_f32 v[126:127], v[126:127], v[130:131]
	v_pk_mul_f32 v[128:129], v[128:129], v[132:133]
	v_pk_mul_f32 v[76:77], v[76:77], v[144:145]
	v_pk_mul_f32 v[74:75], v[74:75], v[142:143]
	v_pk_mul_f32 v[72:73], v[72:73], v[128:129]
	v_pk_mul_f32 v[70:71], v[70:71], v[126:127]
	global_load_dwordx4 v[196:199], v[4:5], off offset:256
	global_load_dwordx4 v[236:239], v[186:187], off offset:256
	global_load_dwordx4 v[146:149], v[188:189], off offset:256
	global_load_dwordx4 v[142:145], v[190:191], off offset:256
	global_load_dwordx4 v[130:133], v[194:195], off offset:256
	global_load_dwordx4 v[126:129], v[200:201], off offset:256
	s_waitcnt vmcnt(11)
; __device__ __forceinline__ void unpack8(const u32x4 w, float (&v)[8]) { v[0] = bf_lo(w.x); v[1] = bf_hi(w.x); v[2] = bf_lo(w.y); v[3] = bf_hi(w.y); v[4] = bf_lo(w.z); v[5] = bf_hi(w.z); v[6] = bf_lo(w.w); v[7] = bf_hi(w.w); }
;     __device__ __forceinline__ void after(int te, f32x4 (&acc)[2][2][4][2], const Unit& u, int wr, int wc, int fr, int fq) const {
;     ...
;                     for (int m = 0; m < 4; ++m) { float vs[8], va[8]; unpack8(gs[m], vs); unpack8(ga[m], va);
; #pragma unroll
;                         for (int e = 0; e < 4; ++e) {
;                             acc[ai][bj][m][0][e] *= (1.f + __expf(-(va[e] + a0[e]))) * __builtin_amdgcn_rcpf(1.f + __expf(-(vs[e] + s0[e])));
;                             acc[ai][bj][m][1][e] *= (1.f + __expf(-(va[4 + e] + a1[e]))) * __builtin_amdgcn_rcpf(1.f + __expf(-(vs[4 + e] + s1[e]))); } }
	v_lshlrev_b32_e32 v3, 16, v228
	v_lshlrev_b32_e32 v187, 16, v230
	v_and_b32_e32 v5, 0xffff0000, v228
	s_waitcnt vmcnt(10)
	v_lshlrev_b32_e32 v188, 16, v234
	v_and_b32_e32 v189, 0xffff0000, v230
	v_lshlrev_b32_e32 v192, 16, v229
	v_and_b32_e32 v191, 0xffff0000, v232
	v_lshlrev_b32_e32 v195, 16, v231
	v_lshlrev_b32_e32 v194, 16, v233
	v_and_b32_e32 v193, 0xffff0000, v229
	v_lshlrev_b32_e32 v203, 16, v235
	s_waitcnt vmcnt(8)
	v_add_f32_e32 v3, v158, v3
	v_mul_f32_e32 v3, 0xbfb8aa3b, v3
	v_exp_f32_e32 v3, v3
	v_add_f32_e32 v193, v161, v193
	v_mul_f32_e32 v193, 0xbfb8aa3b, v193
	v_lshlrev_b32_e32 v4, 16, v232
	v_add_f32_e32 v3, 1.0, v3
	v_rcp_f32_e32 v186, v3
	v_add_f32_e32 v3, v150, v187
	v_mul_f32_e32 v3, 0xbfb8aa3b, v3
	v_exp_f32_e32 v3, v3
	s_waitcnt vmcnt(7)
	v_add_f32_e32 v187, v154, v188
	v_mul_f32_e32 v187, 0xbfb8aa3b, v187
	v_exp_f32_e32 v188, v187
	v_add_f32_e32 v3, 1.0, v3
	v_rcp_f32_e32 v190, v3
	v_add_f32_e32 v3, v159, v5
	v_mul_f32_e32 v3, 0xbfb8aa3b, v3
	v_exp_f32_e32 v3, v3
	s_waitcnt vmcnt(6)
	v_add_f32_e32 v5, v163, v191
	v_and_b32_e32 v202, 0xffff0000, v233
	v_and_b32_e32 v200, 0xffff0000, v234
	v_add_f32_e32 v3, 1.0, v3
	v_rcp_f32_e32 v187, v3
	v_add_f32_e32 v3, v151, v189
	v_mul_f32_e32 v3, 0xbfb8aa3b, v3
	v_exp_f32_e32 v3, v3
	v_add_f32_e32 v4, v162, v4
	v_add_f32_e32 v189, v155, v200
	v_mul_f32_e32 v4, 0xbfb8aa3b, v4
	v_add_f32_e32 v3, 1.0, v3
	v_rcp_f32_e32 v191, v3
	v_add_f32_e32 v3, v160, v192
	v_mul_f32_e32 v3, 0xbfb8aa3b, v3
	v_exp_f32_e32 v3, v3
	v_add_f32_e32 v192, v164, v194
	v_mul_f32_e32 v5, 0xbfb8aa3b, v5
	v_mul_f32_e32 v192, 0xbfb8aa3b, v192
	v_add_f32_e32 v3, 1.0, v3
	v_rcp_f32_e32 v194, v3
	v_add_f32_e32 v3, v152, v195
	v_mul_f32_e32 v3, 0xbfb8aa3b, v3
	v_exp_f32_e32 v3, v3
	v_add_f32_e32 v195, v156, v203
	v_exp_f32_e32 v203, v193
	v_mul_f32_e32 v195, 0xbfb8aa3b, v195
	v_exp_f32_e32 v200, v195
	v_add_f32_e32 v195, v165, v202
	v_add_f32_e32 v3, 1.0, v3
	v_mul_f32_e32 v193, 0xbfb8aa3b, v195
	v_exp_f32_e32 v4, v4
	v_exp_f32_e32 v5, v5
	v_exp_f32_e32 v192, v192
	v_exp_f32_e32 v193, v193
	v_rcp_f32_e32 v202, v3
	v_add_f32_e32 v3, 1.0, v203
	v_rcp_f32_e32 v195, v3
	v_pk_add_f32 v[192:193], v[192:193], 1.0 op_sel_hi:[1,0]
	v_pk_add_f32 v[4:5], v[4:5], 1.0 op_sel_hi:[1,0]
	v_and_b32_e32 v201, 0xffff0000, v231
	v_pk_mul_f32 v[4:5], v[4:5], v[186:187]
	v_pk_mul_f32 v[186:187], v[192:193], v[194:195]
	v_and_b32_e32 v225, 0xffff0000, v235
	v_pk_mul_f32 v[68:69], v[68:69], v[186:187]
	v_add_f32_e32 v186, v153, v201
	v_mul_f32_e32 v186, 0xbfb8aa3b, v186
	v_exp_f32_e32 v186, v186
	v_add_f32_e32 v3, v157, v225
	v_mul_f32_e32 v3, 0xbfb8aa3b, v3
	v_exp_f32_e32 v201, v3
	v_add_f32_e32 v3, 1.0, v186
	v_mul_f32_e32 v189, 0xbfb8aa3b, v189
	v_rcp_f32_e32 v203, v3
	s_waitcnt vmcnt(5)
	v_lshlrev_b32_e32 v3, 16, v196
	v_exp_f32_e32 v189, v189
	v_add_f32_e32 v3, v158, v3
	v_mul_f32_e32 v3, 0xbfb8aa3b, v3
	v_exp_f32_e32 v3, v3
	v_pk_add_f32 v[186:187], v[188:189], 1.0 op_sel_hi:[1,0]
	v_pk_mul_f32 v[66:67], v[66:67], v[4:5]
	v_pk_mul_f32 v[186:187], v[186:187], v[190:191]
	v_add_f32_e32 v3, 1.0, v3
	v_pk_mul_f32 v[62:63], v[62:63], v[186:187]
	v_lshlrev_b32_e32 v187, 16, v198
	v_rcp_f32_e32 v186, v3
	v_add_f32_e32 v3, v150, v187
	v_mul_f32_e32 v3, 0xbfb8aa3b, v3
	v_exp_f32_e32 v3, v3
	v_pk_add_f32 v[4:5], v[200:201], 1.0 op_sel_hi:[1,0]
	s_waitcnt vmcnt(4)
	v_lshlrev_b32_e32 v188, 16, v238
	v_pk_mul_f32 v[4:5], v[4:5], v[202:203]
	v_add_f32_e32 v3, 1.0, v3
	v_pk_mul_f32 v[64:65], v[64:65], v[4:5]
	v_and_b32_e32 v5, 0xffff0000, v196
	v_rcp_f32_e32 v190, v3
	v_add_f32_e32 v3, v159, v5
	v_mul_f32_e32 v3, 0xbfb8aa3b, v3
	v_exp_f32_e32 v3, v3
	v_add_f32_e32 v187, v154, v188
	v_and_b32_e32 v189, 0xffff0000, v198
	v_mul_f32_e32 v187, 0xbfb8aa3b, v187
	v_add_f32_e32 v3, 1.0, v3
	v_exp_f32_e32 v188, v187
	v_rcp_f32_e32 v187, v3
	v_add_f32_e32 v3, v151, v189
	v_mul_f32_e32 v3, 0xbfb8aa3b, v3
	v_exp_f32_e32 v3, v3
	v_lshlrev_b32_e32 v192, 16, v197
	v_and_b32_e32 v191, 0xffff0000, v236
	v_add_f32_e32 v5, v163, v191
	v_add_f32_e32 v3, 1.0, v3
	v_rcp_f32_e32 v191, v3
	v_add_f32_e32 v3, v160, v192
	v_mul_f32_e32 v3, 0xbfb8aa3b, v3
	v_exp_f32_e32 v3, v3
	v_lshlrev_b32_e32 v195, 16, v199
	v_lshlrev_b32_e32 v194, 16, v237
	v_and_b32_e32 v193, 0xffff0000, v197
	v_add_f32_e32 v3, 1.0, v3
	v_add_f32_e32 v192, v164, v194
	v_rcp_f32_e32 v194, v3
	v_add_f32_e32 v3, v152, v195
	v_mul_f32_e32 v3, 0xbfb8aa3b, v3
	v_add_f32_e32 v193, v161, v193
	v_and_b32_e32 v197, 0xffff0000, v199
	v_lshlrev_b32_e32 v199, 16, v239
	v_exp_f32_e32 v3, v3
	v_mul_f32_e32 v193, 0xbfb8aa3b, v193
	v_add_f32_e32 v195, v156, v199
	v_exp_f32_e32 v199, v193
	v_lshlrev_b32_e32 v4, 16, v236
	v_and_b32_e32 v198, 0xffff0000, v237
	v_and_b32_e32 v196, 0xffff0000, v238
	v_mul_f32_e32 v195, 0xbfb8aa3b, v195
	v_add_f32_e32 v4, v162, v4
	v_add_f32_e32 v189, v155, v196
	v_exp_f32_e32 v196, v195
	v_add_f32_e32 v195, v165, v198
	v_mul_f32_e32 v4, 0xbfb8aa3b, v4
	v_mul_f32_e32 v5, 0xbfb8aa3b, v5
	v_mul_f32_e32 v192, 0xbfb8aa3b, v192
	v_add_f32_e32 v3, 1.0, v3
	v_mul_f32_e32 v193, 0xbfb8aa3b, v195
	v_exp_f32_e32 v4, v4
	v_exp_f32_e32 v5, v5
	v_exp_f32_e32 v192, v192
	v_exp_f32_e32 v193, v193
	v_rcp_f32_e32 v198, v3
	v_add_f32_e32 v3, 1.0, v199
	v_rcp_f32_e32 v195, v3
	v_pk_add_f32 v[192:193], v[192:193], 1.0 op_sel_hi:[1,0]
	v_pk_add_f32 v[4:5], v[4:5], 1.0 op_sel_hi:[1,0]
	v_and_b32_e32 v200, 0xffff0000, v239
	v_pk_mul_f32 v[4:5], v[4:5], v[186:187]
	v_pk_mul_f32 v[186:187], v[192:193], v[194:195]
	v_add_f32_e32 v3, v157, v200
	v_pk_mul_f32 v[60:61], v[60:61], v[186:187]
	v_add_f32_e32 v186, v153, v197
	v_mul_f32_e32 v186, 0xbfb8aa3b, v186
	v_exp_f32_e32 v186, v186
	v_mul_f32_e32 v3, 0xbfb8aa3b, v3
	v_exp_f32_e32 v197, v3
	v_mul_f32_e32 v189, 0xbfb8aa3b, v189
	v_add_f32_e32 v3, 1.0, v186
	v_rcp_f32_e32 v199, v3
	s_waitcnt vmcnt(3)
; __device__ __forceinline__ void unpack8(const u32x4 w, float (&v)[8]) { v[0] = bf_lo(w.x); v[1] = bf_hi(w.x); v[2] = bf_lo(w.y); v[3] = bf_hi(w.y); v[4] = bf_lo(w.z); v[5] = bf_hi(w.z); v[6] = bf_lo(w.w); v[7] = bf_hi(w.w); }
;     __device__ __forceinline__ void after(int te, f32x4 (&acc)[2][2][4][2], const Unit& u, int wr, int wc, int fr, int fq) const {
;     ...
;                     for (int m = 0; m < 4; ++m) { const size_t r = (size_t)(row0 + ai * HALF + m * 16); gs[m] = *(const u32x4*)(proj + r * LDP + PGS + c); ga[m] = *(const u32x4*)(proj + r * LDP + PGA + c); }
;     ...
;                     for (int m = 0; m < 4; ++m) { float vs[8], va[8]; unpack8(gs[m], vs); unpack8(ga[m], va);
; #pragma unroll
;                         for (int e = 0; e < 4; ++e) {
;                             acc[ai][bj][m][0][e] *= (1.f + __expf(-(va[e] + a0[e]))) * __builtin_amdgcn_rcpf(1.f + __expf(-(vs[e] + s0[e])));
;                             acc[ai][bj][m][1][e] *= (1.f + __expf(-(va[4 + e] + a1[e]))) * __builtin_amdgcn_rcpf(1.f + __expf(-(vs[4 + e] + s1[e]))); } }
	v_lshlrev_b32_e32 v3, 16, v146
	v_add_f32_e32 v3, v158, v3
	v_exp_f32_e32 v189, v189
	v_mul_f32_e32 v3, 0xbfb8aa3b, v3
	v_exp_f32_e32 v3, v3
	v_pk_mul_f32 v[58:59], v[58:59], v[4:5]
	v_pk_add_f32 v[4:5], v[196:197], 1.0 op_sel_hi:[1,0]
	v_pk_add_f32 v[186:187], v[188:189], 1.0 op_sel_hi:[1,0]
	v_pk_mul_f32 v[4:5], v[4:5], v[198:199]
	v_pk_mul_f32 v[186:187], v[186:187], v[190:191]
	v_pk_mul_f32 v[56:57], v[56:57], v[4:5]
	v_and_b32_e32 v5, 0xffff0000, v146
	v_lshlrev_b32_e32 v146, 16, v148
	v_add_f32_e32 v3, 1.0, v3
	v_pk_mul_f32 v[54:55], v[54:55], v[186:187]
	v_lshlrev_b32_e32 v186, 16, v147
	v_and_b32_e32 v187, 0xffff0000, v147
	v_and_b32_e32 v147, 0xffff0000, v148
	s_waitcnt vmcnt(2)
	v_lshlrev_b32_e32 v4, 16, v142
	v_and_b32_e32 v148, 0xffff0000, v142
	v_rcp_f32_e32 v142, v3
	v_add_f32_e32 v3, v150, v146
	v_mul_f32_e32 v3, 0xbfb8aa3b, v3
	v_exp_f32_e32 v3, v3
	v_lshlrev_b32_e32 v188, 16, v149
	v_and_b32_e32 v189, 0xffff0000, v149
	v_lshlrev_b32_e32 v149, 16, v143
	v_add_f32_e32 v3, 1.0, v3
	v_rcp_f32_e32 v146, v3
	v_add_f32_e32 v3, v159, v5
	v_mul_f32_e32 v3, 0xbfb8aa3b, v3
	v_exp_f32_e32 v3, v3
	v_and_b32_e32 v190, 0xffff0000, v143
	v_lshlrev_b32_e32 v143, 16, v144
	v_add_f32_e32 v143, v154, v143
	v_mul_f32_e32 v143, 0xbfb8aa3b, v143
	v_add_f32_e32 v3, 1.0, v3
	v_and_b32_e32 v191, 0xffff0000, v144
	v_exp_f32_e32 v144, v143
	v_rcp_f32_e32 v143, v3
	v_add_f32_e32 v3, v151, v147
	v_mul_f32_e32 v3, 0xbfb8aa3b, v3
	v_exp_f32_e32 v3, v3
	v_add_f32_e32 v187, v161, v187
	v_lshlrev_b32_e32 v192, 16, v145
	v_mul_f32_e32 v187, 0xbfb8aa3b, v187
	v_add_f32_e32 v3, 1.0, v3
	v_rcp_f32_e32 v147, v3
	v_add_f32_e32 v3, v160, v186
	v_mul_f32_e32 v3, 0xbfb8aa3b, v3
	v_exp_f32_e32 v3, v3
	v_add_f32_e32 v5, v163, v148
	v_add_f32_e32 v148, v164, v149
	v_add_f32_e32 v149, v156, v192
	v_add_f32_e32 v3, 1.0, v3
	v_rcp_f32_e32 v186, v3
	v_add_f32_e32 v3, v152, v188
	v_mul_f32_e32 v3, 0xbfb8aa3b, v3
	v_exp_f32_e32 v3, v3
	v_exp_f32_e32 v187, v187
	v_mul_f32_e32 v149, 0xbfb8aa3b, v149
	v_add_f32_e32 v4, v162, v4
	v_exp_f32_e32 v188, v149
	v_add_f32_e32 v149, v165, v190
	v_mul_f32_e32 v4, 0xbfb8aa3b, v4
	v_mul_f32_e32 v5, 0xbfb8aa3b, v5
	v_mul_f32_e32 v148, 0xbfb8aa3b, v148
	v_add_f32_e32 v3, 1.0, v3
	v_mul_f32_e32 v149, 0xbfb8aa3b, v149
	v_exp_f32_e32 v4, v4
	v_exp_f32_e32 v5, v5
	v_exp_f32_e32 v148, v148
	v_exp_f32_e32 v149, v149
	v_rcp_f32_e32 v190, v3
	v_add_f32_e32 v3, 1.0, v187
	v_rcp_f32_e32 v187, v3
	v_pk_add_f32 v[148:149], v[148:149], 1.0 op_sel_hi:[1,0]
	v_pk_add_f32 v[4:5], v[4:5], 1.0 op_sel_hi:[1,0]
	v_and_b32_e32 v193, 0xffff0000, v145
	v_pk_mul_f32 v[4:5], v[4:5], v[142:143]
	v_pk_mul_f32 v[142:143], v[148:149], v[186:187]
	v_add_f32_e32 v3, v157, v193
	v_pk_mul_f32 v[52:53], v[52:53], v[142:143]
	v_add_f32_e32 v142, v153, v189
	v_mul_f32_e32 v142, 0xbfb8aa3b, v142
	v_mul_f32_e32 v3, 0xbfb8aa3b, v3
	v_exp_f32_e32 v142, v142
	v_exp_f32_e32 v189, v3
	v_pk_mul_f32 v[50:51], v[50:51], v[4:5]
	v_add_f32_e32 v3, 1.0, v142
	v_pk_add_f32 v[4:5], v[188:189], 1.0 op_sel_hi:[1,0]
	global_load_dwordx4 v[186:189], v[218:219], off offset:256
	v_add_f32_e32 v145, v155, v191
	v_rcp_f32_e32 v191, v3
	s_waitcnt vmcnt(2)
	v_lshlrev_b32_e32 v3, 16, v130
	v_mul_f32_e32 v145, 0xbfb8aa3b, v145
	v_add_f32_e32 v3, v158, v3
	v_exp_f32_e32 v145, v145
	v_mul_f32_e32 v3, 0xbfb8aa3b, v3
	v_exp_f32_e32 v3, v3
	v_pk_mul_f32 v[4:5], v[4:5], v[190:191]
	v_pk_add_f32 v[142:143], v[144:145], 1.0 op_sel_hi:[1,0]
	v_pk_mul_f32 v[48:49], v[48:49], v[4:5]
	v_pk_mul_f32 v[142:143], v[142:143], v[146:147]
	v_and_b32_e32 v5, 0xffff0000, v130
	v_lshlrev_b32_e32 v130, 16, v132
	v_add_f32_e32 v3, 1.0, v3
	v_pk_mul_f32 v[46:47], v[46:47], v[142:143]
	v_lshlrev_b32_e32 v142, 16, v131
	v_and_b32_e32 v143, 0xffff0000, v131
	v_and_b32_e32 v131, 0xffff0000, v132
	s_waitcnt vmcnt(1)
	v_lshlrev_b32_e32 v4, 16, v126
	v_and_b32_e32 v132, 0xffff0000, v126
	v_rcp_f32_e32 v126, v3
	v_add_f32_e32 v3, v150, v130
	v_mul_f32_e32 v3, 0xbfb8aa3b, v3
	v_exp_f32_e32 v3, v3
	global_load_dwordx4 v[190:193], v[216:217], off offset:256
	v_lshlrev_b32_e32 v144, 16, v133
	v_and_b32_e32 v145, 0xffff0000, v133
	v_add_f32_e32 v3, 1.0, v3
	v_rcp_f32_e32 v130, v3
	v_add_f32_e32 v3, v159, v5
	v_mul_f32_e32 v3, 0xbfb8aa3b, v3
	v_exp_f32_e32 v3, v3
	v_lshlrev_b32_e32 v133, 16, v127
	v_and_b32_e32 v146, 0xffff0000, v127
	v_lshlrev_b32_e32 v127, 16, v128
	v_add_f32_e32 v127, v154, v127
	v_mul_f32_e32 v127, 0xbfb8aa3b, v127
	v_add_f32_e32 v3, 1.0, v3
	v_and_b32_e32 v147, 0xffff0000, v128
	v_exp_f32_e32 v128, v127
	v_rcp_f32_e32 v127, v3
	v_add_f32_e32 v3, v151, v131
	v_mul_f32_e32 v3, 0xbfb8aa3b, v3
	v_exp_f32_e32 v3, v3
	v_add_f32_e32 v143, v161, v143
	v_lshlrev_b32_e32 v148, 16, v129
	v_mul_f32_e32 v143, 0xbfb8aa3b, v143
	v_add_f32_e32 v3, 1.0, v3
	v_rcp_f32_e32 v131, v3
	v_add_f32_e32 v3, v160, v142
	v_mul_f32_e32 v3, 0xbfb8aa3b, v3
	v_exp_f32_e32 v3, v3
	v_add_f32_e32 v5, v163, v132
	v_add_f32_e32 v132, v164, v133
	v_add_f32_e32 v133, v156, v148
	v_add_f32_e32 v3, 1.0, v3
	v_rcp_f32_e32 v142, v3
	v_add_f32_e32 v3, v152, v144
	v_mul_f32_e32 v3, 0xbfb8aa3b, v3
	v_exp_f32_e32 v3, v3
	v_exp_f32_e32 v143, v143
	v_mul_f32_e32 v133, 0xbfb8aa3b, v133
	v_add_f32_e32 v4, v162, v4
	v_exp_f32_e32 v144, v133
	v_add_f32_e32 v133, v165, v146
	v_mul_f32_e32 v4, 0xbfb8aa3b, v4
	v_mul_f32_e32 v5, 0xbfb8aa3b, v5
	v_mul_f32_e32 v132, 0xbfb8aa3b, v132
	v_add_f32_e32 v3, 1.0, v3
	v_mul_f32_e32 v133, 0xbfb8aa3b, v133
	v_exp_f32_e32 v4, v4
	v_exp_f32_e32 v5, v5
	v_exp_f32_e32 v132, v132
	v_exp_f32_e32 v133, v133
	v_rcp_f32_e32 v146, v3
	v_add_f32_e32 v3, 1.0, v143
	v_rcp_f32_e32 v143, v3
	v_pk_add_f32 v[132:133], v[132:133], 1.0 op_sel_hi:[1,0]
	v_pk_add_f32 v[4:5], v[4:5], 1.0 op_sel_hi:[1,0]
	v_and_b32_e32 v149, 0xffff0000, v129
	v_pk_mul_f32 v[4:5], v[4:5], v[126:127]
	v_pk_mul_f32 v[126:127], v[132:133], v[142:143]
	v_add_f32_e32 v129, v155, v147
	v_pk_mul_f32 v[44:45], v[44:45], v[126:127]
	v_add_f32_e32 v126, v153, v145
	v_mul_f32_e32 v126, 0xbfb8aa3b, v126
	v_exp_f32_e32 v126, v126
	v_mul_f32_e32 v129, 0xbfb8aa3b, v129
	v_add_f32_e32 v3, v157, v149
	v_exp_f32_e32 v129, v129
	v_mul_f32_e32 v3, 0xbfb8aa3b, v3
	v_exp_f32_e32 v145, v3
	v_add_f32_e32 v3, 1.0, v126
	v_rcp_f32_e32 v147, v3
	v_pk_add_f32 v[126:127], v[128:129], 1.0 op_sel_hi:[1,0]
	v_pk_mul_f32 v[42:43], v[42:43], v[4:5]
	v_pk_add_f32 v[4:5], v[144:145], 1.0 op_sel_hi:[1,0]
	v_pk_mul_f32 v[126:127], v[126:127], v[130:131]
	v_pk_mul_f32 v[4:5], v[4:5], v[146:147]
	v_pk_mul_f32 v[38:39], v[38:39], v[126:127]
	global_load_dwordx4 v[194:197], v[204:205], off offset:256
	global_load_dwordx4 v[198:201], v[206:207], off offset:256
	global_load_dwordx4 v[146:149], v[208:209], off offset:256
	global_load_dwordx4 v[142:145], v[210:211], off offset:256
	global_load_dwordx4 v[130:133], v[212:213], off offset:256
	global_load_dwordx4 v[126:129], v[214:215], off offset:256
	s_waitcnt vmcnt(7)
; __device__ __forceinline__ void unpack8(const u32x4 w, float (&v)[8]) { v[0] = bf_lo(w.x); v[1] = bf_hi(w.x); v[2] = bf_lo(w.y); v[3] = bf_hi(w.y); v[4] = bf_lo(w.z); v[5] = bf_hi(w.z); v[6] = bf_lo(w.w); v[7] = bf_hi(w.w); }
;     __device__ __forceinline__ void after(int te, f32x4 (&acc)[2][2][4][2], const Unit& u, int wr, int wc, int fr, int fq) const {
;     ...
;                     for (int m = 0; m < 4; ++m) { float vs[8], va[8]; unpack8(gs[m], vs); unpack8(ga[m], va);
; #pragma unroll
;                         for (int e = 0; e < 4; ++e) {
;                             acc[ai][bj][m][0][e] *= (1.f + __expf(-(va[e] + a0[e]))) * __builtin_amdgcn_rcpf(1.f + __expf(-(vs[e] + s0[e])));
;                             acc[ai][bj][m][1][e] *= (1.f + __expf(-(va[4 + e] + a1[e]))) * __builtin_amdgcn_rcpf(1.f + __expf(-(vs[4 + e] + s1[e]))); } }
	v_lshlrev_b32_e32 v3, 16, v186
	v_add_f32_e32 v3, v158, v3
	v_mul_f32_e32 v3, 0xbfb8aa3b, v3
	v_exp_f32_e32 v3, v3
	v_lshlrev_b32_e32 v202, 16, v187
	v_and_b32_e32 v203, 0xffff0000, v187
	v_lshlrev_b32_e32 v187, 16, v188
	v_add_f32_e32 v3, 1.0, v3
	v_pk_mul_f32 v[40:41], v[40:41], v[4:5]
	v_and_b32_e32 v5, 0xffff0000, v186
	v_rcp_f32_e32 v186, v3
	v_add_f32_e32 v3, v150, v187
	v_mul_f32_e32 v3, 0xbfb8aa3b, v3
	v_exp_f32_e32 v3, v3
	v_lshlrev_b32_e32 v205, 16, v189
	v_and_b32_e32 v207, 0xffff0000, v189
	s_waitcnt vmcnt(6)
	v_lshlrev_b32_e32 v4, 16, v190
	v_add_f32_e32 v3, 1.0, v3
	v_and_b32_e32 v189, 0xffff0000, v190
	v_rcp_f32_e32 v190, v3
	v_add_f32_e32 v3, v159, v5
	v_mul_f32_e32 v3, 0xbfb8aa3b, v3
	v_exp_f32_e32 v3, v3
	v_and_b32_e32 v204, 0xffff0000, v188
	v_lshlrev_b32_e32 v188, 16, v192
	v_add_f32_e32 v187, v154, v188
	v_mul_f32_e32 v187, 0xbfb8aa3b, v187
	v_add_f32_e32 v3, 1.0, v3
	v_exp_f32_e32 v188, v187
	v_rcp_f32_e32 v187, v3
	v_add_f32_e32 v3, v151, v204
	v_mul_f32_e32 v3, 0xbfb8aa3b, v3
	v_exp_f32_e32 v3, v3
	v_lshlrev_b32_e32 v206, 16, v191
	v_and_b32_e32 v208, 0xffff0000, v191
	v_and_b32_e32 v191, 0xffff0000, v192
	v_add_f32_e32 v3, 1.0, v3
	v_add_f32_e32 v5, v163, v189
	v_add_f32_e32 v189, v155, v191
	v_rcp_f32_e32 v191, v3
	v_add_f32_e32 v3, v160, v202
	v_mul_f32_e32 v3, 0xbfb8aa3b, v3
	v_exp_f32_e32 v3, v3
	v_add_f32_e32 v203, v161, v203
	v_lshlrev_b32_e32 v209, 16, v193
	v_mul_f32_e32 v203, 0xbfb8aa3b, v203
	v_add_f32_e32 v3, 1.0, v3
	v_rcp_f32_e32 v202, v3
	v_add_f32_e32 v3, v152, v205
	v_mul_f32_e32 v3, 0xbfb8aa3b, v3
	v_exp_f32_e32 v3, v3
	v_and_b32_e32 v210, 0xffff0000, v193
	v_add_f32_e32 v193, v156, v209
	v_exp_f32_e32 v203, v203
	v_mul_f32_e32 v193, 0xbfb8aa3b, v193
	v_add_f32_e32 v4, v162, v4
	v_add_f32_e32 v192, v164, v206
	v_exp_f32_e32 v204, v193
	v_add_f32_e32 v193, v165, v208
	v_mul_f32_e32 v4, 0xbfb8aa3b, v4
	v_mul_f32_e32 v5, 0xbfb8aa3b, v5
	v_mul_f32_e32 v192, 0xbfb8aa3b, v192
	v_add_f32_e32 v3, 1.0, v3
	v_mul_f32_e32 v193, 0xbfb8aa3b, v193
	v_exp_f32_e32 v4, v4
	v_exp_f32_e32 v5, v5
	v_exp_f32_e32 v192, v192
	v_exp_f32_e32 v193, v193
	v_rcp_f32_e32 v206, v3
	v_add_f32_e32 v3, 1.0, v203
	v_rcp_f32_e32 v203, v3
	v_pk_add_f32 v[192:193], v[192:193], 1.0 op_sel_hi:[1,0]
	v_pk_add_f32 v[4:5], v[4:5], 1.0 op_sel_hi:[1,0]
	v_add_f32_e32 v3, v157, v210
	v_pk_mul_f32 v[4:5], v[4:5], v[186:187]
	v_pk_mul_f32 v[186:187], v[192:193], v[202:203]
	v_mul_f32_e32 v3, 0xbfb8aa3b, v3
	v_pk_mul_f32 v[36:37], v[36:37], v[186:187]
	v_add_f32_e32 v186, v153, v207
	v_mul_f32_e32 v186, 0xbfb8aa3b, v186
	v_exp_f32_e32 v186, v186
	v_exp_f32_e32 v205, v3
	v_mul_f32_e32 v189, 0xbfb8aa3b, v189
	v_exp_f32_e32 v189, v189
	v_add_f32_e32 v3, 1.0, v186
	v_rcp_f32_e32 v207, v3
	s_waitcnt vmcnt(5)
	v_lshlrev_b32_e32 v3, 16, v194
	v_add_f32_e32 v3, v158, v3
	v_mul_f32_e32 v3, 0xbfb8aa3b, v3
	v_exp_f32_e32 v3, v3
	v_pk_add_f32 v[186:187], v[188:189], 1.0 op_sel_hi:[1,0]
	v_pk_mul_f32 v[34:35], v[34:35], v[4:5]
	v_pk_mul_f32 v[186:187], v[186:187], v[190:191]
	v_add_f32_e32 v3, 1.0, v3
	v_pk_mul_f32 v[30:31], v[30:31], v[186:187]
	v_lshlrev_b32_e32 v187, 16, v196
	v_rcp_f32_e32 v186, v3
	v_add_f32_e32 v3, v150, v187
	v_mul_f32_e32 v3, 0xbfb8aa3b, v3
	v_exp_f32_e32 v3, v3
	v_pk_add_f32 v[4:5], v[204:205], 1.0 op_sel_hi:[1,0]
	s_waitcnt vmcnt(4)
	v_lshlrev_b32_e32 v188, 16, v200
	v_pk_mul_f32 v[4:5], v[4:5], v[206:207]
	v_add_f32_e32 v3, 1.0, v3
	v_pk_mul_f32 v[32:33], v[32:33], v[4:5]
	v_and_b32_e32 v5, 0xffff0000, v194
	v_rcp_f32_e32 v190, v3
	v_add_f32_e32 v3, v159, v5
	v_mul_f32_e32 v3, 0xbfb8aa3b, v3
	v_exp_f32_e32 v3, v3
	v_add_f32_e32 v187, v154, v188
	v_and_b32_e32 v189, 0xffff0000, v196
	v_mul_f32_e32 v187, 0xbfb8aa3b, v187
	v_add_f32_e32 v3, 1.0, v3
	v_exp_f32_e32 v188, v187
	v_rcp_f32_e32 v187, v3
	v_add_f32_e32 v3, v151, v189
	v_mul_f32_e32 v3, 0xbfb8aa3b, v3
	v_exp_f32_e32 v3, v3
	v_lshlrev_b32_e32 v192, 16, v195
	v_and_b32_e32 v191, 0xffff0000, v198
	v_add_f32_e32 v5, v163, v191
	v_add_f32_e32 v3, 1.0, v3
	v_rcp_f32_e32 v191, v3
	v_add_f32_e32 v3, v160, v192
	v_mul_f32_e32 v3, 0xbfb8aa3b, v3
	v_exp_f32_e32 v3, v3
	v_and_b32_e32 v193, 0xffff0000, v195
	v_lshlrev_b32_e32 v195, 16, v197
	v_lshlrev_b32_e32 v194, 16, v199
	v_add_f32_e32 v3, 1.0, v3
	v_add_f32_e32 v192, v164, v194
	v_rcp_f32_e32 v194, v3
	v_add_f32_e32 v3, v152, v195
	v_mul_f32_e32 v3, 0xbfb8aa3b, v3
	v_add_f32_e32 v193, v161, v193
	v_lshlrev_b32_e32 v4, 16, v198
	v_and_b32_e32 v198, 0xffff0000, v199
	v_lshlrev_b32_e32 v199, 16, v201
	v_exp_f32_e32 v3, v3
	v_mul_f32_e32 v193, 0xbfb8aa3b, v193
	v_add_f32_e32 v195, v156, v199
	v_exp_f32_e32 v199, v193
	v_and_b32_e32 v196, 0xffff0000, v200
	v_mul_f32_e32 v195, 0xbfb8aa3b, v195
	v_add_f32_e32 v4, v162, v4
	v_add_f32_e32 v189, v155, v196
	v_exp_f32_e32 v196, v195
	v_add_f32_e32 v195, v165, v198
	v_mul_f32_e32 v4, 0xbfb8aa3b, v4
	v_mul_f32_e32 v5, 0xbfb8aa3b, v5
	v_mul_f32_e32 v192, 0xbfb8aa3b, v192
	v_add_f32_e32 v3, 1.0, v3
	v_mul_f32_e32 v193, 0xbfb8aa3b, v195
	v_exp_f32_e32 v4, v4
	v_exp_f32_e32 v5, v5
	v_exp_f32_e32 v192, v192
	v_exp_f32_e32 v193, v193
	v_rcp_f32_e32 v198, v3
	v_add_f32_e32 v3, 1.0, v199
	v_rcp_f32_e32 v195, v3
	v_pk_add_f32 v[192:193], v[192:193], 1.0 op_sel_hi:[1,0]
	v_pk_add_f32 v[4:5], v[4:5], 1.0 op_sel_hi:[1,0]
	v_and_b32_e32 v197, 0xffff0000, v197
	v_pk_mul_f32 v[4:5], v[4:5], v[186:187]
	v_pk_mul_f32 v[186:187], v[192:193], v[194:195]
	v_and_b32_e32 v200, 0xffff0000, v201
	v_pk_mul_f32 v[28:29], v[28:29], v[186:187]
	v_add_f32_e32 v186, v153, v197
	v_mul_f32_e32 v186, 0xbfb8aa3b, v186
	v_exp_f32_e32 v186, v186
	v_add_f32_e32 v3, v157, v200
	v_mul_f32_e32 v3, 0xbfb8aa3b, v3
	v_exp_f32_e32 v197, v3
	v_add_f32_e32 v3, 1.0, v186
	v_rcp_f32_e32 v199, v3
	s_waitcnt vmcnt(3)
; __device__ __forceinline__ void unpack8(const u32x4 w, float (&v)[8]) { v[0] = bf_lo(w.x); v[1] = bf_hi(w.x); v[2] = bf_lo(w.y); v[3] = bf_hi(w.y); v[4] = bf_lo(w.z); v[5] = bf_hi(w.z); v[6] = bf_lo(w.w); v[7] = bf_hi(w.w); }
;     __device__ __forceinline__ void after(int te, f32x4 (&acc)[2][2][4][2], const Unit& u, int wr, int wc, int fr, int fq) const {
;     ...
;                     for (int m = 0; m < 4; ++m) { float vs[8], va[8]; unpack8(gs[m], vs); unpack8(ga[m], va);
; #pragma unroll
;                         for (int e = 0; e < 4; ++e) {
;                             acc[ai][bj][m][0][e] *= (1.f + __expf(-(va[e] + a0[e]))) * __builtin_amdgcn_rcpf(1.f + __expf(-(vs[e] + s0[e])));
;                             acc[ai][bj][m][1][e] *= (1.f + __expf(-(va[4 + e] + a1[e]))) * __builtin_amdgcn_rcpf(1.f + __expf(-(vs[4 + e] + s1[e]))); } }
	v_lshlrev_b32_e32 v3, 16, v146
	v_mul_f32_e32 v189, 0xbfb8aa3b, v189
	v_add_f32_e32 v3, v158, v3
	v_exp_f32_e32 v189, v189
	v_mul_f32_e32 v3, 0xbfb8aa3b, v3
	v_exp_f32_e32 v3, v3
	v_pk_mul_f32 v[26:27], v[26:27], v[4:5]
	v_pk_add_f32 v[4:5], v[196:197], 1.0 op_sel_hi:[1,0]
	v_pk_add_f32 v[186:187], v[188:189], 1.0 op_sel_hi:[1,0]
	v_pk_mul_f32 v[4:5], v[4:5], v[198:199]
	v_pk_mul_f32 v[186:187], v[186:187], v[190:191]
	v_pk_mul_f32 v[24:25], v[24:25], v[4:5]
	v_and_b32_e32 v5, 0xffff0000, v146
	v_lshlrev_b32_e32 v146, 16, v148
	v_add_f32_e32 v3, 1.0, v3
	v_pk_mul_f32 v[22:23], v[22:23], v[186:187]
	v_lshlrev_b32_e32 v186, 16, v147
	v_and_b32_e32 v187, 0xffff0000, v147
	v_and_b32_e32 v147, 0xffff0000, v148
	s_waitcnt vmcnt(2)
	v_lshlrev_b32_e32 v4, 16, v142
	v_and_b32_e32 v148, 0xffff0000, v142
	v_rcp_f32_e32 v142, v3
	v_add_f32_e32 v3, v150, v146
	v_mul_f32_e32 v3, 0xbfb8aa3b, v3
	v_exp_f32_e32 v3, v3
	v_lshlrev_b32_e32 v188, 16, v149
	v_and_b32_e32 v189, 0xffff0000, v149
	v_lshlrev_b32_e32 v149, 16, v143
	v_add_f32_e32 v3, 1.0, v3
	v_rcp_f32_e32 v146, v3
	v_add_f32_e32 v3, v159, v5
	v_mul_f32_e32 v3, 0xbfb8aa3b, v3
	v_exp_f32_e32 v3, v3
	v_and_b32_e32 v190, 0xffff0000, v143
	v_lshlrev_b32_e32 v143, 16, v144
	v_add_f32_e32 v143, v154, v143
	v_mul_f32_e32 v143, 0xbfb8aa3b, v143
	v_add_f32_e32 v3, 1.0, v3
	v_and_b32_e32 v191, 0xffff0000, v144
	v_exp_f32_e32 v144, v143
	v_rcp_f32_e32 v143, v3
	v_add_f32_e32 v3, v151, v147
	v_mul_f32_e32 v3, 0xbfb8aa3b, v3
	v_exp_f32_e32 v3, v3
	v_add_f32_e32 v187, v161, v187
	v_lshlrev_b32_e32 v192, 16, v145
	v_mul_f32_e32 v187, 0xbfb8aa3b, v187
	v_add_f32_e32 v3, 1.0, v3
	v_rcp_f32_e32 v147, v3
	v_add_f32_e32 v3, v160, v186
	v_mul_f32_e32 v3, 0xbfb8aa3b, v3
	v_exp_f32_e32 v3, v3
	v_add_f32_e32 v5, v163, v148
	v_add_f32_e32 v148, v164, v149
	v_add_f32_e32 v149, v156, v192
	v_add_f32_e32 v3, 1.0, v3
	v_rcp_f32_e32 v186, v3
	v_add_f32_e32 v3, v152, v188
	v_mul_f32_e32 v3, 0xbfb8aa3b, v3
	v_exp_f32_e32 v3, v3
	v_exp_f32_e32 v187, v187
	v_mul_f32_e32 v149, 0xbfb8aa3b, v149
	v_add_f32_e32 v4, v162, v4
	v_exp_f32_e32 v188, v149
	v_add_f32_e32 v149, v165, v190
	v_mul_f32_e32 v4, 0xbfb8aa3b, v4
	v_mul_f32_e32 v5, 0xbfb8aa3b, v5
	v_mul_f32_e32 v148, 0xbfb8aa3b, v148
	v_add_f32_e32 v3, 1.0, v3
	v_mul_f32_e32 v149, 0xbfb8aa3b, v149
	v_exp_f32_e32 v4, v4
	v_exp_f32_e32 v5, v5
	v_exp_f32_e32 v148, v148
	v_exp_f32_e32 v149, v149
	v_rcp_f32_e32 v190, v3
	v_add_f32_e32 v3, 1.0, v187
	v_rcp_f32_e32 v187, v3
	v_pk_add_f32 v[148:149], v[148:149], 1.0 op_sel_hi:[1,0]
	v_pk_add_f32 v[4:5], v[4:5], 1.0 op_sel_hi:[1,0]
	v_and_b32_e32 v193, 0xffff0000, v145
	v_pk_mul_f32 v[4:5], v[4:5], v[142:143]
	v_pk_mul_f32 v[142:143], v[148:149], v[186:187]
	v_add_f32_e32 v3, v157, v193
	v_pk_mul_f32 v[20:21], v[20:21], v[142:143]
	v_add_f32_e32 v142, v153, v189
	v_mul_f32_e32 v142, 0xbfb8aa3b, v142
	v_exp_f32_e32 v142, v142
	v_mul_f32_e32 v3, 0xbfb8aa3b, v3
	v_exp_f32_e32 v189, v3
	v_add_f32_e32 v145, v155, v191
	v_add_f32_e32 v3, 1.0, v142
	v_rcp_f32_e32 v191, v3
	s_waitcnt vmcnt(1)
	v_lshlrev_b32_e32 v3, 16, v130
	v_mul_f32_e32 v145, 0xbfb8aa3b, v145
	v_add_f32_e32 v3, v158, v3
	v_exp_f32_e32 v145, v145
	v_mul_f32_e32 v3, 0xbfb8aa3b, v3
	v_exp_f32_e32 v3, v3
	v_pk_mul_f32 v[18:19], v[18:19], v[4:5]
	v_pk_add_f32 v[4:5], v[188:189], 1.0 op_sel_hi:[1,0]
	v_pk_add_f32 v[142:143], v[144:145], 1.0 op_sel_hi:[1,0]
	v_pk_mul_f32 v[4:5], v[4:5], v[190:191]
	v_pk_mul_f32 v[142:143], v[142:143], v[146:147]
	v_pk_mul_f32 v[16:17], v[16:17], v[4:5]
	v_and_b32_e32 v5, 0xffff0000, v130
	v_lshlrev_b32_e32 v130, 16, v132
	v_add_f32_e32 v3, 1.0, v3
	v_pk_mul_f32 v[14:15], v[14:15], v[142:143]
	v_lshlrev_b32_e32 v142, 16, v131
	v_and_b32_e32 v143, 0xffff0000, v131
	v_and_b32_e32 v131, 0xffff0000, v132
	s_waitcnt vmcnt(0)
	v_lshlrev_b32_e32 v4, 16, v126
	v_and_b32_e32 v132, 0xffff0000, v126
	v_rcp_f32_e32 v126, v3
	v_add_f32_e32 v3, v150, v130
	v_mul_f32_e32 v3, 0xbfb8aa3b, v3
	v_exp_f32_e32 v3, v3
	v_lshlrev_b32_e32 v144, 16, v133
	v_and_b32_e32 v145, 0xffff0000, v133
	v_lshlrev_b32_e32 v133, 16, v127
	v_add_f32_e32 v3, 1.0, v3
	v_rcp_f32_e32 v130, v3
	v_add_f32_e32 v3, v159, v5
	v_mul_f32_e32 v3, 0xbfb8aa3b, v3
	v_exp_f32_e32 v3, v3
	v_and_b32_e32 v146, 0xffff0000, v127
	v_lshlrev_b32_e32 v127, 16, v128
	v_add_f32_e32 v127, v154, v127
	v_mul_f32_e32 v127, 0xbfb8aa3b, v127
	v_add_f32_e32 v3, 1.0, v3
	v_and_b32_e32 v147, 0xffff0000, v128
	v_exp_f32_e32 v128, v127
	v_rcp_f32_e32 v127, v3
	v_add_f32_e32 v3, v151, v131
	v_mul_f32_e32 v3, 0xbfb8aa3b, v3
	v_exp_f32_e32 v3, v3
	v_add_f32_e32 v143, v161, v143
	v_lshlrev_b32_e32 v148, 16, v129
	v_mul_f32_e32 v143, 0xbfb8aa3b, v143
	v_add_f32_e32 v3, 1.0, v3
	v_rcp_f32_e32 v131, v3
	v_add_f32_e32 v3, v160, v142
	v_mul_f32_e32 v3, 0xbfb8aa3b, v3
	v_exp_f32_e32 v3, v3
	v_add_f32_e32 v5, v163, v132
	v_add_f32_e32 v132, v164, v133
	v_add_f32_e32 v133, v156, v148
	v_add_f32_e32 v3, 1.0, v3
	v_rcp_f32_e32 v142, v3
	v_add_f32_e32 v3, v152, v144
	v_mul_f32_e32 v3, 0xbfb8aa3b, v3
	v_exp_f32_e32 v3, v3
	v_exp_f32_e32 v143, v143
	v_mul_f32_e32 v133, 0xbfb8aa3b, v133
	v_add_f32_e32 v4, v162, v4
	v_exp_f32_e32 v144, v133
	v_add_f32_e32 v133, v165, v146
	v_mul_f32_e32 v4, 0xbfb8aa3b, v4
	v_mul_f32_e32 v5, 0xbfb8aa3b, v5
	v_mul_f32_e32 v132, 0xbfb8aa3b, v132
	v_add_f32_e32 v3, 1.0, v3
	v_mul_f32_e32 v133, 0xbfb8aa3b, v133
	v_exp_f32_e32 v4, v4
	v_exp_f32_e32 v5, v5
	v_exp_f32_e32 v132, v132
	v_exp_f32_e32 v133, v133
	v_rcp_f32_e32 v146, v3
	v_add_f32_e32 v3, 1.0, v143
	v_rcp_f32_e32 v143, v3
	v_pk_add_f32 v[132:133], v[132:133], 1.0 op_sel_hi:[1,0]
	v_pk_add_f32 v[4:5], v[4:5], 1.0 op_sel_hi:[1,0]
	v_and_b32_e32 v149, 0xffff0000, v129
	v_pk_mul_f32 v[4:5], v[4:5], v[126:127]
	v_pk_mul_f32 v[126:127], v[132:133], v[142:143]
	v_add_f32_e32 v129, v155, v147
	v_pk_mul_f32 v[12:13], v[12:13], v[126:127]
	v_add_f32_e32 v126, v153, v145
	v_mul_f32_e32 v126, 0xbfb8aa3b, v126
	v_exp_f32_e32 v126, v126
	v_add_f32_e32 v3, v157, v149
	v_mul_f32_e32 v129, 0xbfb8aa3b, v129
	v_mul_f32_e32 v3, 0xbfb8aa3b, v3
	v_exp_f32_e32 v129, v129
	v_exp_f32_e32 v145, v3
	v_add_f32_e32 v3, 1.0, v126
	v_rcp_f32_e32 v147, v3
	v_pk_mul_f32 v[10:11], v[10:11], v[4:5]
	v_pk_add_f32 v[4:5], v[144:145], 1.0 op_sel_hi:[1,0]
	v_pk_add_f32 v[126:127], v[128:129], 1.0 op_sel_hi:[1,0]
	v_pk_mul_f32 v[4:5], v[4:5], v[146:147]
	v_pk_mul_f32 v[126:127], v[126:127], v[130:131]
	v_pk_mul_f32 v[8:9], v[8:9], v[4:5]
	v_pk_mul_f32 v[6:7], v[6:7], v[126:127]

; #define PG8_STAGE(bufoff, gbase, voff) do { _Pragma("unroll") for (int _i = 0; _i < 2; ++_i) \
;         __builtin_amdgcn_global_load_lds((const unsigned*)((const char*)(gbase) + (voff)[_i]), (LAS unsigned*)(lds + (bufoff) + ldsw + _i * 8192), 16, 0, 0); } while (0)
; #define PG8_LDA(dst, b, h) do { _Pragma("unroll") for (int m = 0; m < 4; ++m) _Pragma("unroll") for (int k = 0; k < 2; ++k) dst[m][k] = *(const LAS bf16x8*)(lds + PG8_SA(b, h) + aoff + m * 2048 + k * 1024); } while (0)
; #define PG8_LDB(dst, b, h) do { _Pragma("unroll") for (int n = 0; n < 2; ++n) _Pragma("unroll") for (int k = 0; k < 2; ++k) dst[n][k] = *(const LAS bf16x8*)(lds + PG8_SB(b, h) + boff + n * 2048 + k * 1024); } while (0)
; #define PG8_MMA(ai, bj, At, Bt) do { __builtin_amdgcn_s_setprio(1); _Pragma("unroll") for (int m = 0; m < 4; ++m) _Pragma("unroll") for (int n = 0; n < 2; ++n) _Pragma("unroll") for (int k = 0; k < 2; ++k) \
;         acc[ai][bj][m][n] = __builtin_amdgcn_mfma_f32_16x16x32_bf16(Bt[n][k], At[m][k], acc[ai][bj][m][n], 0, 0, 0); __builtin_amdgcn_s_setprio(0); } while (0)
; #define PG8_WAIT_V(n) asm volatile("s_waitcnt vmcnt(" #n ")" ::: "memory")
; #define PG8_WAIT_L(n) asm volatile("s_waitcnt lgkmcnt(" #n ")" ::: "memory")
; #define PG8_BAR __builtin_amdgcn_s_barrier()
; #define PG8_SCHED __builtin_amdgcn_sched_barrier(0)
; template <class Epi, class Sched, bool ALIGN_EPI, class Hook = NoHook>
; __device__ __forceinline__ void gemm_phase(LAS unsigned char* lds, const Gemm g, const Sched& S, const Epi& E, const Hook& H = Hook()) {
;     ...
;             const char* a1 = cA + (size_t)(t + 1) * kstep;
;             const char* a2 = last ? nA : cA + (size_t)(t + 2) * kstep; const char* b2 = last ? nB : cB + (size_t)(t + 2) * kstep;
;             const char* a3 = a2 + kstep; const char* b3 = b2 + kstep;
;             if (last && has_next) S.a_ready(nxt);
;             PG8_LDB(B0, 0, 0); PG8_LDB(B1, 0, 1); PG8_SCHED; PG8_LDA(At, 0, 0); PG8_STAGE(PG8_SA(1, 1), a1 + hA, voffA);
;             PG8_WAIT_V(8); PG8_WAIT_L(0); PG8_BAR; PG8_MMA(0, 0, At, B0); PG8_MMA(0, 1, At, B1); PG8_BAR; PG8_SCHED;
;             PG8_LDA(At, 0, 1); PG8_STAGE(PG8_SB(0, 0), b2, voffB); PG8_STAGE(PG8_SB(0, 1), b2 + hB, voffB); PG8_STAGE(PG8_SA(0, 0), a2, voffA);
;             PG8_WAIT_V(8); PG8_WAIT_L(0); PG8_BAR; PG8_MMA(1, 0, At, B0); PG8_MMA(1, 1, At, B1); PG8_BAR; PG8_SCHED;
.LBB0_850:
	ds_read_b128 v[146:149], v1
	ds_read_b128 v[150:153], v1 offset:1024
	s_add_u32 s20, s6, 0x87c00080
	s_addc_u32 s21, s7, -1
	s_cmp_lg_u32 s42, 60
	s_cselect_b32 s20, s20, 0
	s_cselect_b32 s21, s21, 0
	s_add_u32 s22, s2, s20
	s_addc_u32 s23, s3, s21
	s_add_u32 s20, s14, s20
	s_addc_u32 s21, s15, s21
	s_mov_b32 m0, s43
	ds_read_b128 v[154:157], v1 offset:2048
	ds_read_b128 v[158:161], v1 offset:3072
	ds_read_b128 v[162:165], v142
	ds_read_b128 v[166:169], v142 offset:1024
	ds_read_b128 v[170:173], v142 offset:2048
	ds_read_b128 v[174:177], v142 offset:3072
	v_lshl_add_u64 v[178:179], v[138:139], 0, s[6:7]
	global_load_lds_dwordx4 v[178:179], off
	ds_read_b128 v[186:189], v143
	ds_read_b128 v[190:193], v143 offset:1024
	ds_read_b128 v[194:197], v143 offset:2048
	ds_read_b128 v[198:201], v143 offset:3072
	ds_read_b128 v[202:205], v143 offset:4096
	ds_read_b128 v[206:209], v143 offset:5120
	ds_read_b128 v[210:213], v143 offset:6144
	ds_read_b128 v[214:217], v143 offset:7168
	v_lshl_add_u64 v[178:179], v[140:141], 0, s[6:7]
	s_mov_b32 m0, s44
	s_nop 0
	global_load_lds_dwordx4 v[178:179], off
	s_waitcnt vmcnt(8) lgkmcnt(0)
	s_barrier
	s_setprio 1
	v_mfma_f32_16x16x32_bf16 v[54:57], v[146:149], v[186:189], v[54:57]
	v_mfma_f32_16x16x32_bf16 v[34:37], v[154:157], v[186:189], v[34:37]
	v_mfma_f32_16x16x32_bf16 v[42:45], v[146:149], v[194:197], v[42:45]
	v_mfma_f32_16x16x32_bf16 v[30:33], v[154:157], v[194:197], v[30:33]
	v_mfma_f32_16x16x32_bf16 v[62:65], v[146:149], v[202:205], v[62:65]
	v_mfma_f32_16x16x32_bf16 v[50:53], v[154:157], v[202:205], v[50:53]
	v_mfma_f32_16x16x32_bf16 v[78:81], v[146:149], v[210:213], v[78:81]
	v_mfma_f32_16x16x32_bf16 v[70:73], v[154:157], v[210:213], v[70:73]
	v_mfma_f32_16x16x32_bf16 v[54:57], v[150:153], v[190:193], v[54:57]
	v_mfma_f32_16x16x32_bf16 v[34:37], v[158:161], v[190:193], v[34:37]
	v_mfma_f32_16x16x32_bf16 v[42:45], v[150:153], v[198:201], v[42:45]
	v_mfma_f32_16x16x32_bf16 v[30:33], v[158:161], v[198:201], v[30:33]
	v_mfma_f32_16x16x32_bf16 v[62:65], v[150:153], v[206:209], v[62:65]
	v_mfma_f32_16x16x32_bf16 v[50:53], v[158:161], v[206:209], v[50:53]
	v_mfma_f32_16x16x32_bf16 v[78:81], v[150:153], v[214:217], v[78:81]
	v_mfma_f32_16x16x32_bf16 v[70:73], v[158:161], v[214:217], v[70:73]
	s_setprio 0
	s_setprio 1
	v_mfma_f32_16x16x32_bf16 v[10:13], v[162:165], v[186:189], v[10:13]
	v_mfma_f32_16x16x32_bf16 v[2:5], v[170:173], v[186:189], v[2:5]
	v_mfma_f32_16x16x32_bf16 v[14:17], v[162:165], v[194:197], v[14:17]
	v_mfma_f32_16x16x32_bf16 v[6:9], v[170:173], v[194:197], v[6:9]
	v_mfma_f32_16x16x32_bf16 v[22:25], v[162:165], v[202:205], v[22:25]
	v_mfma_f32_16x16x32_bf16 v[18:21], v[170:173], v[202:205], v[18:21]
	v_mfma_f32_16x16x32_bf16 v[38:41], v[162:165], v[210:213], v[38:41]
	v_mfma_f32_16x16x32_bf16 v[26:29], v[170:173], v[210:213], v[26:29]
	v_mfma_f32_16x16x32_bf16 v[10:13], v[166:169], v[190:193], v[10:13]
	v_mfma_f32_16x16x32_bf16 v[2:5], v[174:177], v[190:193], v[2:5]
	v_mfma_f32_16x16x32_bf16 v[14:17], v[166:169], v[198:201], v[14:17]
	v_mfma_f32_16x16x32_bf16 v[6:9], v[174:177], v[198:201], v[6:9]
	v_mfma_f32_16x16x32_bf16 v[22:25], v[166:169], v[206:209], v[22:25]
	v_mfma_f32_16x16x32_bf16 v[18:21], v[174:177], v[206:209], v[18:21]
	v_mfma_f32_16x16x32_bf16 v[38:41], v[166:169], v[214:217], v[38:41]
	v_mfma_f32_16x16x32_bf16 v[26:29], v[174:177], v[214:217], v[26:29]
	s_barrier
	s_setprio 0
	s_mov_b32 m0, s45
	s_add_u32 s54, s20, 0x100000
	ds_read_b128 v[186:189], v143 offset:16384
	ds_read_b128 v[190:193], v143 offset:17408
	global_load_lds_dwordx4 v132, s[20:21]
	ds_read_b128 v[194:197], v143 offset:18432
	s_mov_b32 m0, s46
	s_addc_u32 s55, s21, 0
	global_load_lds_dwordx4 v136, s[20:21]
	ds_read_b128 v[198:201], v143 offset:19456
	s_mov_b32 m0, s47
	s_nop 0
	global_load_lds_dwordx4 v132, s[54:55]
	ds_read_b128 v[202:205], v143 offset:20480
	s_mov_b32 m0, s48
	s_nop 0
	global_load_lds_dwordx4 v136, s[54:55]
	ds_read_b128 v[206:209], v143 offset:21504
	s_add_u32 s58, s22, s4
	s_addc_u32 s59, s23, s5
	s_mov_b32 m0, s28
	s_nop 0
	global_load_lds_dwordx4 v130, s[22:23]
	ds_read_b128 v[210:213], v143 offset:22528
	s_mov_b32 m0, s29
	s_nop 0
	global_load_lds_dwordx4 v134, s[22:23]
	ds_read_b128 v[214:217], v143 offset:23552
	s_waitcnt vmcnt(8) lgkmcnt(0)
	s_barrier
	s_setprio 1
	v_mfma_f32_16x16x32_bf16 v[94:97], v[146:149], v[186:189], v[94:97]
	v_mfma_f32_16x16x32_bf16 v[86:89], v[154:157], v[186:189], v[86:89]
	v_mfma_f32_16x16x32_bf16 v[102:105], v[146:149], v[194:197], v[102:105]
	v_mfma_f32_16x16x32_bf16 v[98:101], v[154:157], v[194:197], v[98:101]
	v_mfma_f32_16x16x32_bf16 v[110:113], v[146:149], v[202:205], v[110:113]
	v_mfma_f32_16x16x32_bf16 v[106:109], v[154:157], v[202:205], v[106:109]
	v_mfma_f32_16x16x32_bf16 v[126:129], v[146:149], v[210:213], v[126:129]
	v_mfma_f32_16x16x32_bf16 v[122:125], v[154:157], v[210:213], v[122:125]
	v_mfma_f32_16x16x32_bf16 v[94:97], v[150:153], v[190:193], v[94:97]
	v_mfma_f32_16x16x32_bf16 v[86:89], v[158:161], v[190:193], v[86:89]
	v_mfma_f32_16x16x32_bf16 v[102:105], v[150:153], v[198:201], v[102:105]
	v_mfma_f32_16x16x32_bf16 v[98:101], v[158:161], v[198:201], v[98:101]
	v_mfma_f32_16x16x32_bf16 v[110:113], v[150:153], v[206:209], v[110:113]
	v_mfma_f32_16x16x32_bf16 v[106:109], v[158:161], v[206:209], v[106:109]
	v_mfma_f32_16x16x32_bf16 v[126:129], v[150:153], v[214:217], v[126:129]
	v_mfma_f32_16x16x32_bf16 v[122:125], v[158:161], v[214:217], v[122:125]
	s_setprio 0
	s_setprio 1
	v_mfma_f32_16x16x32_bf16 v[58:61], v[162:165], v[186:189], v[58:61]
	v_mfma_f32_16x16x32_bf16 v[46:49], v[170:173], v[186:189], v[46:49]
	v_mfma_f32_16x16x32_bf16 v[74:77], v[162:165], v[194:197], v[74:77]
	v_mfma_f32_16x16x32_bf16 v[66:69], v[170:173], v[194:197], v[66:69]
	v_mfma_f32_16x16x32_bf16 v[90:93], v[162:165], v[202:205], v[90:93]
	v_mfma_f32_16x16x32_bf16 v[82:85], v[170:173], v[202:205], v[82:85]
	v_mfma_f32_16x16x32_bf16 v[118:121], v[162:165], v[210:213], v[118:121]
	v_mfma_f32_16x16x32_bf16 v[114:117], v[170:173], v[210:213], v[114:117]
	v_mfma_f32_16x16x32_bf16 v[58:61], v[166:169], v[190:193], v[58:61]
	v_mfma_f32_16x16x32_bf16 v[46:49], v[174:177], v[190:193], v[46:49]
	v_mfma_f32_16x16x32_bf16 v[74:77], v[166:169], v[198:201], v[74:77]
	v_mfma_f32_16x16x32_bf16 v[66:69], v[174:177], v[198:201], v[66:69]
	v_mfma_f32_16x16x32_bf16 v[90:93], v[166:169], v[206:209], v[90:93]
	v_mfma_f32_16x16x32_bf16 v[82:85], v[174:177], v[206:209], v[82:85]
	v_mfma_f32_16x16x32_bf16 v[118:121], v[166:169], v[214:217], v[118:121]
	v_mfma_f32_16x16x32_bf16 v[114:117], v[174:177], v[214:217], v[114:117]
	s_barrier
; #define PG8_STAGE(bufoff, gbase, voff) do { _Pragma("unroll") for (int _i = 0; _i < 2; ++_i) \
;         __builtin_amdgcn_global_load_lds((const unsigned*)((const char*)(gbase) + (voff)[_i]), (LAS unsigned*)(lds + (bufoff) + ldsw + _i * 8192), 16, 0, 0); } while (0)
; #define PG8_LDA(dst, b, h) do { _Pragma("unroll") for (int m = 0; m < 4; ++m) _Pragma("unroll") for (int k = 0; k < 2; ++k) dst[m][k] = *(const LAS bf16x8*)(lds + PG8_SA(b, h) + aoff + m * 2048 + k * 1024); } while (0)
; #define PG8_LDB(dst, b, h) do { _Pragma("unroll") for (int n = 0; n < 2; ++n) _Pragma("unroll") for (int k = 0; k < 2; ++k) dst[n][k] = *(const LAS bf16x8*)(lds + PG8_SB(b, h) + boff + n * 2048 + k * 1024); } while (0)
; #define PG8_MMA(ai, bj, At, Bt) do { __builtin_amdgcn_s_setprio(1); _Pragma("unroll") for (int m = 0; m < 4; ++m) _Pragma("unroll") for (int n = 0; n < 2; ++n) _Pragma("unroll") for (int k = 0; k < 2; ++k) \
;         acc[ai][bj][m][n] = __builtin_amdgcn_mfma_f32_16x16x32_bf16(Bt[n][k], At[m][k], acc[ai][bj][m][n], 0, 0, 0); __builtin_amdgcn_s_setprio(0); } while (0)
; #define PG8_WAIT_V(n) asm volatile("s_waitcnt vmcnt(" #n ")" ::: "memory")
; #define PG8_WAIT_L(n) asm volatile("s_waitcnt lgkmcnt(" #n ")" ::: "memory")
; #define PG8_BAR __builtin_amdgcn_s_barrier()
; #define PG8_SCHED __builtin_amdgcn_sched_barrier(0)
; template <class Epi, class Sched, bool ALIGN_EPI, class Hook = NoHook>
; __device__ __forceinline__ void gemm_phase(LAS unsigned char* lds, const Gemm g, const Sched& S, const Epi& E, const Hook& H = Hook()) {
;     ...
;             PG8_LDB(B0, 1, 0); PG8_LDB(B1, 1, 1); PG8_SCHED; PG8_LDA(At, 1, 0); PG8_STAGE(PG8_SA(0, 1), a2 + hA, voffA);
;             PG8_WAIT_V(8); PG8_WAIT_L(0); PG8_BAR; PG8_MMA(0, 0, At, B0); PG8_MMA(0, 1, At, B1); PG8_BAR; PG8_SCHED;
;             PG8_LDA(At, 1, 1); PG8_STAGE(PG8_SB(1, 0), b3, voffB); PG8_STAGE(PG8_SB(1, 1), b3 + hB, voffB); PG8_STAGE(PG8_SA(1, 0), a3, voffA);
;             PG8_WAIT_V(8); PG8_WAIT_L(0); PG8_BAR; PG8_MMA(1, 0, At, B0); PG8_MMA(1, 1, At, B1); PG8_BAR; PG8_SCHED;
;         }
;         if constexpr (Hook::ON) H.after(te, acc, cur, wr, wc, fr, fq);
;         }
;         if constexpr (ALIGN_EPI) { if (wr == 0) PG8_BAR; }
	s_setprio 0
	ds_read_b128 v[146:149], v144
	ds_read_b128 v[150:153], v144 offset:1024
	s_add_u32 s22, s22, 0x100000
	s_addc_u32 s23, s23, 0
	s_mov_b32 m0, s38
	s_nop 0
	global_load_lds_dwordx4 v130, s[22:23]
	ds_read_b128 v[154:157], v144 offset:2048
	ds_read_b128 v[158:161], v144 offset:3072
	ds_read_b128 v[162:165], v145
	ds_read_b128 v[166:169], v145 offset:1024
	ds_read_b128 v[170:173], v145 offset:2048
	ds_read_b128 v[174:177], v145 offset:3072
	ds_read_b128 v[186:189], v143 offset:32768
	s_mov_b32 m0, s39
	s_nop 0
	global_load_lds_dwordx4 v134, s[22:23]
	ds_read_b128 v[190:193], v143 offset:33792
	ds_read_b128 v[194:197], v143 offset:34816
	ds_read_b128 v[198:201], v143 offset:35840
	ds_read_b128 v[202:205], v143 offset:36864
	ds_read_b128 v[206:209], v143 offset:37888
	ds_read_b128 v[210:213], v143 offset:38912
	ds_read_b128 v[214:217], v143 offset:39936
	s_waitcnt vmcnt(8) lgkmcnt(0)
	s_barrier
	s_setprio 1
	v_mfma_f32_16x16x32_bf16 v[54:57], v[146:149], v[186:189], v[54:57]
	v_mfma_f32_16x16x32_bf16 v[34:37], v[154:157], v[186:189], v[34:37]
	v_mfma_f32_16x16x32_bf16 v[42:45], v[146:149], v[194:197], v[42:45]
	v_mfma_f32_16x16x32_bf16 v[30:33], v[154:157], v[194:197], v[30:33]
	v_mfma_f32_16x16x32_bf16 v[62:65], v[146:149], v[202:205], v[62:65]
	v_mfma_f32_16x16x32_bf16 v[50:53], v[154:157], v[202:205], v[50:53]
	v_mfma_f32_16x16x32_bf16 v[78:81], v[146:149], v[210:213], v[78:81]
	v_mfma_f32_16x16x32_bf16 v[70:73], v[154:157], v[210:213], v[70:73]
	v_mfma_f32_16x16x32_bf16 v[54:57], v[150:153], v[190:193], v[54:57]
	v_mfma_f32_16x16x32_bf16 v[34:37], v[158:161], v[190:193], v[34:37]
	v_mfma_f32_16x16x32_bf16 v[42:45], v[150:153], v[198:201], v[42:45]
	v_mfma_f32_16x16x32_bf16 v[30:33], v[158:161], v[198:201], v[30:33]
	v_mfma_f32_16x16x32_bf16 v[62:65], v[150:153], v[206:209], v[62:65]
	v_mfma_f32_16x16x32_bf16 v[50:53], v[158:161], v[206:209], v[50:53]
	v_mfma_f32_16x16x32_bf16 v[78:81], v[150:153], v[214:217], v[78:81]
	v_mfma_f32_16x16x32_bf16 v[70:73], v[158:161], v[214:217], v[70:73]
	s_setprio 0
	s_setprio 1
	v_mfma_f32_16x16x32_bf16 v[10:13], v[162:165], v[186:189], v[10:13]
	v_mfma_f32_16x16x32_bf16 v[2:5], v[170:173], v[186:189], v[2:5]
	v_mfma_f32_16x16x32_bf16 v[14:17], v[162:165], v[194:197], v[14:17]
	v_mfma_f32_16x16x32_bf16 v[6:9], v[170:173], v[194:197], v[6:9]
	v_mfma_f32_16x16x32_bf16 v[22:25], v[162:165], v[202:205], v[22:25]
	v_mfma_f32_16x16x32_bf16 v[18:21], v[170:173], v[202:205], v[18:21]
	v_mfma_f32_16x16x32_bf16 v[38:41], v[162:165], v[210:213], v[38:41]
	v_mfma_f32_16x16x32_bf16 v[26:29], v[170:173], v[210:213], v[26:29]
	v_mfma_f32_16x16x32_bf16 v[10:13], v[166:169], v[190:193], v[10:13]
	v_mfma_f32_16x16x32_bf16 v[2:5], v[174:177], v[190:193], v[2:5]
	v_mfma_f32_16x16x32_bf16 v[14:17], v[166:169], v[198:201], v[14:17]
	v_mfma_f32_16x16x32_bf16 v[6:9], v[174:177], v[198:201], v[6:9]
	v_mfma_f32_16x16x32_bf16 v[22:25], v[166:169], v[206:209], v[22:25]
	v_mfma_f32_16x16x32_bf16 v[18:21], v[174:177], v[206:209], v[18:21]
	v_mfma_f32_16x16x32_bf16 v[38:41], v[166:169], v[214:217], v[38:41]
	v_mfma_f32_16x16x32_bf16 v[26:29], v[174:177], v[214:217], v[26:29]
	s_barrier
	s_setprio 0
	s_mov_b32 m0, s49
	s_add_u32 s56, s20, s4
	s_addc_u32 s57, s21, s5
	s_add_u32 s20, s20, 0x100080
	ds_read_b128 v[186:189], v143 offset:49152
	ds_read_b128 v[190:193], v143 offset:50176
	global_load_lds_dwordx4 v132, s[56:57]
	ds_read_b128 v[194:197], v143 offset:51200
	s_mov_b32 m0, s50
	s_addc_u32 s21, s21, 0
	global_load_lds_dwordx4 v136, s[56:57]
	ds_read_b128 v[198:201], v143 offset:52224
	s_mov_b32 m0, s51
	s_nop 0
	global_load_lds_dwordx4 v132, s[20:21]
	ds_read_b128 v[202:205], v143 offset:53248
	s_mov_b32 m0, s52
	s_nop 0
	global_load_lds_dwordx4 v136, s[20:21]
	ds_read_b128 v[206:209], v143 offset:54272
	s_mov_b32 m0, s40
	s_nop 0
	global_load_lds_dwordx4 v130, s[58:59]
	ds_read_b128 v[210:213], v143 offset:55296
	s_mov_b32 m0, s41
	s_nop 0
	global_load_lds_dwordx4 v134, s[58:59]
	ds_read_b128 v[214:217], v143 offset:56320
	s_waitcnt vmcnt(8) lgkmcnt(0)
	s_barrier
	s_setprio 1
	v_mfma_f32_16x16x32_bf16 v[94:97], v[146:149], v[186:189], v[94:97]
	v_mfma_f32_16x16x32_bf16 v[86:89], v[154:157], v[186:189], v[86:89]
	v_mfma_f32_16x16x32_bf16 v[102:105], v[146:149], v[194:197], v[102:105]
	v_mfma_f32_16x16x32_bf16 v[98:101], v[154:157], v[194:197], v[98:101]
	v_mfma_f32_16x16x32_bf16 v[110:113], v[146:149], v[202:205], v[110:113]
	v_mfma_f32_16x16x32_bf16 v[106:109], v[154:157], v[202:205], v[106:109]
	v_mfma_f32_16x16x32_bf16 v[126:129], v[146:149], v[210:213], v[126:129]
	v_mfma_f32_16x16x32_bf16 v[122:125], v[154:157], v[210:213], v[122:125]
	v_mfma_f32_16x16x32_bf16 v[94:97], v[150:153], v[190:193], v[94:97]
	v_mfma_f32_16x16x32_bf16 v[86:89], v[158:161], v[190:193], v[86:89]
	v_mfma_f32_16x16x32_bf16 v[102:105], v[150:153], v[198:201], v[102:105]
	v_mfma_f32_16x16x32_bf16 v[98:101], v[158:161], v[198:201], v[98:101]
	v_mfma_f32_16x16x32_bf16 v[110:113], v[150:153], v[206:209], v[110:113]
	v_mfma_f32_16x16x32_bf16 v[106:109], v[158:161], v[206:209], v[106:109]
	v_mfma_f32_16x16x32_bf16 v[126:129], v[150:153], v[214:217], v[126:129]
	v_mfma_f32_16x16x32_bf16 v[122:125], v[158:161], v[214:217], v[122:125]
	s_setprio 0
	s_setprio 1
	v_mfma_f32_16x16x32_bf16 v[58:61], v[162:165], v[186:189], v[58:61]
	v_mfma_f32_16x16x32_bf16 v[46:49], v[170:173], v[186:189], v[46:49]
	v_mfma_f32_16x16x32_bf16 v[74:77], v[162:165], v[194:197], v[74:77]
	v_mfma_f32_16x16x32_bf16 v[66:69], v[170:173], v[194:197], v[66:69]
	v_mfma_f32_16x16x32_bf16 v[90:93], v[162:165], v[202:205], v[90:93]
	v_mfma_f32_16x16x32_bf16 v[82:85], v[170:173], v[202:205], v[82:85]
	v_mfma_f32_16x16x32_bf16 v[118:121], v[162:165], v[210:213], v[118:121]
	v_mfma_f32_16x16x32_bf16 v[114:117], v[170:173], v[210:213], v[114:117]
	v_mfma_f32_16x16x32_bf16 v[58:61], v[166:169], v[190:193], v[58:61]
	v_mfma_f32_16x16x32_bf16 v[46:49], v[174:177], v[190:193], v[46:49]
	v_mfma_f32_16x16x32_bf16 v[74:77], v[166:169], v[198:201], v[74:77]
	v_mfma_f32_16x16x32_bf16 v[66:69], v[174:177], v[198:201], v[66:69]
	v_mfma_f32_16x16x32_bf16 v[90:93], v[166:169], v[206:209], v[90:93]
	v_mfma_f32_16x16x32_bf16 v[82:85], v[174:177], v[206:209], v[82:85]
	v_mfma_f32_16x16x32_bf16 v[118:121], v[166:169], v[214:217], v[118:121]
	v_mfma_f32_16x16x32_bf16 v[114:117], v[174:177], v[214:217], v[114:117]
	s_barrier
	s_setprio 0
	s_add_i32 s42, s42, 2
	s_add_u32 s6, s6, 0x100
	s_addc_u32 s7, s7, 0
	s_cmp_gt_u32 s42, 61
	s_cbranch_scc0 .LBB0_850
	s_cmpk_lt_u32 s26, 0x100
	s_cbranch_scc0 .LBB0_853
	s_barrier

; #define PG8_STAGE(bufoff, gbase, voff) do { _Pragma("unroll") for (int _i = 0; _i < 2; ++_i) \
;         __builtin_amdgcn_global_load_lds((const unsigned*)((const char*)(gbase) + (voff)[_i]), (LAS unsigned*)(lds + (bufoff) + ldsw + _i * 8192), 16, 0, 0); } while (0)
; #define PG8_LDA(dst, b, h) do { _Pragma("unroll") for (int m = 0; m < 4; ++m) _Pragma("unroll") for (int k = 0; k < 2; ++k) dst[m][k] = *(const LAS bf16x8*)(lds + PG8_SA(b, h) + aoff + m * 2048 + k * 1024); } while (0)
; #define PG8_LDB(dst, b, h) do { _Pragma("unroll") for (int n = 0; n < 2; ++n) _Pragma("unroll") for (int k = 0; k < 2; ++k) dst[n][k] = *(const LAS bf16x8*)(lds + PG8_SB(b, h) + boff + n * 2048 + k * 1024); } while (0)
; #define PG8_MMA(ai, bj, At, Bt) do { __builtin_amdgcn_s_setprio(1); _Pragma("unroll") for (int m = 0; m < 4; ++m) _Pragma("unroll") for (int n = 0; n < 2; ++n) _Pragma("unroll") for (int k = 0; k < 2; ++k) \
;         acc[ai][bj][m][n] = __builtin_amdgcn_mfma_f32_16x16x32_bf16(Bt[n][k], At[m][k], acc[ai][bj][m][n], 0, 0, 0); __builtin_amdgcn_s_setprio(0); } while (0)
; #define PG8_WAIT_V(n) asm volatile("s_waitcnt vmcnt(" #n ")" ::: "memory")
; #define PG8_WAIT_L(n) asm volatile("s_waitcnt lgkmcnt(" #n ")" ::: "memory")
; #define PG8_BAR __builtin_amdgcn_s_barrier()
; #define PG8_SCHED __builtin_amdgcn_sched_barrier(0)
; template <class Epi, class Sched, bool ALIGN_EPI, class Hook = NoHook>
; __device__ __forceinline__ void gemm_phase(LAS unsigned char* lds, const Gemm g, const Sched& S, const Epi& E, const Hook& H = Hook()) {
;     ...
;             const char* a1 = cA + (size_t)(t + 1) * kstep;
;             const char* a2 = last ? nA : cA + (size_t)(t + 2) * kstep; const char* b2 = last ? nB : cB + (size_t)(t + 2) * kstep;
;             const char* a3 = a2 + kstep; const char* b3 = b2 + kstep;
;             if (last && has_next) S.a_ready(nxt);
;             PG8_LDB(B0, 0, 0); PG8_LDB(B1, 0, 1); PG8_SCHED; PG8_LDA(At, 0, 0); PG8_STAGE(PG8_SA(1, 1), a1 + hA, voffA);
;             PG8_WAIT_V(8); PG8_WAIT_L(0); PG8_BAR; PG8_MMA(0, 0, At, B0); PG8_MMA(0, 1, At, B1); PG8_BAR; PG8_SCHED;
;             PG8_LDA(At, 0, 1); PG8_STAGE(PG8_SB(0, 0), b2, voffB); PG8_STAGE(PG8_SB(0, 1), b2 + hB, voffB); PG8_STAGE(PG8_SA(0, 0), a2, voffA);
;             PG8_WAIT_V(8); PG8_WAIT_L(0); PG8_BAR; PG8_MMA(1, 0, At, B0); PG8_MMA(1, 1, At, B1); PG8_BAR; PG8_SCHED;
.LBB0_896:
	ds_read_b128 v[146:149], v140
	ds_read_b128 v[150:153], v140 offset:1024
	s_add_u32 s10, s6, 0x87c00080
	s_addc_u32 s11, s7, -1
	s_cmp_lg_u32 s18, 60
	s_cselect_b32 s10, s10, 0
	s_cselect_b32 s11, s11, 0
	s_add_u32 s16, s2, s10
	s_addc_u32 s17, s3, s11
	s_add_u32 s10, s14, s10
	s_addc_u32 s11, s15, s11
	s_mov_b32 m0, s19
	ds_read_b128 v[154:157], v140 offset:2048
	ds_read_b128 v[158:161], v140 offset:3072
	ds_read_b128 v[162:165], v141
	ds_read_b128 v[166:169], v141 offset:1024
	ds_read_b128 v[170:173], v141 offset:2048
	ds_read_b128 v[174:177], v141 offset:3072
	v_lshl_add_u64 v[178:179], v[136:137], 0, s[6:7]
	global_load_lds_dwordx4 v[178:179], off
	ds_read_b128 v[186:189], v142
	ds_read_b128 v[190:193], v142 offset:1024
	ds_read_b128 v[194:197], v142 offset:2048
	ds_read_b128 v[198:201], v142 offset:3072
	ds_read_b128 v[202:205], v142 offset:4096
	ds_read_b128 v[206:209], v142 offset:5120
	ds_read_b128 v[210:213], v142 offset:6144
	ds_read_b128 v[214:217], v142 offset:7168
	v_lshl_add_u64 v[178:179], v[138:139], 0, s[6:7]
	s_mov_b32 m0, s31
	s_nop 0
	global_load_lds_dwordx4 v[178:179], off
	s_waitcnt vmcnt(8) lgkmcnt(0)
	s_barrier
	s_setprio 1
	v_mfma_f32_16x16x32_bf16 v[54:57], v[146:149], v[186:189], v[54:57]
	v_mfma_f32_16x16x32_bf16 v[34:37], v[154:157], v[186:189], v[34:37]
	v_mfma_f32_16x16x32_bf16 v[42:45], v[146:149], v[194:197], v[42:45]
	v_mfma_f32_16x16x32_bf16 v[30:33], v[154:157], v[194:197], v[30:33]
	v_mfma_f32_16x16x32_bf16 v[62:65], v[146:149], v[202:205], v[62:65]
	v_mfma_f32_16x16x32_bf16 v[50:53], v[154:157], v[202:205], v[50:53]
	v_mfma_f32_16x16x32_bf16 v[78:81], v[146:149], v[210:213], v[78:81]
	v_mfma_f32_16x16x32_bf16 v[70:73], v[154:157], v[210:213], v[70:73]
	v_mfma_f32_16x16x32_bf16 v[54:57], v[150:153], v[190:193], v[54:57]
	v_mfma_f32_16x16x32_bf16 v[34:37], v[158:161], v[190:193], v[34:37]
	v_mfma_f32_16x16x32_bf16 v[42:45], v[150:153], v[198:201], v[42:45]
	v_mfma_f32_16x16x32_bf16 v[30:33], v[158:161], v[198:201], v[30:33]
	v_mfma_f32_16x16x32_bf16 v[62:65], v[150:153], v[206:209], v[62:65]
	v_mfma_f32_16x16x32_bf16 v[50:53], v[158:161], v[206:209], v[50:53]
	v_mfma_f32_16x16x32_bf16 v[78:81], v[150:153], v[214:217], v[78:81]
	v_mfma_f32_16x16x32_bf16 v[70:73], v[158:161], v[214:217], v[70:73]
	s_setprio 0
	s_setprio 1
	v_mfma_f32_16x16x32_bf16 v[10:13], v[162:165], v[186:189], v[10:13]
	v_mfma_f32_16x16x32_bf16 v[2:5], v[170:173], v[186:189], v[2:5]
	v_mfma_f32_16x16x32_bf16 v[14:17], v[162:165], v[194:197], v[14:17]
	v_mfma_f32_16x16x32_bf16 v[6:9], v[170:173], v[194:197], v[6:9]
	v_mfma_f32_16x16x32_bf16 v[22:25], v[162:165], v[202:205], v[22:25]
	v_mfma_f32_16x16x32_bf16 v[18:21], v[170:173], v[202:205], v[18:21]
	v_mfma_f32_16x16x32_bf16 v[38:41], v[162:165], v[210:213], v[38:41]
	v_mfma_f32_16x16x32_bf16 v[26:29], v[170:173], v[210:213], v[26:29]
	v_mfma_f32_16x16x32_bf16 v[10:13], v[166:169], v[190:193], v[10:13]
	v_mfma_f32_16x16x32_bf16 v[2:5], v[174:177], v[190:193], v[2:5]
	v_mfma_f32_16x16x32_bf16 v[14:17], v[166:169], v[198:201], v[14:17]
	v_mfma_f32_16x16x32_bf16 v[6:9], v[174:177], v[198:201], v[6:9]
	v_mfma_f32_16x16x32_bf16 v[22:25], v[166:169], v[206:209], v[22:25]
	v_mfma_f32_16x16x32_bf16 v[18:21], v[174:177], v[206:209], v[18:21]
	v_mfma_f32_16x16x32_bf16 v[38:41], v[166:169], v[214:217], v[38:41]
	v_mfma_f32_16x16x32_bf16 v[26:29], v[174:177], v[214:217], v[26:29]
	s_barrier
	s_setprio 0
	s_mov_b32 m0, s33
	s_add_u32 s46, s10, 0x100000
	ds_read_b128 v[186:189], v142 offset:16384
	ds_read_b128 v[190:193], v142 offset:17408
	global_load_lds_dwordx4 v180, s[10:11]
	ds_read_b128 v[194:197], v142 offset:18432
	s_mov_b32 m0, s34
	s_addc_u32 s47, s11, 0
	global_load_lds_dwordx4 v134, s[10:11]
	ds_read_b128 v[198:201], v142 offset:19456
	s_mov_b32 m0, s35
	s_nop 0
	global_load_lds_dwordx4 v180, s[46:47]
	ds_read_b128 v[202:205], v142 offset:20480
	s_mov_b32 m0, s42
	s_nop 0
	global_load_lds_dwordx4 v134, s[46:47]
	ds_read_b128 v[206:209], v142 offset:21504
	s_add_u32 s50, s16, s4
	s_addc_u32 s51, s17, s5
	s_mov_b32 m0, s27
	s_nop 0
	global_load_lds_dwordx4 v130, s[16:17]
	ds_read_b128 v[210:213], v142 offset:22528
	s_mov_b32 m0, s28
	s_nop 0
	global_load_lds_dwordx4 v132, s[16:17]
	ds_read_b128 v[214:217], v142 offset:23552
	s_waitcnt vmcnt(8) lgkmcnt(0)
	s_barrier
	s_setprio 1
	v_mfma_f32_16x16x32_bf16 v[94:97], v[146:149], v[186:189], v[94:97]
	v_mfma_f32_16x16x32_bf16 v[86:89], v[154:157], v[186:189], v[86:89]
	v_mfma_f32_16x16x32_bf16 v[102:105], v[146:149], v[194:197], v[102:105]
	v_mfma_f32_16x16x32_bf16 v[98:101], v[154:157], v[194:197], v[98:101]
	v_mfma_f32_16x16x32_bf16 v[110:113], v[146:149], v[202:205], v[110:113]
	v_mfma_f32_16x16x32_bf16 v[106:109], v[154:157], v[202:205], v[106:109]
	v_mfma_f32_16x16x32_bf16 v[126:129], v[146:149], v[210:213], v[126:129]
	v_mfma_f32_16x16x32_bf16 v[122:125], v[154:157], v[210:213], v[122:125]
	v_mfma_f32_16x16x32_bf16 v[94:97], v[150:153], v[190:193], v[94:97]
	v_mfma_f32_16x16x32_bf16 v[86:89], v[158:161], v[190:193], v[86:89]
	v_mfma_f32_16x16x32_bf16 v[102:105], v[150:153], v[198:201], v[102:105]
	v_mfma_f32_16x16x32_bf16 v[98:101], v[158:161], v[198:201], v[98:101]
	v_mfma_f32_16x16x32_bf16 v[110:113], v[150:153], v[206:209], v[110:113]
	v_mfma_f32_16x16x32_bf16 v[106:109], v[158:161], v[206:209], v[106:109]
	v_mfma_f32_16x16x32_bf16 v[126:129], v[150:153], v[214:217], v[126:129]
	v_mfma_f32_16x16x32_bf16 v[122:125], v[158:161], v[214:217], v[122:125]
	s_setprio 0
	s_setprio 1
	v_mfma_f32_16x16x32_bf16 v[58:61], v[162:165], v[186:189], v[58:61]
	v_mfma_f32_16x16x32_bf16 v[46:49], v[170:173], v[186:189], v[46:49]
	v_mfma_f32_16x16x32_bf16 v[74:77], v[162:165], v[194:197], v[74:77]
	v_mfma_f32_16x16x32_bf16 v[66:69], v[170:173], v[194:197], v[66:69]
	v_mfma_f32_16x16x32_bf16 v[90:93], v[162:165], v[202:205], v[90:93]
	v_mfma_f32_16x16x32_bf16 v[82:85], v[170:173], v[202:205], v[82:85]
	v_mfma_f32_16x16x32_bf16 v[118:121], v[162:165], v[210:213], v[118:121]
	v_mfma_f32_16x16x32_bf16 v[114:117], v[170:173], v[210:213], v[114:117]
	v_mfma_f32_16x16x32_bf16 v[58:61], v[166:169], v[190:193], v[58:61]
	v_mfma_f32_16x16x32_bf16 v[46:49], v[174:177], v[190:193], v[46:49]
	v_mfma_f32_16x16x32_bf16 v[74:77], v[166:169], v[198:201], v[74:77]
	v_mfma_f32_16x16x32_bf16 v[66:69], v[174:177], v[198:201], v[66:69]
	v_mfma_f32_16x16x32_bf16 v[90:93], v[166:169], v[206:209], v[90:93]
	v_mfma_f32_16x16x32_bf16 v[82:85], v[174:177], v[206:209], v[82:85]
	v_mfma_f32_16x16x32_bf16 v[118:121], v[166:169], v[214:217], v[118:121]
	v_mfma_f32_16x16x32_bf16 v[114:117], v[174:177], v[214:217], v[114:117]
	s_barrier
; #define PG8_STAGE(bufoff, gbase, voff) do { _Pragma("unroll") for (int _i = 0; _i < 2; ++_i) \
;         __builtin_amdgcn_global_load_lds((const unsigned*)((const char*)(gbase) + (voff)[_i]), (LAS unsigned*)(lds + (bufoff) + ldsw + _i * 8192), 16, 0, 0); } while (0)
; #define PG8_LDA(dst, b, h) do { _Pragma("unroll") for (int m = 0; m < 4; ++m) _Pragma("unroll") for (int k = 0; k < 2; ++k) dst[m][k] = *(const LAS bf16x8*)(lds + PG8_SA(b, h) + aoff + m * 2048 + k * 1024); } while (0)
; #define PG8_LDB(dst, b, h) do { _Pragma("unroll") for (int n = 0; n < 2; ++n) _Pragma("unroll") for (int k = 0; k < 2; ++k) dst[n][k] = *(const LAS bf16x8*)(lds + PG8_SB(b, h) + boff + n * 2048 + k * 1024); } while (0)
; #define PG8_MMA(ai, bj, At, Bt) do { __builtin_amdgcn_s_setprio(1); _Pragma("unroll") for (int m = 0; m < 4; ++m) _Pragma("unroll") for (int n = 0; n < 2; ++n) _Pragma("unroll") for (int k = 0; k < 2; ++k) \
;         acc[ai][bj][m][n] = __builtin_amdgcn_mfma_f32_16x16x32_bf16(Bt[n][k], At[m][k], acc[ai][bj][m][n], 0, 0, 0); __builtin_amdgcn_s_setprio(0); } while (0)
; #define PG8_WAIT_V(n) asm volatile("s_waitcnt vmcnt(" #n ")" ::: "memory")
; #define PG8_WAIT_L(n) asm volatile("s_waitcnt lgkmcnt(" #n ")" ::: "memory")
; #define PG8_BAR __builtin_amdgcn_s_barrier()
; #define PG8_SCHED __builtin_amdgcn_sched_barrier(0)
; template <class Epi, class Sched, bool ALIGN_EPI, class Hook = NoHook>
; __device__ __forceinline__ void gemm_phase(LAS unsigned char* lds, const Gemm g, const Sched& S, const Epi& E, const Hook& H = Hook()) {
;     ...
;             PG8_LDB(B0, 1, 0); PG8_LDB(B1, 1, 1); PG8_SCHED; PG8_LDA(At, 1, 0); PG8_STAGE(PG8_SA(0, 1), a2 + hA, voffA);
;             PG8_WAIT_V(8); PG8_WAIT_L(0); PG8_BAR; PG8_MMA(0, 0, At, B0); PG8_MMA(0, 1, At, B1); PG8_BAR; PG8_SCHED;
;             PG8_LDA(At, 1, 1); PG8_STAGE(PG8_SB(1, 0), b3, voffB); PG8_STAGE(PG8_SB(1, 1), b3 + hB, voffB); PG8_STAGE(PG8_SA(1, 0), a3, voffA);
;             PG8_WAIT_V(8); PG8_WAIT_L(0); PG8_BAR; PG8_MMA(1, 0, At, B0); PG8_MMA(1, 1, At, B1); PG8_BAR; PG8_SCHED;
;         }
;         if constexpr (Hook::ON) H.after(te, acc, cur, wr, wc, fr, fq);
;         }
;         if constexpr (ALIGN_EPI) { if (wr == 0) PG8_BAR; }
	s_setprio 0
	ds_read_b128 v[146:149], v143
	ds_read_b128 v[150:153], v143 offset:1024
	s_add_u32 s16, s16, 0x100000
	s_addc_u32 s17, s17, 0
	s_mov_b32 m0, s29
	s_nop 0
	global_load_lds_dwordx4 v130, s[16:17]
	ds_read_b128 v[154:157], v143 offset:2048
	ds_read_b128 v[158:161], v143 offset:3072
	ds_read_b128 v[162:165], v144
	ds_read_b128 v[166:169], v144 offset:1024
	ds_read_b128 v[170:173], v144 offset:2048
	ds_read_b128 v[174:177], v144 offset:3072
	ds_read_b128 v[186:189], v142 offset:32768
	s_mov_b32 m0, s39
	s_nop 0
	global_load_lds_dwordx4 v132, s[16:17]
	ds_read_b128 v[190:193], v142 offset:33792
	ds_read_b128 v[194:197], v142 offset:34816
	ds_read_b128 v[198:201], v142 offset:35840
	ds_read_b128 v[202:205], v142 offset:36864
	ds_read_b128 v[206:209], v142 offset:37888
	ds_read_b128 v[210:213], v142 offset:38912
	ds_read_b128 v[214:217], v142 offset:39936
	s_waitcnt vmcnt(8) lgkmcnt(0)
	s_barrier
	s_setprio 1
	v_mfma_f32_16x16x32_bf16 v[54:57], v[146:149], v[186:189], v[54:57]
	v_mfma_f32_16x16x32_bf16 v[34:37], v[154:157], v[186:189], v[34:37]
	v_mfma_f32_16x16x32_bf16 v[42:45], v[146:149], v[194:197], v[42:45]
	v_mfma_f32_16x16x32_bf16 v[30:33], v[154:157], v[194:197], v[30:33]
	v_mfma_f32_16x16x32_bf16 v[62:65], v[146:149], v[202:205], v[62:65]
	v_mfma_f32_16x16x32_bf16 v[50:53], v[154:157], v[202:205], v[50:53]
	v_mfma_f32_16x16x32_bf16 v[78:81], v[146:149], v[210:213], v[78:81]
	v_mfma_f32_16x16x32_bf16 v[70:73], v[154:157], v[210:213], v[70:73]
	v_mfma_f32_16x16x32_bf16 v[54:57], v[150:153], v[190:193], v[54:57]
	v_mfma_f32_16x16x32_bf16 v[34:37], v[158:161], v[190:193], v[34:37]
	v_mfma_f32_16x16x32_bf16 v[42:45], v[150:153], v[198:201], v[42:45]
	v_mfma_f32_16x16x32_bf16 v[30:33], v[158:161], v[198:201], v[30:33]
	v_mfma_f32_16x16x32_bf16 v[62:65], v[150:153], v[206:209], v[62:65]
	v_mfma_f32_16x16x32_bf16 v[50:53], v[158:161], v[206:209], v[50:53]
	v_mfma_f32_16x16x32_bf16 v[78:81], v[150:153], v[214:217], v[78:81]
	v_mfma_f32_16x16x32_bf16 v[70:73], v[158:161], v[214:217], v[70:73]
	s_setprio 0
	s_setprio 1
	v_mfma_f32_16x16x32_bf16 v[10:13], v[162:165], v[186:189], v[10:13]
	v_mfma_f32_16x16x32_bf16 v[2:5], v[170:173], v[186:189], v[2:5]
	v_mfma_f32_16x16x32_bf16 v[14:17], v[162:165], v[194:197], v[14:17]
	v_mfma_f32_16x16x32_bf16 v[6:9], v[170:173], v[194:197], v[6:9]
	v_mfma_f32_16x16x32_bf16 v[22:25], v[162:165], v[202:205], v[22:25]
	v_mfma_f32_16x16x32_bf16 v[18:21], v[170:173], v[202:205], v[18:21]
	v_mfma_f32_16x16x32_bf16 v[38:41], v[162:165], v[210:213], v[38:41]
	v_mfma_f32_16x16x32_bf16 v[26:29], v[170:173], v[210:213], v[26:29]
	v_mfma_f32_16x16x32_bf16 v[10:13], v[166:169], v[190:193], v[10:13]
	v_mfma_f32_16x16x32_bf16 v[2:5], v[174:177], v[190:193], v[2:5]
	v_mfma_f32_16x16x32_bf16 v[14:17], v[166:169], v[198:201], v[14:17]
	v_mfma_f32_16x16x32_bf16 v[6:9], v[174:177], v[198:201], v[6:9]
	v_mfma_f32_16x16x32_bf16 v[22:25], v[166:169], v[206:209], v[22:25]
	v_mfma_f32_16x16x32_bf16 v[18:21], v[174:177], v[206:209], v[18:21]
	v_mfma_f32_16x16x32_bf16 v[38:41], v[166:169], v[214:217], v[38:41]
	v_mfma_f32_16x16x32_bf16 v[26:29], v[174:177], v[214:217], v[26:29]
	s_barrier
	s_setprio 0
	s_mov_b32 m0, s36
	s_add_u32 s48, s10, s4
	s_addc_u32 s49, s11, s5
	s_add_u32 s10, s10, 0x100080
	ds_read_b128 v[186:189], v142 offset:49152
	ds_read_b128 v[190:193], v142 offset:50176
	global_load_lds_dwordx4 v180, s[48:49]
	ds_read_b128 v[194:197], v142 offset:51200
	s_mov_b32 m0, s43
	s_addc_u32 s11, s11, 0
	global_load_lds_dwordx4 v134, s[48:49]
	ds_read_b128 v[198:201], v142 offset:52224
	s_mov_b32 m0, s37
	s_nop 0
	global_load_lds_dwordx4 v180, s[10:11]
	ds_read_b128 v[202:205], v142 offset:53248
	s_mov_b32 m0, s44
	s_nop 0
	global_load_lds_dwordx4 v134, s[10:11]
	ds_read_b128 v[206:209], v142 offset:54272
	s_mov_b32 m0, s40
	s_nop 0
	global_load_lds_dwordx4 v130, s[50:51]
	ds_read_b128 v[210:213], v142 offset:55296
	s_mov_b32 m0, s41
	s_nop 0
	global_load_lds_dwordx4 v132, s[50:51]
	ds_read_b128 v[214:217], v142 offset:56320
	s_waitcnt vmcnt(8) lgkmcnt(0)
	s_barrier
	s_setprio 1
	v_mfma_f32_16x16x32_bf16 v[94:97], v[146:149], v[186:189], v[94:97]
	v_mfma_f32_16x16x32_bf16 v[86:89], v[154:157], v[186:189], v[86:89]
	v_mfma_f32_16x16x32_bf16 v[102:105], v[146:149], v[194:197], v[102:105]
	v_mfma_f32_16x16x32_bf16 v[98:101], v[154:157], v[194:197], v[98:101]
	v_mfma_f32_16x16x32_bf16 v[110:113], v[146:149], v[202:205], v[110:113]
	v_mfma_f32_16x16x32_bf16 v[106:109], v[154:157], v[202:205], v[106:109]
	v_mfma_f32_16x16x32_bf16 v[126:129], v[146:149], v[210:213], v[126:129]
	v_mfma_f32_16x16x32_bf16 v[122:125], v[154:157], v[210:213], v[122:125]
	v_mfma_f32_16x16x32_bf16 v[94:97], v[150:153], v[190:193], v[94:97]
	v_mfma_f32_16x16x32_bf16 v[86:89], v[158:161], v[190:193], v[86:89]
	v_mfma_f32_16x16x32_bf16 v[102:105], v[150:153], v[198:201], v[102:105]
	v_mfma_f32_16x16x32_bf16 v[98:101], v[158:161], v[198:201], v[98:101]
	v_mfma_f32_16x16x32_bf16 v[110:113], v[150:153], v[206:209], v[110:113]
	v_mfma_f32_16x16x32_bf16 v[106:109], v[158:161], v[206:209], v[106:109]
	v_mfma_f32_16x16x32_bf16 v[126:129], v[150:153], v[214:217], v[126:129]
	v_mfma_f32_16x16x32_bf16 v[122:125], v[158:161], v[214:217], v[122:125]
	s_setprio 0
	s_setprio 1
	v_mfma_f32_16x16x32_bf16 v[58:61], v[162:165], v[186:189], v[58:61]
	v_mfma_f32_16x16x32_bf16 v[46:49], v[170:173], v[186:189], v[46:49]
	v_mfma_f32_16x16x32_bf16 v[74:77], v[162:165], v[194:197], v[74:77]
	v_mfma_f32_16x16x32_bf16 v[66:69], v[170:173], v[194:197], v[66:69]
	v_mfma_f32_16x16x32_bf16 v[90:93], v[162:165], v[202:205], v[90:93]
	v_mfma_f32_16x16x32_bf16 v[82:85], v[170:173], v[202:205], v[82:85]
	v_mfma_f32_16x16x32_bf16 v[118:121], v[162:165], v[210:213], v[118:121]
	v_mfma_f32_16x16x32_bf16 v[114:117], v[170:173], v[210:213], v[114:117]
	v_mfma_f32_16x16x32_bf16 v[58:61], v[166:169], v[190:193], v[58:61]
	v_mfma_f32_16x16x32_bf16 v[46:49], v[174:177], v[190:193], v[46:49]
	v_mfma_f32_16x16x32_bf16 v[74:77], v[166:169], v[198:201], v[74:77]
	v_mfma_f32_16x16x32_bf16 v[66:69], v[174:177], v[198:201], v[66:69]
	v_mfma_f32_16x16x32_bf16 v[90:93], v[166:169], v[206:209], v[90:93]
	v_mfma_f32_16x16x32_bf16 v[82:85], v[174:177], v[206:209], v[82:85]
	v_mfma_f32_16x16x32_bf16 v[118:121], v[166:169], v[214:217], v[118:121]
	v_mfma_f32_16x16x32_bf16 v[114:117], v[174:177], v[214:217], v[114:117]
	s_barrier
	s_setprio 0
	s_add_i32 s18, s18, 2
	s_add_u32 s6, s6, 0x100
	s_addc_u32 s7, s7, 0
	s_cmp_gt_u32 s18, 61
	s_cbranch_scc0 .LBB0_896
	s_cmpk_lt_u32 s22, 0x100
	s_cbranch_scc0 .LBB0_899
	s_barrier

; #define PG8_STAGE(bufoff, gbase, voff) do { _Pragma("unroll") for (int _i = 0; _i < 2; ++_i) \
;         __builtin_amdgcn_global_load_lds((const unsigned*)((const char*)(gbase) + (voff)[_i]), (LAS unsigned*)(lds + (bufoff) + ldsw + _i * 8192), 16, 0, 0); } while (0)
; #define PG8_LDA(dst, b, h) do { _Pragma("unroll") for (int m = 0; m < 4; ++m) _Pragma("unroll") for (int k = 0; k < 2; ++k) dst[m][k] = *(const LAS bf16x8*)(lds + PG8_SA(b, h) + aoff + m * 2048 + k * 1024); } while (0)
; #define PG8_LDB(dst, b, h) do { _Pragma("unroll") for (int n = 0; n < 2; ++n) _Pragma("unroll") for (int k = 0; k < 2; ++k) dst[n][k] = *(const LAS bf16x8*)(lds + PG8_SB(b, h) + boff + n * 2048 + k * 1024); } while (0)
; #define PG8_MMA(ai, bj, At, Bt) do { __builtin_amdgcn_s_setprio(1); _Pragma("unroll") for (int m = 0; m < 4; ++m) _Pragma("unroll") for (int n = 0; n < 2; ++n) _Pragma("unroll") for (int k = 0; k < 2; ++k) \
;         acc[ai][bj][m][n] = __builtin_amdgcn_mfma_f32_16x16x32_bf16(Bt[n][k], At[m][k], acc[ai][bj][m][n], 0, 0, 0); __builtin_amdgcn_s_setprio(0); } while (0)
; #define PG8_WAIT_V(n) asm volatile("s_waitcnt vmcnt(" #n ")" ::: "memory")
; #define PG8_WAIT_L(n) asm volatile("s_waitcnt lgkmcnt(" #n ")" ::: "memory")
; #define PG8_BAR __builtin_amdgcn_s_barrier()
; #define PG8_SCHED __builtin_amdgcn_sched_barrier(0)
; template <class Epi, class Sched, bool ALIGN_EPI, class Hook = NoHook>
; __device__ __forceinline__ void gemm_phase(LAS unsigned char* lds, const Gemm g, const Sched& S, const Epi& E, const Hook& H = Hook()) {
;     ...
;             const char* a1 = cA + (size_t)(t + 1) * kstep;
;             const char* a2 = last ? nA : cA + (size_t)(t + 2) * kstep; const char* b2 = last ? nB : cB + (size_t)(t + 2) * kstep;
;             const char* a3 = a2 + kstep; const char* b3 = b2 + kstep;
;             if (last && has_next) S.a_ready(nxt);
;             PG8_LDB(B0, 0, 0); PG8_LDB(B1, 0, 1); PG8_SCHED; PG8_LDA(At, 0, 0); PG8_STAGE(PG8_SA(1, 1), a1 + hA, voffA);
;             PG8_WAIT_V(8); PG8_WAIT_L(0); PG8_BAR; PG8_MMA(0, 0, At, B0); PG8_MMA(0, 1, At, B1); PG8_BAR; PG8_SCHED;
;             PG8_LDA(At, 0, 1); PG8_STAGE(PG8_SB(0, 0), b2, voffB); PG8_STAGE(PG8_SB(0, 1), b2 + hB, voffB); PG8_STAGE(PG8_SA(0, 0), a2, voffA);
;             PG8_WAIT_V(8); PG8_WAIT_L(0); PG8_BAR; PG8_MMA(1, 0, At, B0); PG8_MMA(1, 1, At, B1); PG8_BAR; PG8_SCHED;
.LBB0_1001:
	ds_read_b128 v[106:109], v246
	ds_read_b128 v[110:113], v246 offset:1024
	s_add_u32 s42, s6, 0x100
	s_addc_u32 s43, s7, 0
	s_cmp_eq_u32 s70, 60
	s_cselect_b32 s47, s35, s43
	s_cselect_b32 s46, s66, s42
	s_cselect_b32 s45, s31, s69
	s_cselect_b32 s44, s67, s68
	s_add_i32 m0, s51, 0xc000
	s_nop 0
	global_load_lds_dwordx4 v236, s[6:7]
	ds_read_b128 v[114:117], v246 offset:2048
	ds_read_b128 v[118:121], v246 offset:3072
	ds_read_b128 v[122:125], v247
	ds_read_b128 v[126:129], v247 offset:1024
	ds_read_b128 v[130:133], v247 offset:2048
	ds_read_b128 v[134:137], v247 offset:3072
	ds_read_b128 v[138:141], v248
	s_add_i32 m0, s51, 0xe000
	s_nop 0
	global_load_lds_dwordx4 v238, s[6:7]
	ds_read_b128 v[142:145], v248 offset:1024
	ds_read_b128 v[146:149], v248 offset:2048
	ds_read_b128 v[150:153], v248 offset:3072
	ds_read_b128 v[154:157], v248 offset:4096
	ds_read_b128 v[158:161], v248 offset:5120
	ds_read_b128 v[162:165], v248 offset:6144
	ds_read_b128 v[170:173], v248 offset:7168
	s_waitcnt vmcnt(8) lgkmcnt(0)
	s_barrier
	s_setprio 1
	v_mfma_f32_16x16x32_bf16 v[190:193], v[106:109], v[138:141], v[190:193]
	v_mfma_f32_16x16x32_bf16 v[178:181], v[114:117], v[138:141], v[178:181]
	v_mfma_f32_16x16x32_bf16 v[182:185], v[106:109], v[146:149], v[182:185]
	v_mfma_f32_16x16x32_bf16 v[98:101], v[114:117], v[146:149], v[98:101]
	v_mfma_f32_16x16x32_bf16 v[102:105], v[106:109], v[154:157], v[102:105]
	v_mfma_f32_16x16x32_bf16 v[86:89], v[114:117], v[154:157], v[86:89]
	v_mfma_f32_16x16x32_bf16 v[78:81], v[106:109], v[162:165], v[78:81]
	v_mfma_f32_16x16x32_bf16 v[70:73], v[114:117], v[162:165], v[70:73]
	v_mfma_f32_16x16x32_bf16 v[190:193], v[110:113], v[142:145], v[190:193]
	v_mfma_f32_16x16x32_bf16 v[178:181], v[118:121], v[142:145], v[178:181]
	v_mfma_f32_16x16x32_bf16 v[182:185], v[110:113], v[150:153], v[182:185]
	v_mfma_f32_16x16x32_bf16 v[98:101], v[118:121], v[150:153], v[98:101]
	v_mfma_f32_16x16x32_bf16 v[102:105], v[110:113], v[158:161], v[102:105]
	v_mfma_f32_16x16x32_bf16 v[86:89], v[118:121], v[158:161], v[86:89]
	v_mfma_f32_16x16x32_bf16 v[78:81], v[110:113], v[170:173], v[78:81]
	v_mfma_f32_16x16x32_bf16 v[70:73], v[118:121], v[170:173], v[70:73]
	s_setprio 0
	s_setprio 1
	v_mfma_f32_16x16x32_bf16 v[186:189], v[122:125], v[138:141], v[186:189]
	v_mfma_f32_16x16x32_bf16 v[138:141], v[130:133], v[138:141], v[174:177]
	v_mfma_f32_16x16x32_bf16 v[94:97], v[130:133], v[146:149], v[94:97]
	v_mfma_f32_16x16x32_bf16 v[90:93], v[122:125], v[154:157], v[90:93]
	v_mfma_f32_16x16x32_bf16 v[82:85], v[130:133], v[154:157], v[82:85]
	v_mfma_f32_16x16x32_bf16 v[74:77], v[122:125], v[162:165], v[74:77]
	v_mfma_f32_16x16x32_bf16 v[66:69], v[130:133], v[162:165], v[66:69]
	v_mfma_f32_16x16x32_bf16 v[186:189], v[126:129], v[142:145], v[186:189]
	v_mfma_f32_16x16x32_bf16 v[138:141], v[134:137], v[142:145], v[138:141]
	v_mfma_f32_16x16x32_bf16 v[142:145], v[122:125], v[146:149], v[166:169]
	v_mfma_f32_16x16x32_bf16 v[94:97], v[134:137], v[150:153], v[94:97]
	v_mfma_f32_16x16x32_bf16 v[90:93], v[126:129], v[158:161], v[90:93]
	v_mfma_f32_16x16x32_bf16 v[82:85], v[134:137], v[158:161], v[82:85]
	v_mfma_f32_16x16x32_bf16 v[74:77], v[126:129], v[170:173], v[74:77]
	v_mfma_f32_16x16x32_bf16 v[66:69], v[134:137], v[170:173], v[66:69]
	v_mfma_f32_16x16x32_bf16 v[142:145], v[126:129], v[150:153], v[142:145]
	s_barrier
	s_setprio 0
	s_add_i32 s6, s63, s29
	s_mov_b32 m0, s6
	ds_read_b128 v[146:149], v248 offset:16384
	ds_read_b128 v[150:153], v248 offset:17408
	global_load_lds_dwordx4 v232, s[44:45]
	ds_read_b128 v[154:157], v248 offset:18432
	s_add_i32 m0, s6, 0x2000
	s_add_u32 s6, s44, 0x100000
	s_addc_u32 s7, s45, 0
	s_add_i32 s71, s64, s29
	global_load_lds_dwordx4 v228, s[44:45]
	ds_read_b128 v[158:161], v248 offset:19456
	s_mov_b32 m0, s71
	s_nop 0
	global_load_lds_dwordx4 v232, s[6:7]
	ds_read_b128 v[162:165], v248 offset:20480
	s_add_i32 m0, s71, 0x2000
	s_nop 0
	global_load_lds_dwordx4 v228, s[6:7]
	ds_read_b128 v[166:169], v248 offset:21504
	s_mov_b32 m0, s51
	s_nop 0
	global_load_lds_dwordx4 v234, s[46:47]
	ds_read_b128 v[170:173], v248 offset:22528
	s_mov_b32 m0, s52
	s_nop 0
	global_load_lds_dwordx4 v230, s[46:47]
	ds_read_b128 v[174:177], v248 offset:23552
	s_waitcnt vmcnt(8) lgkmcnt(0)
	s_barrier
	s_setprio 1
	v_mfma_f32_16x16x32_bf16 v[62:65], v[106:109], v[146:149], v[62:65]
	v_mfma_f32_16x16x32_bf16 v[54:57], v[114:117], v[146:149], v[54:57]
	v_mfma_f32_16x16x32_bf16 v[46:49], v[106:109], v[154:157], v[46:49]
	v_mfma_f32_16x16x32_bf16 v[22:25], v[114:117], v[154:157], v[22:25]
	v_mfma_f32_16x16x32_bf16 v[42:45], v[106:109], v[162:165], v[42:45]
	v_mfma_f32_16x16x32_bf16 v[10:13], v[114:117], v[162:165], v[10:13]
	v_mfma_f32_16x16x32_bf16 v[38:41], v[106:109], v[170:173], v[38:41]
	v_mfma_f32_16x16x32_bf16 v[14:17], v[114:117], v[170:173], v[14:17]
	v_mfma_f32_16x16x32_bf16 v[62:65], v[110:113], v[150:153], v[62:65]
	v_mfma_f32_16x16x32_bf16 v[54:57], v[118:121], v[150:153], v[54:57]
	v_mfma_f32_16x16x32_bf16 v[46:49], v[110:113], v[158:161], v[46:49]
	v_mfma_f32_16x16x32_bf16 v[22:25], v[118:121], v[158:161], v[22:25]
	v_mfma_f32_16x16x32_bf16 v[42:45], v[110:113], v[166:169], v[42:45]
	v_mfma_f32_16x16x32_bf16 v[10:13], v[118:121], v[166:169], v[10:13]
	v_mfma_f32_16x16x32_bf16 v[38:41], v[110:113], v[174:177], v[38:41]
	v_mfma_f32_16x16x32_bf16 v[14:17], v[118:121], v[174:177], v[14:17]
	s_setprio 0
	s_setprio 1
	v_mfma_f32_16x16x32_bf16 v[58:61], v[122:125], v[146:149], v[58:61]
	v_mfma_f32_16x16x32_bf16 v[50:53], v[130:133], v[146:149], v[50:53]
	v_mfma_f32_16x16x32_bf16 v[34:37], v[122:125], v[154:157], v[34:37]
	v_mfma_f32_16x16x32_bf16 v[18:21], v[130:133], v[154:157], v[18:21]
	v_mfma_f32_16x16x32_bf16 v[30:33], v[122:125], v[162:165], v[30:33]
	v_mfma_f32_16x16x32_bf16 v[2:5], v[130:133], v[162:165], v[2:5]
	v_mfma_f32_16x16x32_bf16 v[26:29], v[122:125], v[170:173], v[26:29]
	v_mfma_f32_16x16x32_bf16 v[6:9], v[130:133], v[170:173], v[6:9]
	v_mfma_f32_16x16x32_bf16 v[58:61], v[126:129], v[150:153], v[58:61]
	v_mfma_f32_16x16x32_bf16 v[50:53], v[134:137], v[150:153], v[50:53]
	v_mfma_f32_16x16x32_bf16 v[34:37], v[126:129], v[158:161], v[34:37]
	v_mfma_f32_16x16x32_bf16 v[18:21], v[134:137], v[158:161], v[18:21]
	v_mfma_f32_16x16x32_bf16 v[30:33], v[126:129], v[166:169], v[30:33]
	v_mfma_f32_16x16x32_bf16 v[2:5], v[134:137], v[166:169], v[2:5]
	v_mfma_f32_16x16x32_bf16 v[26:29], v[126:129], v[174:177], v[26:29]
	v_mfma_f32_16x16x32_bf16 v[6:9], v[134:137], v[174:177], v[6:9]
	s_barrier
; #define PG8_STAGE(bufoff, gbase, voff) do { _Pragma("unroll") for (int _i = 0; _i < 2; ++_i) \
;         __builtin_amdgcn_global_load_lds((const unsigned*)((const char*)(gbase) + (voff)[_i]), (LAS unsigned*)(lds + (bufoff) + ldsw + _i * 8192), 16, 0, 0); } while (0)
; #define PG8_LDA(dst, b, h) do { _Pragma("unroll") for (int m = 0; m < 4; ++m) _Pragma("unroll") for (int k = 0; k < 2; ++k) dst[m][k] = *(const LAS bf16x8*)(lds + PG8_SA(b, h) + aoff + m * 2048 + k * 1024); } while (0)
; #define PG8_LDB(dst, b, h) do { _Pragma("unroll") for (int n = 0; n < 2; ++n) _Pragma("unroll") for (int k = 0; k < 2; ++k) dst[n][k] = *(const LAS bf16x8*)(lds + PG8_SB(b, h) + boff + n * 2048 + k * 1024); } while (0)
; #define PG8_MMA(ai, bj, At, Bt) do { __builtin_amdgcn_s_setprio(1); _Pragma("unroll") for (int m = 0; m < 4; ++m) _Pragma("unroll") for (int n = 0; n < 2; ++n) _Pragma("unroll") for (int k = 0; k < 2; ++k) \
;         acc[ai][bj][m][n] = __builtin_amdgcn_mfma_f32_16x16x32_bf16(Bt[n][k], At[m][k], acc[ai][bj][m][n], 0, 0, 0); __builtin_amdgcn_s_setprio(0); } while (0)
; #define PG8_WAIT_V(n) asm volatile("s_waitcnt vmcnt(" #n ")" ::: "memory")
; #define PG8_WAIT_L(n) asm volatile("s_waitcnt lgkmcnt(" #n ")" ::: "memory")
; #define PG8_BAR __builtin_amdgcn_s_barrier()
; #define PG8_SCHED __builtin_amdgcn_sched_barrier(0)
; template <class Epi, class Sched, bool ALIGN_EPI, class Hook = NoHook>
; __device__ __forceinline__ void gemm_phase(LAS unsigned char* lds, const Gemm g, const Sched& S, const Epi& E, const Hook& H = Hook()) {
;     ...
;             PG8_LDB(B0, 1, 0); PG8_LDB(B1, 1, 1); PG8_SCHED; PG8_LDA(At, 1, 0); PG8_STAGE(PG8_SA(0, 1), a2 + hA, voffA);
;             PG8_WAIT_V(8); PG8_WAIT_L(0); PG8_BAR; PG8_MMA(0, 0, At, B0); PG8_MMA(0, 1, At, B1); PG8_BAR; PG8_SCHED;
;             PG8_LDA(At, 1, 1); PG8_STAGE(PG8_SB(1, 0), b3, voffB); PG8_STAGE(PG8_SB(1, 1), b3 + hB, voffB); PG8_STAGE(PG8_SA(1, 0), a3, voffA);
;             PG8_WAIT_V(8); PG8_WAIT_L(0); PG8_BAR; PG8_MMA(1, 0, At, B0); PG8_MMA(1, 1, At, B1); PG8_BAR; PG8_SCHED;
;         }
;         if constexpr (Hook::ON) H.after(te, acc, cur, wr, wc, fr, fq);
;         }
;         if constexpr (ALIGN_EPI) { if (wr == 0) PG8_BAR; }
	s_setprio 0
	s_add_i32 s71, 0, 0x18000
	s_add_i32 s72, 0, 0x1c000
	v_add_u32_e32 v118, s71, v245
	v_add_u32_e32 v134, s72, v245
	ds_read_b128 v[106:109], v118
	ds_read_b128 v[110:113], v118 offset:1024
	s_add_u32 s6, s46, 0x8000
	s_addc_u32 s7, s47, 0
	s_mov_b32 m0, s53
	s_nop 0
	global_load_lds_dwordx4 v234, s[6:7]
	ds_read_b128 v[114:117], v118 offset:2048
	ds_read_b128 v[118:121], v118 offset:3072
	ds_read_b128 v[122:125], v134
	ds_read_b128 v[126:129], v134 offset:1024
	ds_read_b128 v[130:133], v134 offset:2048
	ds_read_b128 v[134:137], v134 offset:3072
	ds_read_b128 v[146:149], v248 offset:32768
	s_mov_b32 m0, s54
	s_nop 0
	global_load_lds_dwordx4 v230, s[6:7]
	ds_read_b128 v[150:153], v248 offset:33792
	ds_read_b128 v[154:157], v248 offset:34816
	ds_read_b128 v[158:161], v248 offset:35840
	ds_read_b128 v[162:165], v248 offset:36864
	ds_read_b128 v[170:173], v248 offset:37888
	ds_read_b128 v[194:197], v248 offset:38912
	ds_read_b128 v[198:201], v248 offset:39936
	s_waitcnt vmcnt(8) lgkmcnt(0)
	s_barrier
	s_setprio 1
	v_mfma_f32_16x16x32_bf16 v[166:169], v[106:109], v[146:149], v[190:193]
	v_mfma_f32_16x16x32_bf16 v[190:193], v[110:113], v[150:153], v[166:169]
	v_mfma_f32_16x16x32_bf16 v[166:169], v[114:117], v[146:149], v[178:181]
	v_mfma_f32_16x16x32_bf16 v[178:181], v[118:121], v[150:153], v[166:169]
	v_mfma_f32_16x16x32_bf16 v[166:169], v[106:109], v[154:157], v[182:185]
	v_mfma_f32_16x16x32_bf16 v[98:101], v[114:117], v[154:157], v[98:101]
	v_mfma_f32_16x16x32_bf16 v[102:105], v[106:109], v[162:165], v[102:105]
	v_mfma_f32_16x16x32_bf16 v[86:89], v[114:117], v[162:165], v[86:89]
	v_mfma_f32_16x16x32_bf16 v[78:81], v[106:109], v[194:197], v[78:81]
	v_mfma_f32_16x16x32_bf16 v[70:73], v[114:117], v[194:197], v[70:73]
	v_mfma_f32_16x16x32_bf16 v[182:185], v[110:113], v[158:161], v[166:169]
	v_mfma_f32_16x16x32_bf16 v[98:101], v[118:121], v[158:161], v[98:101]
	v_mfma_f32_16x16x32_bf16 v[102:105], v[110:113], v[170:173], v[102:105]
	v_mfma_f32_16x16x32_bf16 v[86:89], v[118:121], v[170:173], v[86:89]
	v_mfma_f32_16x16x32_bf16 v[78:81], v[110:113], v[198:201], v[78:81]
	v_mfma_f32_16x16x32_bf16 v[70:73], v[118:121], v[198:201], v[70:73]
	s_setprio 0
	s_setprio 1
	v_mfma_f32_16x16x32_bf16 v[138:141], v[130:133], v[146:149], v[138:141]
	v_mfma_f32_16x16x32_bf16 v[166:169], v[122:125], v[146:149], v[186:189]
	v_mfma_f32_16x16x32_bf16 v[174:177], v[134:137], v[150:153], v[138:141]
	v_mfma_f32_16x16x32_bf16 v[138:141], v[122:125], v[154:157], v[142:145]
	v_mfma_f32_16x16x32_bf16 v[94:97], v[130:133], v[154:157], v[94:97]
	v_mfma_f32_16x16x32_bf16 v[90:93], v[122:125], v[162:165], v[90:93]
	v_mfma_f32_16x16x32_bf16 v[82:85], v[130:133], v[162:165], v[82:85]
	v_mfma_f32_16x16x32_bf16 v[74:77], v[122:125], v[194:197], v[74:77]
	v_mfma_f32_16x16x32_bf16 v[66:69], v[130:133], v[194:197], v[66:69]
	v_mfma_f32_16x16x32_bf16 v[186:189], v[126:129], v[150:153], v[166:169]
	v_mfma_f32_16x16x32_bf16 v[166:169], v[126:129], v[158:161], v[138:141]
	v_mfma_f32_16x16x32_bf16 v[94:97], v[134:137], v[158:161], v[94:97]
	v_mfma_f32_16x16x32_bf16 v[90:93], v[126:129], v[170:173], v[90:93]
	v_mfma_f32_16x16x32_bf16 v[82:85], v[134:137], v[170:173], v[82:85]
	v_mfma_f32_16x16x32_bf16 v[74:77], v[126:129], v[198:201], v[74:77]
	v_mfma_f32_16x16x32_bf16 v[66:69], v[134:137], v[198:201], v[66:69]
	s_barrier
	s_setprio 0
	s_add_i32 s6, s71, s29
	s_add_u32 s74, s44, s14
	s_addc_u32 s75, s45, s15
	s_mov_b32 m0, s6
	ds_read_b128 v[138:141], v248 offset:49152
	ds_read_b128 v[142:145], v248 offset:50176
	global_load_lds_dwordx4 v232, s[74:75]
	ds_read_b128 v[146:149], v248 offset:51200
	s_add_i32 m0, s6, 0x2000
	s_add_u32 s6, s44, 0x100080
	s_addc_u32 s7, s45, 0
	s_add_i32 s44, s72, s29
	global_load_lds_dwordx4 v228, s[74:75]
	ds_read_b128 v[150:153], v248 offset:52224
	s_mov_b32 m0, s44
	s_nop 0
	global_load_lds_dwordx4 v232, s[6:7]
	ds_read_b128 v[154:157], v248 offset:53248
	s_add_i32 m0, s44, 0x2000
	s_nop 0
	global_load_lds_dwordx4 v228, s[6:7]
	ds_read_b128 v[158:161], v248 offset:54272
	s_add_u32 s78, s46, s14
	s_addc_u32 s79, s47, s15
	s_mov_b32 m0, s57
	s_nop 0
	global_load_lds_dwordx4 v234, s[78:79]
	ds_read_b128 v[162:165], v248 offset:55296
	s_mov_b32 m0, s58
	s_nop 0
	global_load_lds_dwordx4 v230, s[78:79]
	ds_read_b128 v[170:173], v248 offset:56320
	s_waitcnt vmcnt(8) lgkmcnt(0)
	s_barrier
	s_setprio 1
	v_mfma_f32_16x16x32_bf16 v[62:65], v[106:109], v[138:141], v[62:65]
	v_mfma_f32_16x16x32_bf16 v[54:57], v[114:117], v[138:141], v[54:57]
	v_mfma_f32_16x16x32_bf16 v[46:49], v[106:109], v[146:149], v[46:49]
	v_mfma_f32_16x16x32_bf16 v[22:25], v[114:117], v[146:149], v[22:25]
	v_mfma_f32_16x16x32_bf16 v[42:45], v[106:109], v[154:157], v[42:45]
	v_mfma_f32_16x16x32_bf16 v[10:13], v[114:117], v[154:157], v[10:13]
	v_mfma_f32_16x16x32_bf16 v[38:41], v[106:109], v[162:165], v[38:41]
	v_mfma_f32_16x16x32_bf16 v[14:17], v[114:117], v[162:165], v[14:17]
	v_mfma_f32_16x16x32_bf16 v[62:65], v[110:113], v[142:145], v[62:65]
	v_mfma_f32_16x16x32_bf16 v[54:57], v[118:121], v[142:145], v[54:57]
	v_mfma_f32_16x16x32_bf16 v[46:49], v[110:113], v[150:153], v[46:49]
	v_mfma_f32_16x16x32_bf16 v[22:25], v[118:121], v[150:153], v[22:25]
	v_mfma_f32_16x16x32_bf16 v[42:45], v[110:113], v[158:161], v[42:45]
	v_mfma_f32_16x16x32_bf16 v[10:13], v[118:121], v[158:161], v[10:13]
	v_mfma_f32_16x16x32_bf16 v[38:41], v[110:113], v[170:173], v[38:41]
	v_mfma_f32_16x16x32_bf16 v[14:17], v[118:121], v[170:173], v[14:17]
	s_setprio 0
	s_setprio 1
	v_mfma_f32_16x16x32_bf16 v[58:61], v[122:125], v[138:141], v[58:61]
	v_mfma_f32_16x16x32_bf16 v[50:53], v[130:133], v[138:141], v[50:53]
	v_mfma_f32_16x16x32_bf16 v[34:37], v[122:125], v[146:149], v[34:37]
	v_mfma_f32_16x16x32_bf16 v[18:21], v[130:133], v[146:149], v[18:21]
	v_mfma_f32_16x16x32_bf16 v[30:33], v[122:125], v[154:157], v[30:33]
	v_mfma_f32_16x16x32_bf16 v[2:5], v[130:133], v[154:157], v[2:5]
	v_mfma_f32_16x16x32_bf16 v[26:29], v[122:125], v[162:165], v[26:29]
	v_mfma_f32_16x16x32_bf16 v[6:9], v[130:133], v[162:165], v[6:9]
	v_mfma_f32_16x16x32_bf16 v[58:61], v[126:129], v[142:145], v[58:61]
	v_mfma_f32_16x16x32_bf16 v[50:53], v[134:137], v[142:145], v[50:53]
	v_mfma_f32_16x16x32_bf16 v[34:37], v[126:129], v[150:153], v[34:37]
	v_mfma_f32_16x16x32_bf16 v[18:21], v[134:137], v[150:153], v[18:21]
	v_mfma_f32_16x16x32_bf16 v[30:33], v[126:129], v[158:161], v[30:33]
	v_mfma_f32_16x16x32_bf16 v[2:5], v[134:137], v[158:161], v[2:5]
	v_mfma_f32_16x16x32_bf16 v[26:29], v[126:129], v[170:173], v[26:29]
	v_mfma_f32_16x16x32_bf16 v[6:9], v[134:137], v[170:173], v[6:9]
	s_barrier
	s_setprio 0
	s_add_i32 s70, s70, 2
	s_add_u32 s68, s68, 0x100
	s_addc_u32 s69, s69, 0
	s_cmp_gt_u32 s70, 61
	s_mov_b64 s[6:7], s[42:43]
	s_cbranch_scc0 .LBB0_1001
	s_and_b64 vcc, exec, s[2:3]
	s_cbranch_vccz .LBB0_1004
	s_barrier

; #define PG8_STAGE(bufoff, gbase, voff) do { _Pragma("unroll") for (int _i = 0; _i < 2; ++_i) \
;         __builtin_amdgcn_global_load_lds((const unsigned*)((const char*)(gbase) + (voff)[_i]), (LAS unsigned*)(lds + (bufoff) + ldsw + _i * 8192), 16, 0, 0); } while (0)
; #define PG8_LDA(dst, b, h) do { _Pragma("unroll") for (int m = 0; m < 4; ++m) _Pragma("unroll") for (int k = 0; k < 2; ++k) dst[m][k] = *(const LAS bf16x8*)(lds + PG8_SA(b, h) + aoff + m * 2048 + k * 1024); } while (0)
; #define PG8_LDB(dst, b, h) do { _Pragma("unroll") for (int n = 0; n < 2; ++n) _Pragma("unroll") for (int k = 0; k < 2; ++k) dst[n][k] = *(const LAS bf16x8*)(lds + PG8_SB(b, h) + boff + n * 2048 + k * 1024); } while (0)
; #define PG8_MMA(ai, bj, At, Bt) do { __builtin_amdgcn_s_setprio(1); _Pragma("unroll") for (int m = 0; m < 4; ++m) _Pragma("unroll") for (int n = 0; n < 2; ++n) _Pragma("unroll") for (int k = 0; k < 2; ++k) \
;         acc[ai][bj][m][n] = __builtin_amdgcn_mfma_f32_16x16x32_bf16(Bt[n][k], At[m][k], acc[ai][bj][m][n], 0, 0, 0); __builtin_amdgcn_s_setprio(0); } while (0)
; #define PG8_WAIT_V(n) asm volatile("s_waitcnt vmcnt(" #n ")" ::: "memory")
; #define PG8_WAIT_L(n) asm volatile("s_waitcnt lgkmcnt(" #n ")" ::: "memory")
; #define PG8_BAR __builtin_amdgcn_s_barrier()
; #define PG8_SCHED __builtin_amdgcn_sched_barrier(0)
; template <class Epi, class Sched, bool ALIGN_EPI, class Hook = NoHook>
; __device__ __forceinline__ void gemm_phase(LAS unsigned char* lds, const Gemm g, const Sched& S, const Epi& E, const Hook& H = Hook()) {
;     ...
;             const char* a1 = cA + (size_t)(t + 1) * kstep;
;             const char* a2 = last ? nA : cA + (size_t)(t + 2) * kstep; const char* b2 = last ? nB : cB + (size_t)(t + 2) * kstep;
;             const char* a3 = a2 + kstep; const char* b3 = b2 + kstep;
;             if (last && has_next) S.a_ready(nxt);
;             PG8_LDB(B0, 0, 0); PG8_LDB(B1, 0, 1); PG8_SCHED; PG8_LDA(At, 0, 0); PG8_STAGE(PG8_SA(1, 1), a1 + hA, voffA);
;             PG8_WAIT_V(8); PG8_WAIT_L(0); PG8_BAR; PG8_MMA(0, 0, At, B0); PG8_MMA(0, 1, At, B1); PG8_BAR; PG8_SCHED;
;             PG8_LDA(At, 0, 1); PG8_STAGE(PG8_SB(0, 0), b2, voffB); PG8_STAGE(PG8_SB(0, 1), b2 + hB, voffB); PG8_STAGE(PG8_SA(0, 0), a2, voffA);
;             PG8_WAIT_V(8); PG8_WAIT_L(0); PG8_BAR; PG8_MMA(1, 0, At, B0); PG8_MMA(1, 1, At, B1); PG8_BAR; PG8_SCHED;
.LBB0_1360:
	ds_read_b128 v[146:149], v1
	ds_read_b128 v[150:153], v1 offset:1024
	s_add_u32 s14, s4, 0xbb050080
	s_addc_u32 s15, s5, -1
	s_cmpk_lg_i32 s41, 0xa8
	s_cselect_b32 s14, s14, 0
	s_cselect_b32 s15, s15, 0
	s_add_u32 s20, s0, s14
	s_addc_u32 s21, s1, s15
	s_add_u32 s14, s12, s14
	s_addc_u32 s15, s13, s15
	s_mov_b32 m0, s42
	ds_read_b128 v[154:157], v1 offset:2048
	ds_read_b128 v[158:161], v1 offset:3072
	ds_read_b128 v[164:167], v142
	ds_read_b128 v[170:173], v142 offset:1024
	ds_read_b128 v[174:177], v142 offset:2048
	ds_read_b128 v[178:181], v142 offset:3072
	v_lshl_add_u64 v[214:215], v[138:139], 0, s[4:5]
	global_load_lds_dwordx4 v[214:215], off
	ds_read_b128 v[182:185], v143
	ds_read_b128 v[186:189], v143 offset:1024
	ds_read_b128 v[190:193], v143 offset:2048
	ds_read_b128 v[194:197], v143 offset:3072
	ds_read_b128 v[198:201], v143 offset:4096
	ds_read_b128 v[202:205], v143 offset:5120
	ds_read_b128 v[206:209], v143 offset:6144
	ds_read_b128 v[210:213], v143 offset:7168
	v_lshl_add_u64 v[214:215], v[140:141], 0, s[4:5]
	s_mov_b32 m0, s43
	s_nop 0
	global_load_lds_dwordx4 v[214:215], off
	s_waitcnt vmcnt(8) lgkmcnt(0)
	s_barrier
	s_setprio 1
	v_mfma_f32_16x16x32_bf16 v[82:85], v[146:149], v[182:185], v[82:85]
	v_mfma_f32_16x16x32_bf16 v[54:57], v[154:157], v[182:185], v[54:57]
	v_mfma_f32_16x16x32_bf16 v[58:61], v[146:149], v[190:193], v[58:61]
	v_mfma_f32_16x16x32_bf16 v[42:45], v[154:157], v[190:193], v[42:45]
	v_mfma_f32_16x16x32_bf16 v[70:73], v[146:149], v[198:201], v[70:73]
	v_mfma_f32_16x16x32_bf16 v[50:53], v[154:157], v[198:201], v[50:53]
	v_mfma_f32_16x16x32_bf16 v[86:89], v[146:149], v[206:209], v[86:89]
	v_mfma_f32_16x16x32_bf16 v[74:77], v[154:157], v[206:209], v[74:77]
	v_mfma_f32_16x16x32_bf16 v[82:85], v[150:153], v[186:189], v[82:85]
	v_mfma_f32_16x16x32_bf16 v[54:57], v[158:161], v[186:189], v[54:57]
	v_mfma_f32_16x16x32_bf16 v[58:61], v[150:153], v[194:197], v[58:61]
	v_mfma_f32_16x16x32_bf16 v[42:45], v[158:161], v[194:197], v[42:45]
	v_mfma_f32_16x16x32_bf16 v[70:73], v[150:153], v[202:205], v[70:73]
	v_mfma_f32_16x16x32_bf16 v[50:53], v[158:161], v[202:205], v[50:53]
	v_mfma_f32_16x16x32_bf16 v[86:89], v[150:153], v[210:213], v[86:89]
	v_mfma_f32_16x16x32_bf16 v[74:77], v[158:161], v[210:213], v[74:77]
	s_setprio 0
	s_setprio 1
	v_mfma_f32_16x16x32_bf16 v[14:17], v[164:167], v[182:185], v[14:17]
	v_mfma_f32_16x16x32_bf16 v[2:5], v[174:177], v[182:185], v[2:5]
	v_mfma_f32_16x16x32_bf16 v[18:21], v[164:167], v[190:193], v[18:21]
	v_mfma_f32_16x16x32_bf16 v[6:9], v[174:177], v[190:193], v[6:9]
	v_mfma_f32_16x16x32_bf16 v[22:25], v[164:167], v[198:201], v[22:25]
	v_mfma_f32_16x16x32_bf16 v[10:13], v[174:177], v[198:201], v[10:13]
	v_mfma_f32_16x16x32_bf16 v[30:33], v[164:167], v[206:209], v[30:33]
	v_mfma_f32_16x16x32_bf16 v[26:29], v[174:177], v[206:209], v[26:29]
	v_mfma_f32_16x16x32_bf16 v[14:17], v[170:173], v[186:189], v[14:17]
	v_mfma_f32_16x16x32_bf16 v[2:5], v[178:181], v[186:189], v[2:5]
	v_mfma_f32_16x16x32_bf16 v[18:21], v[170:173], v[194:197], v[18:21]
	v_mfma_f32_16x16x32_bf16 v[6:9], v[178:181], v[194:197], v[6:9]
	v_mfma_f32_16x16x32_bf16 v[22:25], v[170:173], v[202:205], v[22:25]
	v_mfma_f32_16x16x32_bf16 v[10:13], v[178:181], v[202:205], v[10:13]
	v_mfma_f32_16x16x32_bf16 v[30:33], v[170:173], v[210:213], v[30:33]
	v_mfma_f32_16x16x32_bf16 v[26:29], v[178:181], v[210:213], v[26:29]
	s_barrier
	s_setprio 0
	s_mov_b32 m0, s44
	s_add_u32 s52, s14, 0x2b0000
	ds_read_b128 v[182:185], v143 offset:16384
	ds_read_b128 v[186:189], v143 offset:17408
	global_load_lds_dwordx4 v132, s[14:15]
	ds_read_b128 v[190:193], v143 offset:18432
	s_mov_b32 m0, s45
	s_addc_u32 s53, s15, 0
	global_load_lds_dwordx4 v136, s[14:15]
	ds_read_b128 v[194:197], v143 offset:19456
	s_mov_b32 m0, s46
	s_nop 0
	global_load_lds_dwordx4 v132, s[52:53]
	ds_read_b128 v[198:201], v143 offset:20480
	s_mov_b32 m0, s47
	s_nop 0
	global_load_lds_dwordx4 v136, s[52:53]
	ds_read_b128 v[202:205], v143 offset:21504
	s_add_u32 s56, s20, s2
	s_addc_u32 s57, s21, s3
	s_mov_b32 m0, s25
	s_nop 0
	global_load_lds_dwordx4 v130, s[20:21]
	ds_read_b128 v[206:209], v143 offset:22528
	s_mov_b32 m0, s27
	s_nop 0
	global_load_lds_dwordx4 v134, s[20:21]
	ds_read_b128 v[210:213], v143 offset:23552
	s_waitcnt vmcnt(8) lgkmcnt(0)
	s_barrier
	s_setprio 1
	v_mfma_f32_16x16x32_bf16 v[94:97], v[146:149], v[182:185], v[94:97]
	v_mfma_f32_16x16x32_bf16 v[90:93], v[154:157], v[182:185], v[90:93]
	v_mfma_f32_16x16x32_bf16 v[106:109], v[146:149], v[190:193], v[106:109]
	v_mfma_f32_16x16x32_bf16 v[98:101], v[154:157], v[190:193], v[98:101]
	v_mfma_f32_16x16x32_bf16 v[110:113], v[146:149], v[198:201], v[110:113]
	v_mfma_f32_16x16x32_bf16 v[102:105], v[154:157], v[198:201], v[102:105]
	v_mfma_f32_16x16x32_bf16 v[126:129], v[146:149], v[206:209], v[126:129]
	v_mfma_f32_16x16x32_bf16 v[122:125], v[154:157], v[206:209], v[122:125]
	v_mfma_f32_16x16x32_bf16 v[94:97], v[150:153], v[186:189], v[94:97]
	v_mfma_f32_16x16x32_bf16 v[90:93], v[158:161], v[186:189], v[90:93]
	v_mfma_f32_16x16x32_bf16 v[106:109], v[150:153], v[194:197], v[106:109]
	v_mfma_f32_16x16x32_bf16 v[98:101], v[158:161], v[194:197], v[98:101]
	v_mfma_f32_16x16x32_bf16 v[110:113], v[150:153], v[202:205], v[110:113]
	v_mfma_f32_16x16x32_bf16 v[102:105], v[158:161], v[202:205], v[102:105]
	v_mfma_f32_16x16x32_bf16 v[126:129], v[150:153], v[210:213], v[126:129]
	v_mfma_f32_16x16x32_bf16 v[122:125], v[158:161], v[210:213], v[122:125]
	s_setprio 0
	s_setprio 1
	v_mfma_f32_16x16x32_bf16 v[38:41], v[164:167], v[182:185], v[38:41]
	v_mfma_f32_16x16x32_bf16 v[34:37], v[174:177], v[182:185], v[34:37]
	v_mfma_f32_16x16x32_bf16 v[66:69], v[164:167], v[190:193], v[66:69]
	v_mfma_f32_16x16x32_bf16 v[46:49], v[174:177], v[190:193], v[46:49]
	v_mfma_f32_16x16x32_bf16 v[78:81], v[164:167], v[198:201], v[78:81]
	v_mfma_f32_16x16x32_bf16 v[62:65], v[174:177], v[198:201], v[62:65]
	v_mfma_f32_16x16x32_bf16 v[118:121], v[164:167], v[206:209], v[118:121]
	v_mfma_f32_16x16x32_bf16 v[114:117], v[174:177], v[206:209], v[114:117]
	v_mfma_f32_16x16x32_bf16 v[38:41], v[170:173], v[186:189], v[38:41]
	v_mfma_f32_16x16x32_bf16 v[34:37], v[178:181], v[186:189], v[34:37]
	v_mfma_f32_16x16x32_bf16 v[66:69], v[170:173], v[194:197], v[66:69]
	v_mfma_f32_16x16x32_bf16 v[46:49], v[178:181], v[194:197], v[46:49]
	v_mfma_f32_16x16x32_bf16 v[78:81], v[170:173], v[202:205], v[78:81]
	v_mfma_f32_16x16x32_bf16 v[62:65], v[178:181], v[202:205], v[62:65]
	v_mfma_f32_16x16x32_bf16 v[118:121], v[170:173], v[210:213], v[118:121]
	v_mfma_f32_16x16x32_bf16 v[114:117], v[178:181], v[210:213], v[114:117]
	s_barrier
; #define PG8_STAGE(bufoff, gbase, voff) do { _Pragma("unroll") for (int _i = 0; _i < 2; ++_i) \
;         __builtin_amdgcn_global_load_lds((const unsigned*)((const char*)(gbase) + (voff)[_i]), (LAS unsigned*)(lds + (bufoff) + ldsw + _i * 8192), 16, 0, 0); } while (0)
; #define PG8_LDA(dst, b, h) do { _Pragma("unroll") for (int m = 0; m < 4; ++m) _Pragma("unroll") for (int k = 0; k < 2; ++k) dst[m][k] = *(const LAS bf16x8*)(lds + PG8_SA(b, h) + aoff + m * 2048 + k * 1024); } while (0)
; #define PG8_LDB(dst, b, h) do { _Pragma("unroll") for (int n = 0; n < 2; ++n) _Pragma("unroll") for (int k = 0; k < 2; ++k) dst[n][k] = *(const LAS bf16x8*)(lds + PG8_SB(b, h) + boff + n * 2048 + k * 1024); } while (0)
; #define PG8_MMA(ai, bj, At, Bt) do { __builtin_amdgcn_s_setprio(1); _Pragma("unroll") for (int m = 0; m < 4; ++m) _Pragma("unroll") for (int n = 0; n < 2; ++n) _Pragma("unroll") for (int k = 0; k < 2; ++k) \
;         acc[ai][bj][m][n] = __builtin_amdgcn_mfma_f32_16x16x32_bf16(Bt[n][k], At[m][k], acc[ai][bj][m][n], 0, 0, 0); __builtin_amdgcn_s_setprio(0); } while (0)
; #define PG8_WAIT_V(n) asm volatile("s_waitcnt vmcnt(" #n ")" ::: "memory")
; #define PG8_WAIT_L(n) asm volatile("s_waitcnt lgkmcnt(" #n ")" ::: "memory")
; #define PG8_BAR __builtin_amdgcn_s_barrier()
; #define PG8_SCHED __builtin_amdgcn_sched_barrier(0)
; template <class Epi, class Sched, bool ALIGN_EPI, class Hook = NoHook>
; __device__ __forceinline__ void gemm_phase(LAS unsigned char* lds, const Gemm g, const Sched& S, const Epi& E, const Hook& H = Hook()) {
;     ...
;             PG8_LDB(B0, 1, 0); PG8_LDB(B1, 1, 1); PG8_SCHED; PG8_LDA(At, 1, 0); PG8_STAGE(PG8_SA(0, 1), a2 + hA, voffA);
;             PG8_WAIT_V(8); PG8_WAIT_L(0); PG8_BAR; PG8_MMA(0, 0, At, B0); PG8_MMA(0, 1, At, B1); PG8_BAR; PG8_SCHED;
;             PG8_LDA(At, 1, 1); PG8_STAGE(PG8_SB(1, 0), b3, voffB); PG8_STAGE(PG8_SB(1, 1), b3 + hB, voffB); PG8_STAGE(PG8_SA(1, 0), a3, voffA);
;             PG8_WAIT_V(8); PG8_WAIT_L(0); PG8_BAR; PG8_MMA(1, 0, At, B0); PG8_MMA(1, 1, At, B1); PG8_BAR; PG8_SCHED;
;         }
;         if constexpr (Hook::ON) H.after(te, acc, cur, wr, wc, fr, fq);
;         }
;         if constexpr (ALIGN_EPI) { if (wr == 0) PG8_BAR; }
	s_setprio 0
	ds_read_b128 v[146:149], v144
	ds_read_b128 v[150:153], v144 offset:1024
	s_add_u32 s20, s20, 0x2b0000
	s_addc_u32 s21, s21, 0
	s_mov_b32 m0, s28
	s_nop 0
	global_load_lds_dwordx4 v130, s[20:21]
	ds_read_b128 v[154:157], v144 offset:2048
	ds_read_b128 v[158:161], v144 offset:3072
	ds_read_b128 v[164:167], v145
	ds_read_b128 v[170:173], v145 offset:1024
	ds_read_b128 v[174:177], v145 offset:2048
	ds_read_b128 v[178:181], v145 offset:3072
	ds_read_b128 v[182:185], v143 offset:32768
	s_mov_b32 m0, s38
	s_nop 0
	global_load_lds_dwordx4 v134, s[20:21]
	ds_read_b128 v[186:189], v143 offset:33792
	ds_read_b128 v[190:193], v143 offset:34816
	ds_read_b128 v[194:197], v143 offset:35840
	ds_read_b128 v[198:201], v143 offset:36864
	ds_read_b128 v[202:205], v143 offset:37888
	ds_read_b128 v[206:209], v143 offset:38912
	ds_read_b128 v[210:213], v143 offset:39936
	s_waitcnt vmcnt(8) lgkmcnt(0)
	s_barrier
	s_setprio 1
	v_mfma_f32_16x16x32_bf16 v[82:85], v[146:149], v[182:185], v[82:85]
	v_mfma_f32_16x16x32_bf16 v[54:57], v[154:157], v[182:185], v[54:57]
	v_mfma_f32_16x16x32_bf16 v[58:61], v[146:149], v[190:193], v[58:61]
	v_mfma_f32_16x16x32_bf16 v[42:45], v[154:157], v[190:193], v[42:45]
	v_mfma_f32_16x16x32_bf16 v[70:73], v[146:149], v[198:201], v[70:73]
	v_mfma_f32_16x16x32_bf16 v[50:53], v[154:157], v[198:201], v[50:53]
	v_mfma_f32_16x16x32_bf16 v[86:89], v[146:149], v[206:209], v[86:89]
	v_mfma_f32_16x16x32_bf16 v[74:77], v[154:157], v[206:209], v[74:77]
	v_mfma_f32_16x16x32_bf16 v[82:85], v[150:153], v[186:189], v[82:85]
	v_mfma_f32_16x16x32_bf16 v[54:57], v[158:161], v[186:189], v[54:57]
	v_mfma_f32_16x16x32_bf16 v[58:61], v[150:153], v[194:197], v[58:61]
	v_mfma_f32_16x16x32_bf16 v[42:45], v[158:161], v[194:197], v[42:45]
	v_mfma_f32_16x16x32_bf16 v[70:73], v[150:153], v[202:205], v[70:73]
	v_mfma_f32_16x16x32_bf16 v[50:53], v[158:161], v[202:205], v[50:53]
	v_mfma_f32_16x16x32_bf16 v[86:89], v[150:153], v[210:213], v[86:89]
	v_mfma_f32_16x16x32_bf16 v[74:77], v[158:161], v[210:213], v[74:77]
	s_setprio 0
	s_setprio 1
	v_mfma_f32_16x16x32_bf16 v[14:17], v[164:167], v[182:185], v[14:17]
	v_mfma_f32_16x16x32_bf16 v[2:5], v[174:177], v[182:185], v[2:5]
	v_mfma_f32_16x16x32_bf16 v[18:21], v[164:167], v[190:193], v[18:21]
	v_mfma_f32_16x16x32_bf16 v[6:9], v[174:177], v[190:193], v[6:9]
	v_mfma_f32_16x16x32_bf16 v[22:25], v[164:167], v[198:201], v[22:25]
	v_mfma_f32_16x16x32_bf16 v[10:13], v[174:177], v[198:201], v[10:13]
	v_mfma_f32_16x16x32_bf16 v[30:33], v[164:167], v[206:209], v[30:33]
	v_mfma_f32_16x16x32_bf16 v[26:29], v[174:177], v[206:209], v[26:29]
	v_mfma_f32_16x16x32_bf16 v[14:17], v[170:173], v[186:189], v[14:17]
	v_mfma_f32_16x16x32_bf16 v[2:5], v[178:181], v[186:189], v[2:5]
	v_mfma_f32_16x16x32_bf16 v[18:21], v[170:173], v[194:197], v[18:21]
	v_mfma_f32_16x16x32_bf16 v[6:9], v[178:181], v[194:197], v[6:9]
	v_mfma_f32_16x16x32_bf16 v[22:25], v[170:173], v[202:205], v[22:25]
	v_mfma_f32_16x16x32_bf16 v[10:13], v[178:181], v[202:205], v[10:13]
	v_mfma_f32_16x16x32_bf16 v[30:33], v[170:173], v[210:213], v[30:33]
	v_mfma_f32_16x16x32_bf16 v[26:29], v[178:181], v[210:213], v[26:29]
	s_barrier
	s_setprio 0
	s_mov_b32 m0, s48
	s_add_u32 s54, s14, s2
	s_addc_u32 s55, s15, s3
	s_add_u32 s14, s14, 0x2b0080
	ds_read_b128 v[182:185], v143 offset:49152
	ds_read_b128 v[186:189], v143 offset:50176
	global_load_lds_dwordx4 v132, s[54:55]
	ds_read_b128 v[190:193], v143 offset:51200
	s_mov_b32 m0, s49
	s_addc_u32 s15, s15, 0
	global_load_lds_dwordx4 v136, s[54:55]
	ds_read_b128 v[194:197], v143 offset:52224
	s_mov_b32 m0, s50
	s_nop 0
	global_load_lds_dwordx4 v132, s[14:15]
	ds_read_b128 v[198:201], v143 offset:53248
	s_mov_b32 m0, s51
	s_nop 0
	global_load_lds_dwordx4 v136, s[14:15]
	ds_read_b128 v[202:205], v143 offset:54272
	s_mov_b32 m0, s39
	s_nop 0
	global_load_lds_dwordx4 v130, s[56:57]
	ds_read_b128 v[206:209], v143 offset:55296
	s_mov_b32 m0, s40
	s_nop 0
	global_load_lds_dwordx4 v134, s[56:57]
	ds_read_b128 v[210:213], v143 offset:56320
	s_waitcnt vmcnt(8) lgkmcnt(0)
	s_barrier
	s_setprio 1
	v_mfma_f32_16x16x32_bf16 v[94:97], v[146:149], v[182:185], v[94:97]
	v_mfma_f32_16x16x32_bf16 v[90:93], v[154:157], v[182:185], v[90:93]
	v_mfma_f32_16x16x32_bf16 v[106:109], v[146:149], v[190:193], v[106:109]
	v_mfma_f32_16x16x32_bf16 v[98:101], v[154:157], v[190:193], v[98:101]
	v_mfma_f32_16x16x32_bf16 v[110:113], v[146:149], v[198:201], v[110:113]
	v_mfma_f32_16x16x32_bf16 v[102:105], v[154:157], v[198:201], v[102:105]
	v_mfma_f32_16x16x32_bf16 v[126:129], v[146:149], v[206:209], v[126:129]
	v_mfma_f32_16x16x32_bf16 v[122:125], v[154:157], v[206:209], v[122:125]
	v_mfma_f32_16x16x32_bf16 v[94:97], v[150:153], v[186:189], v[94:97]
	v_mfma_f32_16x16x32_bf16 v[90:93], v[158:161], v[186:189], v[90:93]
	v_mfma_f32_16x16x32_bf16 v[106:109], v[150:153], v[194:197], v[106:109]
	v_mfma_f32_16x16x32_bf16 v[98:101], v[158:161], v[194:197], v[98:101]
	v_mfma_f32_16x16x32_bf16 v[110:113], v[150:153], v[202:205], v[110:113]
	v_mfma_f32_16x16x32_bf16 v[102:105], v[158:161], v[202:205], v[102:105]
	v_mfma_f32_16x16x32_bf16 v[126:129], v[150:153], v[210:213], v[126:129]
	v_mfma_f32_16x16x32_bf16 v[122:125], v[158:161], v[210:213], v[122:125]
	s_setprio 0
	s_setprio 1
	v_mfma_f32_16x16x32_bf16 v[38:41], v[164:167], v[182:185], v[38:41]
	v_mfma_f32_16x16x32_bf16 v[34:37], v[174:177], v[182:185], v[34:37]
	v_mfma_f32_16x16x32_bf16 v[66:69], v[164:167], v[190:193], v[66:69]
	v_mfma_f32_16x16x32_bf16 v[46:49], v[174:177], v[190:193], v[46:49]
	v_mfma_f32_16x16x32_bf16 v[78:81], v[164:167], v[198:201], v[78:81]
	v_mfma_f32_16x16x32_bf16 v[62:65], v[174:177], v[198:201], v[62:65]
	v_mfma_f32_16x16x32_bf16 v[118:121], v[164:167], v[206:209], v[118:121]
	v_mfma_f32_16x16x32_bf16 v[114:117], v[174:177], v[206:209], v[114:117]
	v_mfma_f32_16x16x32_bf16 v[38:41], v[170:173], v[186:189], v[38:41]
	v_mfma_f32_16x16x32_bf16 v[34:37], v[178:181], v[186:189], v[34:37]
	v_mfma_f32_16x16x32_bf16 v[66:69], v[170:173], v[194:197], v[66:69]
	v_mfma_f32_16x16x32_bf16 v[46:49], v[178:181], v[194:197], v[46:49]
	v_mfma_f32_16x16x32_bf16 v[78:81], v[170:173], v[202:205], v[78:81]
	v_mfma_f32_16x16x32_bf16 v[62:65], v[178:181], v[202:205], v[62:65]
	v_mfma_f32_16x16x32_bf16 v[118:121], v[170:173], v[210:213], v[118:121]
	v_mfma_f32_16x16x32_bf16 v[114:117], v[178:181], v[210:213], v[114:117]
	s_barrier
	s_setprio 0
	s_add_i32 s41, s41, 2
	s_add_u32 s4, s4, 0x100
	s_addc_u32 s5, s5, 0
	s_cmpk_gt_u32 s41, 0xa9
	s_cbranch_scc0 .LBB0_1360
	s_cmpk_lt_u32 s26, 0x100
	s_cbranch_scc0 .LBB0_1363
	s_barrier

; #define PG8_STAGE(bufoff, gbase, voff) do { _Pragma("unroll") for (int _i = 0; _i < 2; ++_i) \
;         __builtin_amdgcn_global_load_lds((const unsigned*)((const char*)(gbase) + (voff)[_i]), (LAS unsigned*)(lds + (bufoff) + ldsw + _i * 8192), 16, 0, 0); } while (0)
; #define PG8_LDA(dst, b, h) do { _Pragma("unroll") for (int m = 0; m < 4; ++m) _Pragma("unroll") for (int k = 0; k < 2; ++k) dst[m][k] = *(const LAS bf16x8*)(lds + PG8_SA(b, h) + aoff + m * 2048 + k * 1024); } while (0)
; #define PG8_LDB(dst, b, h) do { _Pragma("unroll") for (int n = 0; n < 2; ++n) _Pragma("unroll") for (int k = 0; k < 2; ++k) dst[n][k] = *(const LAS bf16x8*)(lds + PG8_SB(b, h) + boff + n * 2048 + k * 1024); } while (0)
; #define PG8_MMA(ai, bj, At, Bt) do { __builtin_amdgcn_s_setprio(1); _Pragma("unroll") for (int m = 0; m < 4; ++m) _Pragma("unroll") for (int n = 0; n < 2; ++n) _Pragma("unroll") for (int k = 0; k < 2; ++k) \
;         acc[ai][bj][m][n] = __builtin_amdgcn_mfma_f32_16x16x32_bf16(Bt[n][k], At[m][k], acc[ai][bj][m][n], 0, 0, 0); __builtin_amdgcn_s_setprio(0); } while (0)
; #define PG8_WAIT_V(n) asm volatile("s_waitcnt vmcnt(" #n ")" ::: "memory")
; #define PG8_WAIT_L(n) asm volatile("s_waitcnt lgkmcnt(" #n ")" ::: "memory")
; #define PG8_BAR __builtin_amdgcn_s_barrier()
; #define PG8_SCHED __builtin_amdgcn_sched_barrier(0)
; template <class Epi, class Sched, bool ALIGN_EPI, class Hook = NoHook>
; __device__ __forceinline__ void gemm_phase(LAS unsigned char* lds, const Gemm g, const Sched& S, const Epi& E, const Hook& H = Hook()) {
;     ...
;             const char* a1 = cA + (size_t)(t + 1) * kstep;
;             const char* a2 = last ? nA : cA + (size_t)(t + 2) * kstep; const char* b2 = last ? nB : cB + (size_t)(t + 2) * kstep;
;             const char* a3 = a2 + kstep; const char* b3 = b2 + kstep;
;             if (last && has_next) S.a_ready(nxt);
;             PG8_LDB(B0, 0, 0); PG8_LDB(B1, 0, 1); PG8_SCHED; PG8_LDA(At, 0, 0); PG8_STAGE(PG8_SA(1, 1), a1 + hA, voffA);
;             PG8_WAIT_V(8); PG8_WAIT_L(0); PG8_BAR; PG8_MMA(0, 0, At, B0); PG8_MMA(0, 1, At, B1); PG8_BAR; PG8_SCHED;
;             PG8_LDA(At, 0, 1); PG8_STAGE(PG8_SB(0, 0), b2, voffB); PG8_STAGE(PG8_SB(0, 1), b2 + hB, voffB); PG8_STAGE(PG8_SA(0, 0), a2, voffA);
;             PG8_WAIT_V(8); PG8_WAIT_L(0); PG8_BAR; PG8_MMA(1, 0, At, B0); PG8_MMA(1, 1, At, B1); PG8_BAR; PG8_SCHED;
.LBB0_1406:
	ds_read_b128 v[146:149], v140
	ds_read_b128 v[150:153], v140 offset:1024
	s_add_u32 s10, s4, 0xbb050080
	s_addc_u32 s11, s5, -1
	s_cmpk_lg_i32 s18, 0xa8
	s_cselect_b32 s10, s10, 0
	s_cselect_b32 s11, s11, 0
	s_add_u32 s16, s0, s10
	s_addc_u32 s17, s1, s11
	s_add_u32 s10, s12, s10
	s_addc_u32 s11, s13, s11
	s_mov_b32 m0, s19
	ds_read_b128 v[154:157], v140 offset:2048
	ds_read_b128 v[158:161], v140 offset:3072
	ds_read_b128 v[170:173], v141
	ds_read_b128 v[174:177], v141 offset:1024
	ds_read_b128 v[178:181], v141 offset:2048
	ds_read_b128 v[182:185], v141 offset:3072
	v_lshl_add_u64 v[218:219], v[136:137], 0, s[4:5]
	global_load_lds_dwordx4 v[218:219], off
	ds_read_b128 v[186:189], v142
	ds_read_b128 v[190:193], v142 offset:1024
	ds_read_b128 v[194:197], v142 offset:2048
	ds_read_b128 v[198:201], v142 offset:3072
	ds_read_b128 v[202:205], v142 offset:4096
	ds_read_b128 v[206:209], v142 offset:5120
	ds_read_b128 v[210:213], v142 offset:6144
	ds_read_b128 v[214:217], v142 offset:7168
	v_lshl_add_u64 v[218:219], v[138:139], 0, s[4:5]
	s_mov_b32 m0, s31
	s_nop 0
	global_load_lds_dwordx4 v[218:219], off
	s_waitcnt vmcnt(8) lgkmcnt(0)
	s_barrier
	s_setprio 1
	v_mfma_f32_16x16x32_bf16 v[82:85], v[146:149], v[186:189], v[82:85]
	v_mfma_f32_16x16x32_bf16 v[54:57], v[154:157], v[186:189], v[54:57]
	v_mfma_f32_16x16x32_bf16 v[58:61], v[146:149], v[194:197], v[58:61]
	v_mfma_f32_16x16x32_bf16 v[42:45], v[154:157], v[194:197], v[42:45]
	v_mfma_f32_16x16x32_bf16 v[70:73], v[146:149], v[202:205], v[70:73]
	v_mfma_f32_16x16x32_bf16 v[50:53], v[154:157], v[202:205], v[50:53]
	v_mfma_f32_16x16x32_bf16 v[86:89], v[146:149], v[210:213], v[86:89]
	v_mfma_f32_16x16x32_bf16 v[74:77], v[154:157], v[210:213], v[74:77]
	v_mfma_f32_16x16x32_bf16 v[82:85], v[150:153], v[190:193], v[82:85]
	v_mfma_f32_16x16x32_bf16 v[54:57], v[158:161], v[190:193], v[54:57]
	v_mfma_f32_16x16x32_bf16 v[58:61], v[150:153], v[198:201], v[58:61]
	v_mfma_f32_16x16x32_bf16 v[42:45], v[158:161], v[198:201], v[42:45]
	v_mfma_f32_16x16x32_bf16 v[70:73], v[150:153], v[206:209], v[70:73]
	v_mfma_f32_16x16x32_bf16 v[50:53], v[158:161], v[206:209], v[50:53]
	v_mfma_f32_16x16x32_bf16 v[86:89], v[150:153], v[214:217], v[86:89]
	v_mfma_f32_16x16x32_bf16 v[74:77], v[158:161], v[214:217], v[74:77]
	s_setprio 0
	s_setprio 1
	v_mfma_f32_16x16x32_bf16 v[14:17], v[170:173], v[186:189], v[14:17]
	v_mfma_f32_16x16x32_bf16 v[2:5], v[178:181], v[186:189], v[2:5]
	v_mfma_f32_16x16x32_bf16 v[18:21], v[170:173], v[194:197], v[18:21]
	v_mfma_f32_16x16x32_bf16 v[6:9], v[178:181], v[194:197], v[6:9]
	v_mfma_f32_16x16x32_bf16 v[22:25], v[170:173], v[202:205], v[22:25]
	v_mfma_f32_16x16x32_bf16 v[10:13], v[178:181], v[202:205], v[10:13]
	v_mfma_f32_16x16x32_bf16 v[30:33], v[170:173], v[210:213], v[30:33]
	v_mfma_f32_16x16x32_bf16 v[26:29], v[178:181], v[210:213], v[26:29]
	v_mfma_f32_16x16x32_bf16 v[14:17], v[174:177], v[190:193], v[14:17]
	v_mfma_f32_16x16x32_bf16 v[2:5], v[182:185], v[190:193], v[2:5]
	v_mfma_f32_16x16x32_bf16 v[18:21], v[174:177], v[198:201], v[18:21]
	v_mfma_f32_16x16x32_bf16 v[6:9], v[182:185], v[198:201], v[6:9]
	v_mfma_f32_16x16x32_bf16 v[22:25], v[174:177], v[206:209], v[22:25]
	v_mfma_f32_16x16x32_bf16 v[10:13], v[182:185], v[206:209], v[10:13]
	v_mfma_f32_16x16x32_bf16 v[30:33], v[174:177], v[214:217], v[30:33]
	v_mfma_f32_16x16x32_bf16 v[26:29], v[182:185], v[214:217], v[26:29]
	s_barrier
	s_setprio 0
	s_mov_b32 m0, s33
	s_add_u32 s46, s10, 0x2b0000
	ds_read_b128 v[186:189], v142 offset:16384
	ds_read_b128 v[190:193], v142 offset:17408
	global_load_lds_dwordx4 v162, s[10:11]
	ds_read_b128 v[194:197], v142 offset:18432
	s_mov_b32 m0, s34
	s_addc_u32 s47, s11, 0
	global_load_lds_dwordx4 v134, s[10:11]
	ds_read_b128 v[198:201], v142 offset:19456
	s_mov_b32 m0, s35
	s_nop 0
	global_load_lds_dwordx4 v162, s[46:47]
	ds_read_b128 v[202:205], v142 offset:20480
	s_mov_b32 m0, s43
	s_nop 0
	global_load_lds_dwordx4 v134, s[46:47]
	ds_read_b128 v[206:209], v142 offset:21504
	s_add_u32 s54, s16, s2
	s_addc_u32 s55, s17, s3
	s_mov_b32 m0, s27
	s_nop 0
	global_load_lds_dwordx4 v130, s[16:17]
	ds_read_b128 v[210:213], v142 offset:22528
	s_mov_b32 m0, s28
	s_nop 0
	global_load_lds_dwordx4 v132, s[16:17]
	ds_read_b128 v[214:217], v142 offset:23552
	s_waitcnt vmcnt(8) lgkmcnt(0)
	s_barrier
	s_setprio 1
	v_mfma_f32_16x16x32_bf16 v[94:97], v[146:149], v[186:189], v[94:97]
	v_mfma_f32_16x16x32_bf16 v[90:93], v[154:157], v[186:189], v[90:93]
	v_mfma_f32_16x16x32_bf16 v[118:121], v[146:149], v[194:197], v[118:121]
	v_mfma_f32_16x16x32_bf16 v[98:101], v[154:157], v[194:197], v[98:101]
	v_mfma_f32_16x16x32_bf16 v[126:129], v[146:149], v[202:205], v[126:129]
	v_mfma_f32_16x16x32_bf16 v[110:113], v[154:157], v[202:205], v[110:113]
	v_mfma_f32_16x16x32_bf16 v[122:125], v[146:149], v[210:213], v[122:125]
	v_mfma_f32_16x16x32_bf16 v[114:117], v[154:157], v[210:213], v[114:117]
	v_mfma_f32_16x16x32_bf16 v[94:97], v[150:153], v[190:193], v[94:97]
	v_mfma_f32_16x16x32_bf16 v[90:93], v[158:161], v[190:193], v[90:93]
	v_mfma_f32_16x16x32_bf16 v[118:121], v[150:153], v[198:201], v[118:121]
	v_mfma_f32_16x16x32_bf16 v[98:101], v[158:161], v[198:201], v[98:101]
	v_mfma_f32_16x16x32_bf16 v[126:129], v[150:153], v[206:209], v[126:129]
	v_mfma_f32_16x16x32_bf16 v[110:113], v[158:161], v[206:209], v[110:113]
	v_mfma_f32_16x16x32_bf16 v[122:125], v[150:153], v[214:217], v[122:125]
	v_mfma_f32_16x16x32_bf16 v[114:117], v[158:161], v[214:217], v[114:117]
	s_setprio 0
	s_setprio 1
	v_mfma_f32_16x16x32_bf16 v[38:41], v[170:173], v[186:189], v[38:41]
	v_mfma_f32_16x16x32_bf16 v[34:37], v[178:181], v[186:189], v[34:37]
	v_mfma_f32_16x16x32_bf16 v[66:69], v[170:173], v[194:197], v[66:69]
	v_mfma_f32_16x16x32_bf16 v[46:49], v[178:181], v[194:197], v[46:49]
	v_mfma_f32_16x16x32_bf16 v[78:81], v[170:173], v[202:205], v[78:81]
	v_mfma_f32_16x16x32_bf16 v[62:65], v[178:181], v[202:205], v[62:65]
	v_mfma_f32_16x16x32_bf16 v[106:109], v[170:173], v[210:213], v[106:109]
	v_mfma_f32_16x16x32_bf16 v[102:105], v[178:181], v[210:213], v[102:105]
	v_mfma_f32_16x16x32_bf16 v[38:41], v[174:177], v[190:193], v[38:41]
	v_mfma_f32_16x16x32_bf16 v[34:37], v[182:185], v[190:193], v[34:37]
	v_mfma_f32_16x16x32_bf16 v[66:69], v[174:177], v[198:201], v[66:69]
	v_mfma_f32_16x16x32_bf16 v[46:49], v[182:185], v[198:201], v[46:49]
	v_mfma_f32_16x16x32_bf16 v[78:81], v[174:177], v[206:209], v[78:81]
	v_mfma_f32_16x16x32_bf16 v[62:65], v[182:185], v[206:209], v[62:65]
	v_mfma_f32_16x16x32_bf16 v[106:109], v[174:177], v[214:217], v[106:109]
	v_mfma_f32_16x16x32_bf16 v[102:105], v[182:185], v[214:217], v[102:105]
	s_barrier
; #define PG8_STAGE(bufoff, gbase, voff) do { _Pragma("unroll") for (int _i = 0; _i < 2; ++_i) \
;         __builtin_amdgcn_global_load_lds((const unsigned*)((const char*)(gbase) + (voff)[_i]), (LAS unsigned*)(lds + (bufoff) + ldsw + _i * 8192), 16, 0, 0); } while (0)
; #define PG8_LDA(dst, b, h) do { _Pragma("unroll") for (int m = 0; m < 4; ++m) _Pragma("unroll") for (int k = 0; k < 2; ++k) dst[m][k] = *(const LAS bf16x8*)(lds + PG8_SA(b, h) + aoff + m * 2048 + k * 1024); } while (0)
; #define PG8_LDB(dst, b, h) do { _Pragma("unroll") for (int n = 0; n < 2; ++n) _Pragma("unroll") for (int k = 0; k < 2; ++k) dst[n][k] = *(const LAS bf16x8*)(lds + PG8_SB(b, h) + boff + n * 2048 + k * 1024); } while (0)
; #define PG8_MMA(ai, bj, At, Bt) do { __builtin_amdgcn_s_setprio(1); _Pragma("unroll") for (int m = 0; m < 4; ++m) _Pragma("unroll") for (int n = 0; n < 2; ++n) _Pragma("unroll") for (int k = 0; k < 2; ++k) \
;         acc[ai][bj][m][n] = __builtin_amdgcn_mfma_f32_16x16x32_bf16(Bt[n][k], At[m][k], acc[ai][bj][m][n], 0, 0, 0); __builtin_amdgcn_s_setprio(0); } while (0)
; #define PG8_WAIT_V(n) asm volatile("s_waitcnt vmcnt(" #n ")" ::: "memory")
; #define PG8_WAIT_L(n) asm volatile("s_waitcnt lgkmcnt(" #n ")" ::: "memory")
; #define PG8_BAR __builtin_amdgcn_s_barrier()
; #define PG8_SCHED __builtin_amdgcn_sched_barrier(0)
; template <class Epi, class Sched, bool ALIGN_EPI, class Hook = NoHook>
; __device__ __forceinline__ void gemm_phase(LAS unsigned char* lds, const Gemm g, const Sched& S, const Epi& E, const Hook& H = Hook()) {
;     ...
;             PG8_LDB(B0, 1, 0); PG8_LDB(B1, 1, 1); PG8_SCHED; PG8_LDA(At, 1, 0); PG8_STAGE(PG8_SA(0, 1), a2 + hA, voffA);
;             PG8_WAIT_V(8); PG8_WAIT_L(0); PG8_BAR; PG8_MMA(0, 0, At, B0); PG8_MMA(0, 1, At, B1); PG8_BAR; PG8_SCHED;
;             PG8_LDA(At, 1, 1); PG8_STAGE(PG8_SB(1, 0), b3, voffB); PG8_STAGE(PG8_SB(1, 1), b3 + hB, voffB); PG8_STAGE(PG8_SA(1, 0), a3, voffA);
;             PG8_WAIT_V(8); PG8_WAIT_L(0); PG8_BAR; PG8_MMA(1, 0, At, B0); PG8_MMA(1, 1, At, B1); PG8_BAR; PG8_SCHED;
;         }
;         if constexpr (Hook::ON) H.after(te, acc, cur, wr, wc, fr, fq);
;         }
;         if constexpr (ALIGN_EPI) { if (wr == 0) PG8_BAR; }
	s_setprio 0
	ds_read_b128 v[146:149], v143
	ds_read_b128 v[150:153], v143 offset:1024
	s_add_u32 s16, s16, 0x2b0000
	s_addc_u32 s17, s17, 0
	s_mov_b32 m0, s29
	s_nop 0
	global_load_lds_dwordx4 v130, s[16:17]
	ds_read_b128 v[154:157], v143 offset:2048
	ds_read_b128 v[158:161], v143 offset:3072
	ds_read_b128 v[170:173], v144
	ds_read_b128 v[174:177], v144 offset:1024
	ds_read_b128 v[178:181], v144 offset:2048
	ds_read_b128 v[182:185], v144 offset:3072
	ds_read_b128 v[186:189], v142 offset:32768
	s_mov_b32 m0, s39
	s_nop 0
	global_load_lds_dwordx4 v132, s[16:17]
	ds_read_b128 v[190:193], v142 offset:33792
	ds_read_b128 v[194:197], v142 offset:34816
	ds_read_b128 v[198:201], v142 offset:35840
	ds_read_b128 v[202:205], v142 offset:36864
	ds_read_b128 v[206:209], v142 offset:37888
	ds_read_b128 v[210:213], v142 offset:38912
	ds_read_b128 v[214:217], v142 offset:39936
	s_waitcnt vmcnt(8) lgkmcnt(0)
	s_barrier
	s_setprio 1
	v_mfma_f32_16x16x32_bf16 v[82:85], v[146:149], v[186:189], v[82:85]
	v_mfma_f32_16x16x32_bf16 v[54:57], v[154:157], v[186:189], v[54:57]
	v_mfma_f32_16x16x32_bf16 v[58:61], v[146:149], v[194:197], v[58:61]
	v_mfma_f32_16x16x32_bf16 v[42:45], v[154:157], v[194:197], v[42:45]
	v_mfma_f32_16x16x32_bf16 v[70:73], v[146:149], v[202:205], v[70:73]
	v_mfma_f32_16x16x32_bf16 v[50:53], v[154:157], v[202:205], v[50:53]
	v_mfma_f32_16x16x32_bf16 v[86:89], v[146:149], v[210:213], v[86:89]
	v_mfma_f32_16x16x32_bf16 v[74:77], v[154:157], v[210:213], v[74:77]
	v_mfma_f32_16x16x32_bf16 v[82:85], v[150:153], v[190:193], v[82:85]
	v_mfma_f32_16x16x32_bf16 v[54:57], v[158:161], v[190:193], v[54:57]
	v_mfma_f32_16x16x32_bf16 v[58:61], v[150:153], v[198:201], v[58:61]
	v_mfma_f32_16x16x32_bf16 v[42:45], v[158:161], v[198:201], v[42:45]
	v_mfma_f32_16x16x32_bf16 v[70:73], v[150:153], v[206:209], v[70:73]
	v_mfma_f32_16x16x32_bf16 v[50:53], v[158:161], v[206:209], v[50:53]
	v_mfma_f32_16x16x32_bf16 v[86:89], v[150:153], v[214:217], v[86:89]
	v_mfma_f32_16x16x32_bf16 v[74:77], v[158:161], v[214:217], v[74:77]
	s_setprio 0
	s_setprio 1
	v_mfma_f32_16x16x32_bf16 v[14:17], v[170:173], v[186:189], v[14:17]
	v_mfma_f32_16x16x32_bf16 v[2:5], v[178:181], v[186:189], v[2:5]
	v_mfma_f32_16x16x32_bf16 v[18:21], v[170:173], v[194:197], v[18:21]
	v_mfma_f32_16x16x32_bf16 v[6:9], v[178:181], v[194:197], v[6:9]
	v_mfma_f32_16x16x32_bf16 v[22:25], v[170:173], v[202:205], v[22:25]
	v_mfma_f32_16x16x32_bf16 v[10:13], v[178:181], v[202:205], v[10:13]
	v_mfma_f32_16x16x32_bf16 v[30:33], v[170:173], v[210:213], v[30:33]
	v_mfma_f32_16x16x32_bf16 v[26:29], v[178:181], v[210:213], v[26:29]
	v_mfma_f32_16x16x32_bf16 v[14:17], v[174:177], v[190:193], v[14:17]
	v_mfma_f32_16x16x32_bf16 v[2:5], v[182:185], v[190:193], v[2:5]
	v_mfma_f32_16x16x32_bf16 v[18:21], v[174:177], v[198:201], v[18:21]
	v_mfma_f32_16x16x32_bf16 v[6:9], v[182:185], v[198:201], v[6:9]
	v_mfma_f32_16x16x32_bf16 v[22:25], v[174:177], v[206:209], v[22:25]
	v_mfma_f32_16x16x32_bf16 v[10:13], v[182:185], v[206:209], v[10:13]
	v_mfma_f32_16x16x32_bf16 v[30:33], v[174:177], v[214:217], v[30:33]
	v_mfma_f32_16x16x32_bf16 v[26:29], v[182:185], v[214:217], v[26:29]
	s_barrier
	s_setprio 0
	s_mov_b32 m0, s36
	s_add_u32 s52, s10, s2
	s_addc_u32 s53, s11, s3
	s_add_u32 s10, s10, 0x2b0080
	ds_read_b128 v[186:189], v142 offset:49152
	ds_read_b128 v[190:193], v142 offset:50176
	global_load_lds_dwordx4 v162, s[52:53]
	ds_read_b128 v[194:197], v142 offset:51200
	s_mov_b32 m0, s44
	s_addc_u32 s11, s11, 0
	global_load_lds_dwordx4 v134, s[52:53]
	ds_read_b128 v[198:201], v142 offset:52224
	s_mov_b32 m0, s37
	s_nop 0
	global_load_lds_dwordx4 v162, s[10:11]
	ds_read_b128 v[202:205], v142 offset:53248
	s_mov_b32 m0, s45
	s_nop 0
	global_load_lds_dwordx4 v134, s[10:11]
	ds_read_b128 v[206:209], v142 offset:54272
	s_mov_b32 m0, s41
	s_nop 0
	global_load_lds_dwordx4 v130, s[54:55]
	ds_read_b128 v[210:213], v142 offset:55296
	s_mov_b32 m0, s42
	s_nop 0
	global_load_lds_dwordx4 v132, s[54:55]
	ds_read_b128 v[214:217], v142 offset:56320
	s_waitcnt vmcnt(8) lgkmcnt(0)
	s_barrier
	s_setprio 1
	v_mfma_f32_16x16x32_bf16 v[94:97], v[146:149], v[186:189], v[94:97]
	v_mfma_f32_16x16x32_bf16 v[90:93], v[154:157], v[186:189], v[90:93]
	v_mfma_f32_16x16x32_bf16 v[118:121], v[146:149], v[194:197], v[118:121]
	v_mfma_f32_16x16x32_bf16 v[98:101], v[154:157], v[194:197], v[98:101]
	v_mfma_f32_16x16x32_bf16 v[126:129], v[146:149], v[202:205], v[126:129]
	v_mfma_f32_16x16x32_bf16 v[110:113], v[154:157], v[202:205], v[110:113]
	v_mfma_f32_16x16x32_bf16 v[122:125], v[146:149], v[210:213], v[122:125]
	v_mfma_f32_16x16x32_bf16 v[114:117], v[154:157], v[210:213], v[114:117]
	v_mfma_f32_16x16x32_bf16 v[94:97], v[150:153], v[190:193], v[94:97]
	v_mfma_f32_16x16x32_bf16 v[90:93], v[158:161], v[190:193], v[90:93]
	v_mfma_f32_16x16x32_bf16 v[118:121], v[150:153], v[198:201], v[118:121]
	v_mfma_f32_16x16x32_bf16 v[98:101], v[158:161], v[198:201], v[98:101]
	v_mfma_f32_16x16x32_bf16 v[126:129], v[150:153], v[206:209], v[126:129]
	v_mfma_f32_16x16x32_bf16 v[110:113], v[158:161], v[206:209], v[110:113]
	v_mfma_f32_16x16x32_bf16 v[122:125], v[150:153], v[214:217], v[122:125]
	v_mfma_f32_16x16x32_bf16 v[114:117], v[158:161], v[214:217], v[114:117]
	s_setprio 0
	s_setprio 1
	v_mfma_f32_16x16x32_bf16 v[38:41], v[170:173], v[186:189], v[38:41]
	v_mfma_f32_16x16x32_bf16 v[34:37], v[178:181], v[186:189], v[34:37]
	v_mfma_f32_16x16x32_bf16 v[66:69], v[170:173], v[194:197], v[66:69]
	v_mfma_f32_16x16x32_bf16 v[46:49], v[178:181], v[194:197], v[46:49]
	v_mfma_f32_16x16x32_bf16 v[78:81], v[170:173], v[202:205], v[78:81]
	v_mfma_f32_16x16x32_bf16 v[62:65], v[178:181], v[202:205], v[62:65]
	v_mfma_f32_16x16x32_bf16 v[106:109], v[170:173], v[210:213], v[106:109]
	v_mfma_f32_16x16x32_bf16 v[102:105], v[178:181], v[210:213], v[102:105]
	v_mfma_f32_16x16x32_bf16 v[38:41], v[174:177], v[190:193], v[38:41]
	v_mfma_f32_16x16x32_bf16 v[34:37], v[182:185], v[190:193], v[34:37]
	v_mfma_f32_16x16x32_bf16 v[66:69], v[174:177], v[198:201], v[66:69]
	v_mfma_f32_16x16x32_bf16 v[46:49], v[182:185], v[198:201], v[46:49]
	v_mfma_f32_16x16x32_bf16 v[78:81], v[174:177], v[206:209], v[78:81]
	v_mfma_f32_16x16x32_bf16 v[62:65], v[182:185], v[206:209], v[62:65]
	v_mfma_f32_16x16x32_bf16 v[106:109], v[174:177], v[214:217], v[106:109]
	v_mfma_f32_16x16x32_bf16 v[102:105], v[182:185], v[214:217], v[102:105]
	s_barrier
	s_setprio 0
	s_add_i32 s18, s18, 2
	s_add_u32 s4, s4, 0x100
	s_addc_u32 s5, s5, 0
	s_cmpk_gt_u32 s18, 0xa9
	s_cbranch_scc0 .LBB0_1406
	s_cmpk_lt_u32 s22, 0x100
	s_cbranch_scc0 .LBB0_1409
	s_barrier
